# GEMM: first K-iteration peeled with C=0 so the 128 per-tile accumulator zeroing moves are gone (all six GEMM instances)
# speedup vs baseline: 1.0549x; 1.0001x over previous
; #define PG8_STAGE(bufoff, gbase, voff) do { _Pragma("unroll") for (int _i = 0; _i < 2; ++_i) \
;         __builtin_amdgcn_global_load_lds((const unsigned*)((const char*)(gbase) + (voff)[_i]), (LAS unsigned*)(lds + (bufoff) + ldsw + _i * 8192), 16, 0, 0); } while (0)
; #define PG8_LDA(dst, b, h) do { _Pragma("unroll") for (int m = 0; m < 4; ++m) _Pragma("unroll") for (int k = 0; k < 2; ++k) dst[m][k] = *(const LAS bf16x8*)(lds + PG8_SA(b, h) + aoff + m * 2048 + k * 1024); } while (0)
; #define PG8_LDB(dst, b, h) do { _Pragma("unroll") for (int n = 0; n < 2; ++n) _Pragma("unroll") for (int k = 0; k < 2; ++k) dst[n][k] = *(const LAS bf16x8*)(lds + PG8_SB(b, h) + boff + n * 2048 + k * 1024); } while (0)
; #define PG8_MMA(ai, bj, At, Bt) do { __builtin_amdgcn_s_setprio(1); _Pragma("unroll") for (int m = 0; m < 4; ++m) _Pragma("unroll") for (int n = 0; n < 2; ++n) _Pragma("unroll") for (int k = 0; k < 2; ++k) \
;         acc[ai][bj][m][n] = __builtin_amdgcn_mfma_f32_16x16x32_bf16(Bt[n][k], At[m][k], acc[ai][bj][m][n], 0, 0, 0); __builtin_amdgcn_s_setprio(0); } while (0)
; #define PG8_WAIT_L(n) asm volatile("s_waitcnt lgkmcnt(" #n ")" ::: "memory")
; template <class Epi>
; __device__ __forceinline__ void gemm_phase(LAS unsigned char* lds, const Gemm g, const StaticOrder& S, const Epi& E) {
;     ...
;     for (;;) {
;         const bool has_next = S.next(ui + 1, nxt);
;         const char* nA = has_next ? (const char*)g.A + (size_t)nxt.pm * tstep : cA; const char* nB = has_next ? (const char*)g.Bt + (size_t)nxt.pn * tstep : cB;
;         for (int t = 0; t < nt; t += 2) {
;             const bool last = (t == nt - 2);
;             const char* a1 = cA + (size_t)(t + 1) * kstep;
;             const char* a2 = last ? nA : cA + (size_t)(t + 2) * kstep; const char* b2 = last ? nB : cB + (size_t)(t + 2) * kstep;
;             const char* a3 = a2 + kstep; const char* b3 = b2 + kstep;
;             PG8_LDB(B0, 0, 0); PG8_SCHED; PG8_LDA(At, 0, 0); PG8_STAGE(PG8_SA(1, 1), a1 + hstep, voffA);
;             PG8_WAIT_L(8); PG8_BAR; PG8_WAIT_L(0); PG8_MMA(0, 0, At, B0); PG8_BAR; PG8_SCHED;
;             PG8_LDB(B1, 0, 1); PG8_STAGE(PG8_SB(0, 0), b2, voffB);
;             PG8_BAR; PG8_WAIT_L(0); PG8_MMA(0, 1, At, B1); PG8_BAR;
;             PG8_LDA(At, 0, 1); PG8_STAGE(PG8_SA(0, 0), a2, voffA);
;             PG8_BAR; PG8_WAIT_L(0); PG8_MMA(1, 0, At, B0); PG8_BAR; PG8_SCHED;
.LBB0_2078:
	s_ashr_i32 s15, s14, 31
	v_cmp_lt_i64_e32 vcc, s[16:17], v[156:157]
	s_lshl_b64 s[16:17], s[14:15], 19
	s_add_u32 s16, s29, s16
	s_addc_u32 s17, s30, s17
	s_and_b64 s[18:19], vcc, exec
	s_cselect_b32 s15, s17, s23
	s_cselect_b32 s57, s16, s22
	s_ashr_i32 s13, s12, 31
	s_lshl_b64 s[18:19], s[12:13], 19
	s_add_u32 s18, s31, s18
	s_addc_u32 s19, s34, s19
	s_and_b64 s[26:27], vcc, exec
	s_cselect_b32 s13, s19, s25
	s_cselect_b32 s58, s18, s24
	s_add_u32 s22, s22, 0x40080
	s_addc_u32 s23, s23, 0
	s_add_u32 s59, s24, 0x100
	s_addc_u32 s60, s25, 0
	s_mov_b32 s61, -2
	s_add_u32 s0, s22, 0xfffc0080
	s_addc_u32 s1, s23, -1
	s_add_i32 s62, 0, 0x10000
	v_add_u32_e32 v142, s62, v161
	ds_read_b128 v[122:125], v142
	ds_read_b128 v[126:129], v142 offset:1024
	ds_read_b128 v[138:141], v142 offset:2048
	ds_read_b128 v[142:145], v142 offset:3072
	s_cmp_eq_u32 s61, 12
	s_cselect_b32 s27, s15, s1
	s_cselect_b32 s26, s57, s0
	s_cselect_b32 s25, s13, s60
	s_cselect_b32 s24, s58, s59
	v_lshl_add_u64 v[186:187], s[22:23], 0, v[152:153]
	s_add_i32 m0, s21, 0xc000
	ds_read_b128 v[166:169], v165
	ds_read_b128 v[170:173], v165 offset:1024
	ds_read_b128 v[174:177], v165 offset:2048
	ds_read_b128 v[190:193], v165 offset:3072
	ds_read_b128 v[194:197], v165 offset:4096
	ds_read_b128 v[198:201], v165 offset:5120
	ds_read_b128 v[202:205], v165 offset:6144
	ds_read_b128 v[206:209], v165 offset:7168
	global_load_lds_dwordx4 v[186:187], off
	s_add_i32 m0, s21, 0xe000
	v_lshl_add_u64 v[186:187], s[22:23], 0, v[154:155]
	global_load_lds_dwordx4 v[186:187], off
	s_waitcnt lgkmcnt(8)
	s_barrier
	s_waitcnt lgkmcnt(0)
	v_mfma_f32_16x16x32_bf16 v[134:137], v[122:125], v[166:169], 0
	v_mfma_f32_16x16x32_bf16 v[130:133], v[138:141], v[166:169], 0
	v_mfma_f32_16x16x32_bf16 v[118:121], v[122:125], v[174:177], 0
	v_mfma_f32_16x16x32_bf16 v[114:117], v[138:141], v[174:177], 0
	v_mfma_f32_16x16x32_bf16 v[110:113], v[122:125], v[194:197], 0
	v_mfma_f32_16x16x32_bf16 v[106:109], v[138:141], v[194:197], 0
	v_mfma_f32_16x16x32_bf16 v[102:105], v[122:125], v[202:205], 0
	v_mfma_f32_16x16x32_bf16 v[98:101], v[138:141], v[202:205], 0
	v_mfma_f32_16x16x32_bf16 v[134:137], v[126:129], v[170:173], v[134:137]
	v_mfma_f32_16x16x32_bf16 v[130:133], v[142:145], v[170:173], v[130:133]
	v_mfma_f32_16x16x32_bf16 v[118:121], v[126:129], v[190:193], v[118:121]
	v_mfma_f32_16x16x32_bf16 v[114:117], v[142:145], v[190:193], v[114:117]
	v_mfma_f32_16x16x32_bf16 v[110:113], v[126:129], v[198:201], v[110:113]
	v_mfma_f32_16x16x32_bf16 v[106:109], v[142:145], v[198:201], v[106:109]
	v_mfma_f32_16x16x32_bf16 v[102:105], v[126:129], v[206:209], v[102:105]
	v_mfma_f32_16x16x32_bf16 v[98:101], v[142:145], v[206:209], v[98:101]
	s_barrier
	s_add_i32 s0, 0, 0x14000
	s_add_i32 s1, s62, s36
	v_add_u32_e32 v158, s0, v161
	v_lshl_add_u64 v[186:187], s[24:25], 0, v[4:5]
	s_mov_b32 m0, s1
	ds_read_b128 v[210:213], v158
	ds_read_b128 v[214:217], v158 offset:1024
	ds_read_b128 v[218:221], v158 offset:2048
	ds_read_b128 v[222:225], v158 offset:3072
	global_load_lds_dwordx4 v[186:187], off
	s_add_i32 m0, s1, 0x2000
	v_lshl_add_u64 v[226:227], s[24:25], 0, v[146:147]
	global_load_lds_dwordx4 v[226:227], off
	s_barrier
	s_waitcnt lgkmcnt(0)
	v_mfma_f32_16x16x32_bf16 v[70:73], v[210:213], v[166:169], 0
	v_mfma_f32_16x16x32_bf16 v[66:69], v[218:221], v[166:169], 0
	v_mfma_f32_16x16x32_bf16 v[54:57], v[210:213], v[174:177], 0
	v_mfma_f32_16x16x32_bf16 v[50:53], v[218:221], v[174:177], 0
	v_mfma_f32_16x16x32_bf16 v[46:49], v[210:213], v[194:197], 0
	v_mfma_f32_16x16x32_bf16 v[42:45], v[218:221], v[194:197], 0
	v_mfma_f32_16x16x32_bf16 v[38:41], v[210:213], v[202:205], 0
	v_mfma_f32_16x16x32_bf16 v[34:37], v[218:221], v[202:205], 0
	v_mfma_f32_16x16x32_bf16 v[70:73], v[214:217], v[170:173], v[70:73]
	v_mfma_f32_16x16x32_bf16 v[66:69], v[222:225], v[170:173], v[66:69]
	v_mfma_f32_16x16x32_bf16 v[54:57], v[214:217], v[190:193], v[54:57]
	v_mfma_f32_16x16x32_bf16 v[50:53], v[222:225], v[190:193], v[50:53]
	v_mfma_f32_16x16x32_bf16 v[46:49], v[214:217], v[198:201], v[46:49]
	v_mfma_f32_16x16x32_bf16 v[42:45], v[222:225], v[198:201], v[42:45]
	v_mfma_f32_16x16x32_bf16 v[38:41], v[214:217], v[206:209], v[38:41]
	v_mfma_f32_16x16x32_bf16 v[34:37], v[222:225], v[206:209], v[34:37]
	s_mov_b32 m0, s21
	v_lshl_add_u64 v[242:243], s[26:27], 0, v[150:151]
	s_barrier
	ds_read_b128 v[166:169], v165 offset:16384
	ds_read_b128 v[170:173], v165 offset:17408
	ds_read_b128 v[174:177], v165 offset:18432
	ds_read_b128 v[190:193], v165 offset:19456
	ds_read_b128 v[194:197], v165 offset:20480
	ds_read_b128 v[198:201], v165 offset:21504
	ds_read_b128 v[202:205], v165 offset:22528
	ds_read_b128 v[206:209], v165 offset:23552
	global_load_lds_dwordx4 v[242:243], off
	s_mov_b32 m0, s42
	v_lshl_add_u64 v[244:245], s[26:27], 0, v[148:149]
	global_load_lds_dwordx4 v[244:245], off
	s_barrier
	s_waitcnt lgkmcnt(0)
	v_mfma_f32_16x16x32_bf16 v[94:97], v[122:125], v[166:169], 0
	v_mfma_f32_16x16x32_bf16 v[90:93], v[138:141], v[166:169], 0
	v_mfma_f32_16x16x32_bf16 v[86:89], v[122:125], v[174:177], 0
	v_mfma_f32_16x16x32_bf16 v[82:85], v[138:141], v[174:177], 0
	v_mfma_f32_16x16x32_bf16 v[78:81], v[122:125], v[194:197], 0
	v_mfma_f32_16x16x32_bf16 v[74:77], v[138:141], v[194:197], 0
	v_mfma_f32_16x16x32_bf16 v[62:65], v[122:125], v[202:205], 0
	v_mfma_f32_16x16x32_bf16 v[58:61], v[138:141], v[202:205], 0
	v_mfma_f32_16x16x32_bf16 v[94:97], v[126:129], v[170:173], v[94:97]
	v_mfma_f32_16x16x32_bf16 v[90:93], v[142:145], v[170:173], v[90:93]
	v_mfma_f32_16x16x32_bf16 v[86:89], v[126:129], v[190:193], v[86:89]
	v_mfma_f32_16x16x32_bf16 v[82:85], v[142:145], v[190:193], v[82:85]
	v_mfma_f32_16x16x32_bf16 v[78:81], v[126:129], v[198:201], v[78:81]
	v_mfma_f32_16x16x32_bf16 v[74:77], v[142:145], v[198:201], v[74:77]
	v_mfma_f32_16x16x32_bf16 v[62:65], v[126:129], v[206:209], v[62:65]
	v_mfma_f32_16x16x32_bf16 v[58:61], v[142:145], v[206:209], v[58:61]
	s_barrier
; #define PG8_STAGE(bufoff, gbase, voff) do { _Pragma("unroll") for (int _i = 0; _i < 2; ++_i) \
;         __builtin_amdgcn_global_load_lds((const unsigned*)((const char*)(gbase) + (voff)[_i]), (LAS unsigned*)(lds + (bufoff) + ldsw + _i * 8192), 16, 0, 0); } while (0)
; #define PG8_LDA(dst, b, h) do { _Pragma("unroll") for (int m = 0; m < 4; ++m) _Pragma("unroll") for (int k = 0; k < 2; ++k) dst[m][k] = *(const LAS bf16x8*)(lds + PG8_SA(b, h) + aoff + m * 2048 + k * 1024); } while (0)
; #define PG8_LDB(dst, b, h) do { _Pragma("unroll") for (int n = 0; n < 2; ++n) _Pragma("unroll") for (int k = 0; k < 2; ++k) dst[n][k] = *(const LAS bf16x8*)(lds + PG8_SB(b, h) + boff + n * 2048 + k * 1024); } while (0)
; #define PG8_MMA(ai, bj, At, Bt) do { __builtin_amdgcn_s_setprio(1); _Pragma("unroll") for (int m = 0; m < 4; ++m) _Pragma("unroll") for (int n = 0; n < 2; ++n) _Pragma("unroll") for (int k = 0; k < 2; ++k) \
;         acc[ai][bj][m][n] = __builtin_amdgcn_mfma_f32_16x16x32_bf16(Bt[n][k], At[m][k], acc[ai][bj][m][n], 0, 0, 0); __builtin_amdgcn_s_setprio(0); } while (0)
; #define PG8_WAIT_V(n) asm volatile("s_waitcnt vmcnt(" #n ")" ::: "memory")
; #define PG8_WAIT_L(n) asm volatile("s_waitcnt lgkmcnt(" #n ")" ::: "memory")
; #define PG8_BAR __builtin_amdgcn_s_barrier()
; #define PG8_SCHED __builtin_amdgcn_sched_barrier(0)
; template <class Epi>
; __device__ __forceinline__ void gemm_phase(LAS unsigned char* lds, const Gemm g, const StaticOrder& S, const Epi& E) {
;     ...
;             PG8_BAR; PG8_WAIT_L(0); PG8_MMA(1, 0, At, B0); PG8_BAR; PG8_SCHED;
;             PG8_STAGE(PG8_SB(0, 1), b2 + hstep, voffB);
;             PG8_WAIT_V(6); PG8_BAR; PG8_MMA(1, 1, At, B1); PG8_BAR;
;             PG8_LDB(B0, 1, 0); PG8_SCHED; PG8_LDA(At, 1, 0); PG8_STAGE(PG8_SA(0, 1), a2 + hstep, voffA);
;             PG8_WAIT_L(8); PG8_BAR; PG8_WAIT_L(0); PG8_MMA(0, 0, At, B0); PG8_BAR; PG8_SCHED;
;             PG8_LDB(B1, 1, 1); PG8_STAGE(PG8_SB(1, 0), b3, voffB);
;             PG8_BAR; PG8_WAIT_L(0); PG8_MMA(0, 1, At, B1); PG8_BAR;
	s_add_u32 s62, s24, 0x40000
	s_addc_u32 s63, s25, 0
	s_add_i32 s0, s0, s36
	s_mov_b32 m0, s0
	v_lshl_add_u64 v[122:123], s[62:63], 0, v[4:5]
	global_load_lds_dwordx4 v[122:123], off
	s_add_i32 m0, s0, 0x2000
	v_lshl_add_u64 v[122:123], s[62:63], 0, v[146:147]
	global_load_lds_dwordx4 v[122:123], off
	s_waitcnt vmcnt(6)
	s_barrier
	v_mfma_f32_16x16x32_bf16 v[30:33], v[210:213], v[166:169], 0
	v_mfma_f32_16x16x32_bf16 v[26:29], v[218:221], v[166:169], 0
	v_mfma_f32_16x16x32_bf16 v[22:25], v[210:213], v[174:177], 0
	v_mfma_f32_16x16x32_bf16 v[18:21], v[218:221], v[174:177], 0
	v_mfma_f32_16x16x32_bf16 v[14:17], v[210:213], v[194:197], 0
	v_mfma_f32_16x16x32_bf16 v[10:13], v[218:221], v[194:197], 0
	v_mfma_f32_16x16x32_bf16 v[6:9], v[210:213], v[202:205], 0
	v_mfma_f32_16x16x32_bf16 v[0:3], v[218:221], v[202:205], 0
	v_mfma_f32_16x16x32_bf16 v[30:33], v[214:217], v[170:173], v[30:33]
	v_mfma_f32_16x16x32_bf16 v[26:29], v[222:225], v[170:173], v[26:29]
	v_mfma_f32_16x16x32_bf16 v[22:25], v[214:217], v[190:193], v[22:25]
	v_mfma_f32_16x16x32_bf16 v[18:21], v[222:225], v[190:193], v[18:21]
	v_mfma_f32_16x16x32_bf16 v[14:17], v[214:217], v[198:201], v[14:17]
	v_mfma_f32_16x16x32_bf16 v[10:13], v[222:225], v[198:201], v[10:13]
	v_mfma_f32_16x16x32_bf16 v[6:9], v[214:217], v[206:209], v[6:9]
	v_mfma_f32_16x16x32_bf16 v[0:3], v[222:225], v[206:209], v[0:3]
	s_add_i32 s0, 0, 0x18000
	v_add_u32_e32 v142, s0, v161
	s_barrier
	ds_read_b128 v[122:125], v142
	ds_read_b128 v[126:129], v142 offset:1024
	ds_read_b128 v[138:141], v142 offset:2048
	ds_read_b128 v[142:145], v142 offset:3072
	s_add_u32 s26, s26, 0x40000
	s_addc_u32 s27, s27, 0
	s_mov_b32 m0, s43
	v_lshl_add_u64 v[210:211], s[26:27], 0, v[150:151]
	ds_read_b128 v[166:169], v165 offset:32768
	ds_read_b128 v[170:173], v165 offset:33792
	ds_read_b128 v[174:177], v165 offset:34816
	ds_read_b128 v[190:193], v165 offset:35840
	ds_read_b128 v[194:197], v165 offset:36864
	ds_read_b128 v[198:201], v165 offset:37888
	ds_read_b128 v[202:205], v165 offset:38912
	ds_read_b128 v[206:209], v165 offset:39936
	global_load_lds_dwordx4 v[210:211], off
	s_mov_b32 m0, s48
	v_lshl_add_u64 v[210:211], s[26:27], 0, v[148:149]
	global_load_lds_dwordx4 v[210:211], off
	s_waitcnt lgkmcnt(8)
	s_barrier
	s_waitcnt lgkmcnt(0)
	v_mfma_f32_16x16x32_bf16 v[134:137], v[122:125], v[166:169], v[134:137]
	v_mfma_f32_16x16x32_bf16 v[130:133], v[138:141], v[166:169], v[130:133]
	v_mfma_f32_16x16x32_bf16 v[118:121], v[122:125], v[174:177], v[118:121]
	v_mfma_f32_16x16x32_bf16 v[114:117], v[138:141], v[174:177], v[114:117]
	v_mfma_f32_16x16x32_bf16 v[110:113], v[122:125], v[194:197], v[110:113]
	v_mfma_f32_16x16x32_bf16 v[106:109], v[138:141], v[194:197], v[106:109]
	v_mfma_f32_16x16x32_bf16 v[102:105], v[122:125], v[202:205], v[102:105]
	v_mfma_f32_16x16x32_bf16 v[98:101], v[138:141], v[202:205], v[98:101]
	v_mfma_f32_16x16x32_bf16 v[134:137], v[126:129], v[170:173], v[134:137]
	v_mfma_f32_16x16x32_bf16 v[130:133], v[142:145], v[170:173], v[130:133]
	v_mfma_f32_16x16x32_bf16 v[118:121], v[126:129], v[190:193], v[118:121]
	v_mfma_f32_16x16x32_bf16 v[114:117], v[142:145], v[190:193], v[114:117]
	v_mfma_f32_16x16x32_bf16 v[110:113], v[126:129], v[198:201], v[110:113]
	v_mfma_f32_16x16x32_bf16 v[106:109], v[142:145], v[198:201], v[106:109]
	v_mfma_f32_16x16x32_bf16 v[102:105], v[126:129], v[206:209], v[102:105]
	v_mfma_f32_16x16x32_bf16 v[98:101], v[142:145], v[206:209], v[98:101]
	s_barrier
	s_add_i32 s1, 0, 0x1c000
	s_add_i32 s0, s0, s36
	v_add_u32_e32 v158, s1, v161
	v_lshl_add_u64 v[186:187], v[186:187], 0, s[86:87]
	s_mov_b32 m0, s0
	ds_read_b128 v[210:213], v158
	ds_read_b128 v[214:217], v158 offset:1024
	ds_read_b128 v[218:221], v158 offset:2048
	ds_read_b128 v[222:225], v158 offset:3072
	global_load_lds_dwordx4 v[186:187], off
	s_add_i32 m0, s0, 0x2000
	v_lshl_add_u64 v[186:187], v[226:227], 0, s[86:87]
	global_load_lds_dwordx4 v[186:187], off
	s_barrier
; #define PG8_STAGE(bufoff, gbase, voff) do { _Pragma("unroll") for (int _i = 0; _i < 2; ++_i) \
;         __builtin_amdgcn_global_load_lds((const unsigned*)((const char*)(gbase) + (voff)[_i]), (LAS unsigned*)(lds + (bufoff) + ldsw + _i * 8192), 16, 0, 0); } while (0)
; #define PG8_LDA(dst, b, h) do { _Pragma("unroll") for (int m = 0; m < 4; ++m) _Pragma("unroll") for (int k = 0; k < 2; ++k) dst[m][k] = *(const LAS bf16x8*)(lds + PG8_SA(b, h) + aoff + m * 2048 + k * 1024); } while (0)
; #define PG8_LDB(dst, b, h) do { _Pragma("unroll") for (int n = 0; n < 2; ++n) _Pragma("unroll") for (int k = 0; k < 2; ++k) dst[n][k] = *(const LAS bf16x8*)(lds + PG8_SB(b, h) + boff + n * 2048 + k * 1024); } while (0)
; #define PG8_MMA(ai, bj, At, Bt) do { __builtin_amdgcn_s_setprio(1); _Pragma("unroll") for (int m = 0; m < 4; ++m) _Pragma("unroll") for (int n = 0; n < 2; ++n) _Pragma("unroll") for (int k = 0; k < 2; ++k) \
;         acc[ai][bj][m][n] = __builtin_amdgcn_mfma_f32_16x16x32_bf16(Bt[n][k], At[m][k], acc[ai][bj][m][n], 0, 0, 0); __builtin_amdgcn_s_setprio(0); } while (0)
; #define PG8_WAIT_V(n) asm volatile("s_waitcnt vmcnt(" #n ")" ::: "memory")
; #define PG8_WAIT_L(n) asm volatile("s_waitcnt lgkmcnt(" #n ")" ::: "memory")
; #define PG8_BAR __builtin_amdgcn_s_barrier()
; #define PG8_SCHED __builtin_amdgcn_sched_barrier(0)
; template <class Epi>
; __device__ __forceinline__ void gemm_phase(LAS unsigned char* lds, const Gemm g, const StaticOrder& S, const Epi& E) {
;     ...
;             PG8_WAIT_L(8); PG8_BAR; PG8_WAIT_L(0); PG8_MMA(0, 0, At, B0); PG8_BAR; PG8_SCHED;
;             PG8_LDB(B1, 1, 1); PG8_STAGE(PG8_SB(1, 0), b3, voffB);
;             PG8_BAR; PG8_WAIT_L(0); PG8_MMA(0, 1, At, B1); PG8_BAR;
;             PG8_LDA(At, 1, 1); PG8_STAGE(PG8_SA(1, 0), a3, voffA);
;             PG8_BAR; PG8_WAIT_L(0); PG8_MMA(1, 0, At, B0); PG8_BAR; PG8_SCHED;
;             PG8_STAGE(PG8_SB(1, 1), b3 + hstep, voffB);
;             PG8_WAIT_V(6); PG8_BAR; PG8_MMA(1, 1, At, B1); PG8_BAR;
	s_waitcnt lgkmcnt(0)
	v_mfma_f32_16x16x32_bf16 v[70:73], v[210:213], v[166:169], v[70:73]
	v_mfma_f32_16x16x32_bf16 v[66:69], v[218:221], v[166:169], v[66:69]
	v_mfma_f32_16x16x32_bf16 v[54:57], v[210:213], v[174:177], v[54:57]
	v_mfma_f32_16x16x32_bf16 v[50:53], v[218:221], v[174:177], v[50:53]
	v_mfma_f32_16x16x32_bf16 v[46:49], v[210:213], v[194:197], v[46:49]
	v_mfma_f32_16x16x32_bf16 v[42:45], v[218:221], v[194:197], v[42:45]
	v_mfma_f32_16x16x32_bf16 v[38:41], v[210:213], v[202:205], v[38:41]
	v_mfma_f32_16x16x32_bf16 v[34:37], v[218:221], v[202:205], v[34:37]
	v_mfma_f32_16x16x32_bf16 v[70:73], v[214:217], v[170:173], v[70:73]
	v_mfma_f32_16x16x32_bf16 v[66:69], v[222:225], v[170:173], v[66:69]
	v_mfma_f32_16x16x32_bf16 v[54:57], v[214:217], v[190:193], v[54:57]
	v_mfma_f32_16x16x32_bf16 v[50:53], v[222:225], v[190:193], v[50:53]
	v_mfma_f32_16x16x32_bf16 v[46:49], v[214:217], v[198:201], v[46:49]
	v_mfma_f32_16x16x32_bf16 v[42:45], v[222:225], v[198:201], v[42:45]
	v_mfma_f32_16x16x32_bf16 v[38:41], v[214:217], v[206:209], v[38:41]
	v_mfma_f32_16x16x32_bf16 v[34:37], v[222:225], v[206:209], v[34:37]
	s_mov_b32 m0, s51
	v_lshl_add_u64 v[186:187], v[242:243], 0, s[86:87]
	s_barrier
	ds_read_b128 v[166:169], v165 offset:49152
	ds_read_b128 v[170:173], v165 offset:50176
	ds_read_b128 v[174:177], v165 offset:51200
	ds_read_b128 v[190:193], v165 offset:52224
	ds_read_b128 v[194:197], v165 offset:53248
	ds_read_b128 v[198:201], v165 offset:54272
	ds_read_b128 v[202:205], v165 offset:55296
	ds_read_b128 v[206:209], v165 offset:56320
	global_load_lds_dwordx4 v[186:187], off
	s_mov_b32 m0, s54
	v_lshl_add_u64 v[186:187], v[244:245], 0, s[86:87]
	global_load_lds_dwordx4 v[186:187], off
	s_barrier
	s_waitcnt lgkmcnt(0)
	v_mfma_f32_16x16x32_bf16 v[94:97], v[122:125], v[166:169], v[94:97]
	v_mfma_f32_16x16x32_bf16 v[90:93], v[138:141], v[166:169], v[90:93]
	v_mfma_f32_16x16x32_bf16 v[86:89], v[122:125], v[174:177], v[86:89]
	v_mfma_f32_16x16x32_bf16 v[82:85], v[138:141], v[174:177], v[82:85]
	v_mfma_f32_16x16x32_bf16 v[78:81], v[122:125], v[194:197], v[78:81]
	v_mfma_f32_16x16x32_bf16 v[74:77], v[138:141], v[194:197], v[74:77]
	v_mfma_f32_16x16x32_bf16 v[62:65], v[122:125], v[202:205], v[62:65]
	v_mfma_f32_16x16x32_bf16 v[58:61], v[138:141], v[202:205], v[58:61]
	v_mfma_f32_16x16x32_bf16 v[94:97], v[126:129], v[170:173], v[94:97]
	v_mfma_f32_16x16x32_bf16 v[90:93], v[142:145], v[170:173], v[90:93]
	v_mfma_f32_16x16x32_bf16 v[86:89], v[126:129], v[190:193], v[86:89]
	v_mfma_f32_16x16x32_bf16 v[82:85], v[142:145], v[190:193], v[82:85]
	v_mfma_f32_16x16x32_bf16 v[78:81], v[126:129], v[198:201], v[78:81]
	v_mfma_f32_16x16x32_bf16 v[74:77], v[142:145], v[198:201], v[74:77]
	v_mfma_f32_16x16x32_bf16 v[62:65], v[126:129], v[206:209], v[62:65]
	v_mfma_f32_16x16x32_bf16 v[58:61], v[142:145], v[206:209], v[58:61]
	s_barrier
	s_add_u32 s24, s24, 0x40080
	s_addc_u32 s25, s25, 0
	s_add_i32 s0, s1, s36
	s_mov_b32 m0, s0
	v_lshl_add_u64 v[122:123], s[24:25], 0, v[4:5]
	global_load_lds_dwordx4 v[122:123], off
	s_add_i32 m0, s0, 0x2000
	v_lshl_add_u64 v[122:123], s[24:25], 0, v[146:147]
	global_load_lds_dwordx4 v[122:123], off
	s_waitcnt vmcnt(6)
	s_barrier
	v_mfma_f32_16x16x32_bf16 v[30:33], v[210:213], v[166:169], v[30:33]
	v_mfma_f32_16x16x32_bf16 v[26:29], v[218:221], v[166:169], v[26:29]
	v_mfma_f32_16x16x32_bf16 v[22:25], v[210:213], v[174:177], v[22:25]
	v_mfma_f32_16x16x32_bf16 v[18:21], v[218:221], v[174:177], v[18:21]
	v_mfma_f32_16x16x32_bf16 v[14:17], v[210:213], v[194:197], v[14:17]
	v_mfma_f32_16x16x32_bf16 v[10:13], v[218:221], v[194:197], v[10:13]
	v_mfma_f32_16x16x32_bf16 v[6:9], v[210:213], v[202:205], v[6:9]
	v_mfma_f32_16x16x32_bf16 v[0:3], v[218:221], v[202:205], v[0:3]
	v_mfma_f32_16x16x32_bf16 v[30:33], v[214:217], v[170:173], v[30:33]
	v_mfma_f32_16x16x32_bf16 v[26:29], v[222:225], v[170:173], v[26:29]
	v_mfma_f32_16x16x32_bf16 v[22:25], v[214:217], v[190:193], v[22:25]
	v_mfma_f32_16x16x32_bf16 v[18:21], v[222:225], v[190:193], v[18:21]
	v_mfma_f32_16x16x32_bf16 v[14:17], v[214:217], v[198:201], v[14:17]
	v_mfma_f32_16x16x32_bf16 v[10:13], v[222:225], v[198:201], v[10:13]
	v_mfma_f32_16x16x32_bf16 v[6:9], v[214:217], v[206:209], v[6:9]
	v_mfma_f32_16x16x32_bf16 v[0:3], v[222:225], v[206:209], v[0:3]
	s_add_i32 s61, s61, 2
	s_add_u32 s22, s22, 0x100
	s_addc_u32 s23, s23, 0
	s_add_u32 s59, s59, 0x100
	s_addc_u32 s60, s60, 0
	s_cmp_gt_u32 s61, 13
	s_barrier
	s_cbranch_scc1 .Lpeel_exit_5

; __device__ __forceinline__ unsigned cvt_pk_bf16(float lo, float hi) { unsigned r; asm volatile("s_nop 0\n\tv_cvt_pk_bf16_f32 %0, %1, %2" : "=v"(r) : "v"(lo), "v"(hi)); return r; }
; __device__ __forceinline__ void load_rstd(const float* ss, int row0, f32x4& ra, f32x4& rb) {
;     float t[8];
; #pragma unroll
;     for (int i = 0; i < 8; ++i) t[i] = ss[row0 + (i >> 2) * 128 + (i & 3) * 16];
; #pragma unroll
;     for (int i = 0; i < 4; ++i) { ra[i] = __builtin_amdgcn_rsqf(t[i] * (1.f / 1024.f) + 1e-6f); rb[i] = __builtin_amdgcn_rsqf(t[4 + i] * (1.f / 1024.f) + 1e-6f); }
; }
;     __device__ __forceinline__ void operator()(const f32x4 (&acc)[2][2][4][2], const Unit& u, int wr, int wc, int fr, int fq) const {
;         const int row0 = u.pm * 256 + wr * 64 + fr, col0 = u.pn * 256 + wc * 32 + 8 * fq;
;         f32x4 ra = (f32x4){1.f, 1.f, 1.f, 1.f}, rb = ra;
;         f32x4 swv[4] = {(f32x4){0.f, 0.f, 0.f, 0.f}, (f32x4){0.f, 0.f, 0.f, 0.f}, (f32x4){0.f, 0.f, 0.f, 0.f}, (f32x4){0.f, 0.f, 0.f, 0.f}};
;         if (ss) { load_rstd(ss, row0, ra, rb); const float* swp = sw + (size_t)(u.pm >> 3) * ldc + col0;
;             swv[0] = *(const f32x4*)(swp); swv[1] = *(const f32x4*)(swp + 4); swv[2] = *(const f32x4*)(swp + 128); swv[3] = *(const f32x4*)(swp + 132); }
; #pragma unroll
;         for (int bj = 0; bj < 2; ++bj) {
;             const f32x4 s0 = swv[2 * bj], s1 = swv[2 * bj + 1];
; #pragma unroll
;             for (int ai = 0; ai < 2; ++ai)
; #pragma unroll
;                 for (int m = 0; m < 4; ++m) { const int r = row0 + ai * 128 + m * 16;
;                     const float rstd = ai ? rb[m] : ra[m];
;                     const f32x4 v0 = acc[ai][bj][m][0] * rstd + s0, v1 = acc[ai][bj][m][1] * rstd + s1;
;                     uint4 st; st.x = cvt_pk_bf16(v0[0], v0[1]); st.y = cvt_pk_bf16(v0[2], v0[3]); st.z = cvt_pk_bf16(v1[0], v1[1]); st.w = cvt_pk_bf16(v1[2], v1[3]);
;                     *(uint4*)(O + (size_t)r * ldc + col0 + bj * 128) = st; }
.Lpeel_exit_5:
	v_lshl_add_u32 v174, s20, 8, v159
	v_ashrrev_i32_e32 v175, 31, v174
	v_lshl_add_u64 v[122:123], v[174:175], 2, s[10:11]
	global_load_dword v190, v[122:123], off
	global_load_dword v191, v[122:123], off offset:64
	global_load_dword v192, v[122:123], off offset:128
	global_load_dword v193, v[122:123], off offset:192
	global_load_dword v194, v[122:123], off offset:512
	global_load_dword v195, v[122:123], off offset:576
	global_load_dword v196, v[122:123], off offset:640
	global_load_dword v197, v[122:123], off offset:704
	s_ashr_i32 s0, s20, 3
	s_mul_hi_i32 s23, s0, s52
	s_mul_i32 s22, s0, s52
	s_lshl_b64 s[22:23], s[22:23], 2
	v_lshl_or_b32 v176, s56, 8, v163
	s_add_u32 s22, s49, s22
	s_addc_u32 s23, s50, s23
	v_ashrrev_i32_e32 v177, 31, v176
	v_lshl_add_u64 v[200:201], v[176:177], 2, s[22:23]
	global_load_dwordx4 v[138:141], v[200:201], off offset:16
	global_load_dwordx4 v[142:145], v[200:201], off
	global_load_dwordx4 v[122:125], v[200:201], off offset:528
	global_load_dwordx4 v[126:129], v[200:201], off offset:512
	s_and_b64 vcc, exec, s[4:5]
	s_mov_b32 s56, s12
	s_mov_b32 s20, s14
	s_mov_b64 s[24:25], s[18:19]
	s_waitcnt vmcnt(4)
	v_fmamk_f32 v202, v190, 0x3a800000, v229
	v_rsq_f32_e32 v172, v202
	v_fmamk_f32 v202, v194, 0x3a800000, v229
	v_rsq_f32_e32 v164, v202
	v_fmamk_f32 v202, v191, 0x3a800000, v229
	v_rsq_f32_e32 v170, v202
	v_fmamk_f32 v202, v195, 0x3a800000, v229
	v_rsq_f32_e32 v162, v202
	v_fmamk_f32 v202, v192, 0x3a800000, v229
	v_rsq_f32_e32 v168, v202
	v_fmamk_f32 v202, v196, 0x3a800000, v229
	v_rsq_f32_e32 v160, v202
	v_fmamk_f32 v202, v193, 0x3a800000, v229
	v_fmamk_f32 v203, v197, 0x3a800000, v229
	v_rsq_f32_e32 v166, v202
	v_rsq_f32_e32 v158, v203
	s_waitcnt vmcnt(0)
	v_pk_fma_f32 v[130:131], v[130:131], v[172:173], v[138:139] op_sel_hi:[1,0,1]
	v_pk_fma_f32 v[136:137], v[136:137], v[172:173], v[144:145] op_sel_hi:[1,0,1]
	v_pk_fma_f32 v[134:135], v[134:135], v[172:173], v[142:143] op_sel_hi:[1,0,1]
	v_pk_fma_f32 v[132:133], v[132:133], v[172:173], v[140:141] op_sel_hi:[1,0,1]
	s_nop 0
	v_cvt_pk_bf16_f32 v134, v134, v135
	s_nop 0
	v_cvt_pk_bf16_f32 v135, v136, v137
	s_nop 0
	v_cvt_pk_bf16_f32 v136, v130, v131
	v_mad_i64_i32 v[130:131], s[22:23], v174, s52, 0
	s_nop 0
	v_cvt_pk_bf16_f32 v137, v132, v133
	v_lshl_add_u64 v[130:131], v[130:131], 1, s[8:9]
	v_lshlrev_b64 v[132:133], 1, v[176:177]
	v_lshl_add_u64 v[130:131], v[130:131], 0, v[132:133]
	global_store_dwordx4 v[130:131], v[134:137], off
	v_pk_fma_f32 v[118:119], v[118:119], v[170:171], v[142:143] op_sel_hi:[1,0,1]
	v_pk_fma_f32 v[114:115], v[114:115], v[170:171], v[138:139] op_sel_hi:[1,0,1]
	v_or_b32_e32 v136, 16, v174
	v_pk_fma_f32 v[120:121], v[120:121], v[170:171], v[144:145] op_sel_hi:[1,0,1]
	v_pk_fma_f32 v[134:135], v[116:117], v[170:171], v[140:141] op_sel_hi:[1,0,1]
	s_nop 0
	v_cvt_pk_bf16_f32 v116, v118, v119
	s_nop 0
	v_cvt_pk_bf16_f32 v117, v120, v121
	s_nop 0
	v_cvt_pk_bf16_f32 v118, v114, v115
	v_mad_i64_i32 v[114:115], s[22:23], v136, s52, 0
	v_lshl_add_u64 v[114:115], v[114:115], 1, s[8:9]
	v_lshl_add_u64 v[114:115], v[114:115], 0, v[132:133]
	s_nop 0
	v_cvt_pk_bf16_f32 v119, v134, v135
	global_store_dwordx4 v[114:115], v[116:119], off
	v_pk_fma_f32 v[110:111], v[110:111], v[168:169], v[142:143] op_sel_hi:[1,0,1]
	v_pk_fma_f32 v[106:107], v[106:107], v[168:169], v[138:139] op_sel_hi:[1,0,1]
	v_or_b32_e32 v118, 32, v174
	v_pk_fma_f32 v[112:113], v[112:113], v[168:169], v[144:145] op_sel_hi:[1,0,1]
	v_pk_fma_f32 v[116:117], v[108:109], v[168:169], v[140:141] op_sel_hi:[1,0,1]
	s_nop 0
	v_cvt_pk_bf16_f32 v108, v110, v111
	s_nop 0
	v_cvt_pk_bf16_f32 v109, v112, v113
	s_nop 0
	v_cvt_pk_bf16_f32 v110, v106, v107
	v_mad_i64_i32 v[106:107], s[22:23], v118, s52, 0
	v_lshl_add_u64 v[106:107], v[106:107], 1, s[8:9]
	v_lshl_add_u64 v[106:107], v[106:107], 0, v[132:133]
	s_nop 0
	v_cvt_pk_bf16_f32 v111, v116, v117
	global_store_dwordx4 v[106:107], v[108:111], off
	v_pk_fma_f32 v[102:103], v[102:103], v[166:167], v[142:143] op_sel_hi:[1,0,1]
	v_pk_fma_f32 v[104:105], v[104:105], v[166:167], v[144:145] op_sel_hi:[1,0,1]
	v_or_b32_e32 v110, 48, v174
	v_pk_fma_f32 v[108:109], v[100:101], v[166:167], v[140:141] op_sel_hi:[1,0,1]
	v_pk_fma_f32 v[100:101], v[98:99], v[166:167], v[138:139] op_sel_hi:[1,0,1]
	s_nop 0
	v_cvt_pk_bf16_f32 v98, v102, v103
	v_mad_i64_i32 v[102:103], s[22:23], v110, s52, 0
	v_lshl_add_u64 v[102:103], v[102:103], 1, s[8:9]
	s_nop 0
	v_cvt_pk_bf16_f32 v99, v104, v105
	s_nop 0
	v_cvt_pk_bf16_f32 v100, v100, v101
	v_lshl_add_u64 v[102:103], v[102:103], 0, v[132:133]
	s_nop 0
	v_cvt_pk_bf16_f32 v101, v108, v109
	global_store_dwordx4 v[102:103], v[98:101], off
	v_pk_fma_f32 v[94:95], v[94:95], v[164:165], v[142:143] op_sel_hi:[1,0,1]
	v_pk_fma_f32 v[96:97], v[96:97], v[164:165], v[144:145] op_sel_hi:[1,0,1]
	v_add_u32_e32 v100, 0x80, v174
	v_pk_fma_f32 v[98:99], v[92:93], v[164:165], v[140:141] op_sel_hi:[1,0,1]
	v_pk_fma_f32 v[92:93], v[90:91], v[164:165], v[138:139] op_sel_hi:[1,0,1]
	s_nop 0
	v_cvt_pk_bf16_f32 v90, v94, v95
	v_mad_i64_i32 v[94:95], s[22:23], v100, s52, 0
	v_lshl_add_u64 v[94:95], v[94:95], 1, s[8:9]
	s_nop 0
	v_cvt_pk_bf16_f32 v91, v96, v97
	s_nop 0
	v_cvt_pk_bf16_f32 v92, v92, v93
	v_lshl_add_u64 v[94:95], v[94:95], 0, v[132:133]
	s_nop 0
	v_cvt_pk_bf16_f32 v93, v98, v99
	global_store_dwordx4 v[94:95], v[90:93], off
	v_pk_fma_f32 v[86:87], v[86:87], v[162:163], v[142:143] op_sel_hi:[1,0,1]
	v_pk_fma_f32 v[88:89], v[88:89], v[162:163], v[144:145] op_sel_hi:[1,0,1]
	v_add_u32_e32 v92, 0x90, v174
	v_pk_fma_f32 v[90:91], v[84:85], v[162:163], v[140:141] op_sel_hi:[1,0,1]
	v_pk_fma_f32 v[84:85], v[82:83], v[162:163], v[138:139] op_sel_hi:[1,0,1]
; __device__ __forceinline__ unsigned cvt_pk_bf16(float lo, float hi) { unsigned r; asm volatile("s_nop 0\n\tv_cvt_pk_bf16_f32 %0, %1, %2" : "=v"(r) : "v"(lo), "v"(hi)); return r; }
; #define PG8_WAIT_V(n) asm volatile("s_waitcnt vmcnt(" #n ")" ::: "memory")
; #define PG8_BAR __builtin_amdgcn_s_barrier()
; template <class Epi>
; __device__ __forceinline__ void gemm_phase(LAS unsigned char* lds, const Gemm g, const StaticOrder& S, const Epi& E) {
;     ...
;         E(acc, cur, wr, wc, fr, fq);
;         if (!has_next) break;
; #pragma unroll
;         for (int a = 0; a < 2; ++a)
; #pragma unroll
;             for (int b = 0; b < 2; ++b)
; #pragma unroll
;                 for (int m = 0; m < 4; ++m)
; #pragma unroll
;                     for (int n = 0; n < 2; ++n) acc[a][b][m][n] = (f32x4){0.f, 0.f, 0.f, 0.f};
;         cur = nxt; cA = nA; cB = nB; ++ui;
;     }
;     PG8_WAIT_V(0);
;     if (wr == 0) PG8_BAR;
;     PG8_BAR;
;     __device__ __forceinline__ void operator()(const f32x4 (&acc)[2][2][4][2], const Unit& u, int wr, int wc, int fr, int fq) const {
;     ...
;         for (int bj = 0; bj < 2; ++bj) {
;             const f32x4 s0 = swv[2 * bj], s1 = swv[2 * bj + 1];
; #pragma unroll
;             for (int ai = 0; ai < 2; ++ai)
; #pragma unroll
;                 for (int m = 0; m < 4; ++m) { const int r = row0 + ai * 128 + m * 16;
;                     const float rstd = ai ? rb[m] : ra[m];
;                     const f32x4 v0 = acc[ai][bj][m][0] * rstd + s0, v1 = acc[ai][bj][m][1] * rstd + s1;
;                     uint4 st; st.x = cvt_pk_bf16(v0[0], v0[1]); st.y = cvt_pk_bf16(v0[2], v0[3]); st.z = cvt_pk_bf16(v1[0], v1[1]); st.w = cvt_pk_bf16(v1[2], v1[3]);
;                     *(uint4*)(O + (size_t)r * ldc + col0 + bj * 128) = st; }
	s_nop 0
	v_cvt_pk_bf16_f32 v82, v86, v87
	v_mad_i64_i32 v[86:87], s[22:23], v92, s52, 0
	v_lshl_add_u64 v[86:87], v[86:87], 1, s[8:9]
	s_nop 0
	v_cvt_pk_bf16_f32 v83, v88, v89
	s_nop 0
	v_cvt_pk_bf16_f32 v84, v84, v85
	v_lshl_add_u64 v[86:87], v[86:87], 0, v[132:133]
	s_nop 0
	v_cvt_pk_bf16_f32 v85, v90, v91
	global_store_dwordx4 v[86:87], v[82:85], off
	v_pk_fma_f32 v[78:79], v[78:79], v[160:161], v[142:143] op_sel_hi:[1,0,1]
	v_pk_fma_f32 v[80:81], v[80:81], v[160:161], v[144:145] op_sel_hi:[1,0,1]
	v_add_u32_e32 v84, 0xa0, v174
	v_pk_fma_f32 v[82:83], v[76:77], v[160:161], v[140:141] op_sel_hi:[1,0,1]
	v_pk_fma_f32 v[76:77], v[74:75], v[160:161], v[138:139] op_sel_hi:[1,0,1]
	s_nop 0
	v_cvt_pk_bf16_f32 v74, v78, v79
	v_mad_i64_i32 v[78:79], s[22:23], v84, s52, 0
	v_lshl_add_u64 v[78:79], v[78:79], 1, s[8:9]
	s_nop 0
	v_cvt_pk_bf16_f32 v75, v80, v81
	s_nop 0
	v_cvt_pk_bf16_f32 v76, v76, v77
	v_lshl_add_u64 v[78:79], v[78:79], 0, v[132:133]
	s_nop 0
	v_cvt_pk_bf16_f32 v77, v82, v83
	global_store_dwordx4 v[78:79], v[74:77], off
	v_pk_fma_f32 v[62:63], v[62:63], v[158:159], v[142:143] op_sel_hi:[1,0,1]
	v_pk_fma_f32 v[64:65], v[64:65], v[158:159], v[144:145] op_sel_hi:[1,0,1]
	v_add_u32_e32 v76, 0xb0, v174
	v_pk_fma_f32 v[74:75], v[60:61], v[158:159], v[140:141] op_sel_hi:[1,0,1]
	v_pk_fma_f32 v[60:61], v[58:59], v[158:159], v[138:139] op_sel_hi:[1,0,1]
	s_nop 0
	v_cvt_pk_bf16_f32 v58, v62, v63
	v_mad_i64_i32 v[62:63], s[22:23], v76, s52, 0
	v_lshl_add_u64 v[62:63], v[62:63], 1, s[8:9]
	s_nop 0
	v_cvt_pk_bf16_f32 v59, v64, v65
	v_lshl_add_u64 v[62:63], v[62:63], 0, v[132:133]
	s_nop 0
	v_cvt_pk_bf16_f32 v60, v60, v61
	s_nop 0
	v_cvt_pk_bf16_f32 v61, v74, v75
	global_store_dwordx4 v[62:63], v[58:61], off
	v_pk_fma_f32 v[64:65], v[68:69], v[172:173], v[124:125] op_sel_hi:[1,0,1]
	v_pk_fma_f32 v[66:67], v[66:67], v[172:173], v[122:123] op_sel_hi:[1,0,1]
	v_pk_fma_f32 v[58:59], v[70:71], v[172:173], v[126:127] op_sel_hi:[1,0,1]
	v_pk_fma_f32 v[60:61], v[72:73], v[172:173], v[128:129] op_sel_hi:[1,0,1]
	s_nop 0
	v_cvt_pk_bf16_f32 v58, v58, v59
	v_pk_fma_f32 v[56:57], v[56:57], v[170:171], v[128:129] op_sel_hi:[1,0,1]
	s_nop 0
	v_cvt_pk_bf16_f32 v59, v60, v61
	s_nop 0
	v_cvt_pk_bf16_f32 v60, v66, v67
	s_nop 0
	v_cvt_pk_bf16_f32 v61, v64, v65
	global_store_dwordx4 v[130:131], v[58:61], off offset:256
	v_pk_fma_f32 v[54:55], v[54:55], v[170:171], v[126:127] op_sel_hi:[1,0,1]
	v_pk_fma_f32 v[48:49], v[48:49], v[168:169], v[128:129] op_sel_hi:[1,0,1]
	v_pk_fma_f32 v[58:59], v[52:53], v[170:171], v[124:125] op_sel_hi:[1,0,1]
	v_pk_fma_f32 v[52:53], v[50:51], v[170:171], v[122:123] op_sel_hi:[1,0,1]
	s_nop 0
	v_cvt_pk_bf16_f32 v50, v54, v55
	s_nop 0
	v_cvt_pk_bf16_f32 v51, v56, v57
	v_pk_fma_f32 v[46:47], v[46:47], v[168:169], v[126:127] op_sel_hi:[1,0,1]
	s_nop 0
	v_cvt_pk_bf16_f32 v52, v52, v53
	s_nop 0
	v_cvt_pk_bf16_f32 v53, v58, v59
	global_store_dwordx4 v[114:115], v[50:53], off offset:256
	v_pk_fma_f32 v[40:41], v[40:41], v[166:167], v[128:129] op_sel_hi:[1,0,1]
	v_pk_fma_f32 v[38:39], v[38:39], v[166:167], v[126:127] op_sel_hi:[1,0,1]
	v_pk_fma_f32 v[50:51], v[44:45], v[168:169], v[124:125] op_sel_hi:[1,0,1]
	v_pk_fma_f32 v[44:45], v[42:43], v[168:169], v[122:123] op_sel_hi:[1,0,1]
	s_nop 0
	v_cvt_pk_bf16_f32 v42, v46, v47
	s_nop 0
	v_cvt_pk_bf16_f32 v43, v48, v49
	v_pk_fma_f32 v[32:33], v[32:33], v[164:165], v[128:129] op_sel_hi:[1,0,1]
	s_nop 0
	v_cvt_pk_bf16_f32 v44, v44, v45
	s_nop 0
	v_cvt_pk_bf16_f32 v45, v50, v51
	global_store_dwordx4 v[106:107], v[42:45], off offset:256
	v_pk_fma_f32 v[30:31], v[30:31], v[164:165], v[126:127] op_sel_hi:[1,0,1]
	v_pk_fma_f32 v[24:25], v[24:25], v[162:163], v[128:129] op_sel_hi:[1,0,1]
	v_pk_fma_f32 v[42:43], v[36:37], v[166:167], v[124:125] op_sel_hi:[1,0,1]
	v_pk_fma_f32 v[36:37], v[34:35], v[166:167], v[122:123] op_sel_hi:[1,0,1]
	s_nop 0
	v_cvt_pk_bf16_f32 v34, v38, v39
	s_nop 0
	v_cvt_pk_bf16_f32 v35, v40, v41
	v_pk_fma_f32 v[22:23], v[22:23], v[162:163], v[126:127] op_sel_hi:[1,0,1]
	s_nop 0
	v_cvt_pk_bf16_f32 v36, v36, v37
	s_nop 0
	v_cvt_pk_bf16_f32 v37, v42, v43
	global_store_dwordx4 v[102:103], v[34:37], off offset:256
	v_pk_fma_f32 v[16:17], v[16:17], v[160:161], v[128:129] op_sel_hi:[1,0,1]
	v_pk_fma_f32 v[14:15], v[14:15], v[160:161], v[126:127] op_sel_hi:[1,0,1]
	v_pk_fma_f32 v[34:35], v[28:29], v[164:165], v[124:125] op_sel_hi:[1,0,1]
	v_pk_fma_f32 v[28:29], v[26:27], v[164:165], v[122:123] op_sel_hi:[1,0,1]
	s_nop 0
	v_cvt_pk_bf16_f32 v26, v30, v31
	s_nop 0
	v_cvt_pk_bf16_f32 v27, v32, v33
	s_mov_b64 s[22:23], s[16:17]
	s_nop 0
	v_cvt_pk_bf16_f32 v28, v28, v29
	s_nop 0
	v_cvt_pk_bf16_f32 v29, v34, v35
	global_store_dwordx4 v[94:95], v[26:29], off offset:256
	v_pk_fma_f32 v[8:9], v[8:9], v[158:159], v[128:129] op_sel_hi:[1,0,1]
	v_pk_fma_f32 v[6:7], v[6:7], v[158:159], v[126:127] op_sel_hi:[1,0,1]
	v_pk_fma_f32 v[26:27], v[20:21], v[162:163], v[124:125] op_sel_hi:[1,0,1]
	v_pk_fma_f32 v[20:21], v[18:19], v[162:163], v[122:123] op_sel_hi:[1,0,1]
	s_nop 0
	v_cvt_pk_bf16_f32 v18, v22, v23
	s_nop 0
	v_cvt_pk_bf16_f32 v19, v24, v25
	s_nop 0
	s_nop 0
	v_cvt_pk_bf16_f32 v20, v20, v21
	s_nop 0
	v_cvt_pk_bf16_f32 v21, v26, v27
	global_store_dwordx4 v[86:87], v[18:21], off offset:256
	s_nop 1
	v_pk_fma_f32 v[18:19], v[12:13], v[160:161], v[124:125] op_sel_hi:[1,0,1]
	v_pk_fma_f32 v[12:13], v[10:11], v[160:161], v[122:123] op_sel_hi:[1,0,1]
	s_nop 0
	v_cvt_pk_bf16_f32 v10, v14, v15
	s_nop 0
	v_cvt_pk_bf16_f32 v11, v16, v17
	s_nop 0
	s_nop 0
	v_cvt_pk_bf16_f32 v12, v12, v13
	s_nop 0
	v_cvt_pk_bf16_f32 v13, v18, v19
	global_store_dwordx4 v[78:79], v[10:13], off offset:256
	s_nop 1
	v_pk_fma_f32 v[10:11], v[2:3], v[158:159], v[124:125] op_sel_hi:[1,0,1]
	v_pk_fma_f32 v[2:3], v[0:1], v[158:159], v[122:123] op_sel_hi:[1,0,1]
	s_nop 0
	v_cvt_pk_bf16_f32 v0, v6, v7
	s_nop 0
	v_cvt_pk_bf16_f32 v1, v8, v9
	s_nop 0
	s_nop 0
	v_cvt_pk_bf16_f32 v2, v2, v3
	s_nop 0
	v_cvt_pk_bf16_f32 v3, v10, v11
	global_store_dwordx4 v[62:63], v[0:3], off offset:256
	s_cbranch_vccz .LBB0_2076
	s_waitcnt vmcnt(0)
	s_cmpk_gt_u32 s28, 0xff
	s_cbranch_scc1 .LBB0_2083
	s_barrier

; #define PG8_STAGE(bufoff, gbase, voff) do { _Pragma("unroll") for (int _i = 0; _i < 2; ++_i) \
;         __builtin_amdgcn_global_load_lds((const unsigned*)((const char*)(gbase) + (voff)[_i]), (LAS unsigned*)(lds + (bufoff) + ldsw + _i * 8192), 16, 0, 0); } while (0)
; #define PG8_LDA(dst, b, h) do { _Pragma("unroll") for (int m = 0; m < 4; ++m) _Pragma("unroll") for (int k = 0; k < 2; ++k) dst[m][k] = *(const LAS bf16x8*)(lds + PG8_SA(b, h) + aoff + m * 2048 + k * 1024); } while (0)
; #define PG8_LDB(dst, b, h) do { _Pragma("unroll") for (int n = 0; n < 2; ++n) _Pragma("unroll") for (int k = 0; k < 2; ++k) dst[n][k] = *(const LAS bf16x8*)(lds + PG8_SB(b, h) + boff + n * 2048 + k * 1024); } while (0)
; #define PG8_MMA(ai, bj, At, Bt) do { __builtin_amdgcn_s_setprio(1); _Pragma("unroll") for (int m = 0; m < 4; ++m) _Pragma("unroll") for (int n = 0; n < 2; ++n) _Pragma("unroll") for (int k = 0; k < 2; ++k) \
;         acc[ai][bj][m][n] = __builtin_amdgcn_mfma_f32_16x16x32_bf16(Bt[n][k], At[m][k], acc[ai][bj][m][n], 0, 0, 0); __builtin_amdgcn_s_setprio(0); } while (0)
; #define PG8_WAIT_L(n) asm volatile("s_waitcnt lgkmcnt(" #n ")" ::: "memory")
; template <class Epi>
; __device__ __forceinline__ void gemm_phase(LAS unsigned char* lds, const Gemm g, const StaticOrder& S, const Epi& E) {
;     ...
;     for (;;) {
;         const bool has_next = S.next(ui + 1, nxt);
;         const char* nA = has_next ? (const char*)g.A + (size_t)nxt.pm * tstep : cA; const char* nB = has_next ? (const char*)g.Bt + (size_t)nxt.pn * tstep : cB;
;         for (int t = 0; t < nt; t += 2) {
;             const bool last = (t == nt - 2);
;             const char* a1 = cA + (size_t)(t + 1) * kstep;
;             const char* a2 = last ? nA : cA + (size_t)(t + 2) * kstep; const char* b2 = last ? nB : cB + (size_t)(t + 2) * kstep;
;             const char* a3 = a2 + kstep; const char* b3 = b2 + kstep;
;             PG8_LDB(B0, 0, 0); PG8_SCHED; PG8_LDA(At, 0, 0); PG8_STAGE(PG8_SA(1, 1), a1 + hstep, voffA);
;             PG8_WAIT_L(8); PG8_BAR; PG8_WAIT_L(0); PG8_MMA(0, 0, At, B0); PG8_BAR; PG8_SCHED;
;             PG8_LDB(B1, 0, 1); PG8_STAGE(PG8_SB(0, 0), b2, voffB);
;             PG8_BAR; PG8_WAIT_L(0); PG8_MMA(0, 1, At, B1); PG8_BAR;
;             PG8_LDA(At, 0, 1); PG8_STAGE(PG8_SA(0, 0), a2, voffA);
;             PG8_BAR; PG8_WAIT_L(0); PG8_MMA(1, 0, At, B0); PG8_BAR; PG8_SCHED;
.LBB0_2402:
	s_add_u32 s39, s14, 0x100
	s_addc_u32 s40, s15, 0
	s_mov_b32 s41, -2
	s_add_u32 s14, s12, 0x100
	s_addc_u32 s15, s13, 0
	s_add_i32 s0, 0, 0x10000
	v_add_u32_e32 v156, s0, v141
	ds_read_b128 v[144:147], v156
	ds_read_b128 v[148:151], v156 offset:1024
	ds_read_b128 v[152:155], v156 offset:2048
	ds_read_b128 v[156:159], v156 offset:3072
	s_cmp_eq_u32 s41, 2
	s_cselect_b32 s19, s7, s15
	s_cselect_b32 s18, s6, s14
	s_cselect_b32 s17, s9, s40
	s_cselect_b32 s16, s8, s39
	v_lshl_add_u64 v[176:177], s[12:13], 0, v[136:137]
	s_add_i32 m0, s26, 0xc000
	ds_read_b128 v[160:163], v143
	ds_read_b128 v[164:167], v143 offset:1024
	ds_read_b128 v[168:171], v143 offset:2048
	ds_read_b128 v[172:175], v143 offset:3072
	ds_read_b128 v[190:193], v143 offset:4096
	ds_read_b128 v[194:197], v143 offset:5120
	ds_read_b128 v[198:201], v143 offset:6144
	ds_read_b128 v[202:205], v143 offset:7168
	global_load_lds_dwordx4 v[176:177], off
	s_add_i32 m0, s26, 0xe000
	v_lshl_add_u64 v[176:177], s[12:13], 0, v[138:139]
	global_load_lds_dwordx4 v[176:177], off
	s_waitcnt lgkmcnt(8)
	s_barrier
	s_waitcnt lgkmcnt(0)
	v_mfma_f32_16x16x32_bf16 v[126:129], v[144:147], v[160:163], 0
	v_mfma_f32_16x16x32_bf16 v[122:125], v[152:155], v[160:163], 0
	v_mfma_f32_16x16x32_bf16 v[118:121], v[144:147], v[168:171], 0
	v_mfma_f32_16x16x32_bf16 v[114:117], v[152:155], v[168:171], 0
	v_mfma_f32_16x16x32_bf16 v[110:113], v[144:147], v[190:193], 0
	v_mfma_f32_16x16x32_bf16 v[106:109], v[152:155], v[190:193], 0
	v_mfma_f32_16x16x32_bf16 v[102:105], v[144:147], v[198:201], 0
	v_mfma_f32_16x16x32_bf16 v[98:101], v[152:155], v[198:201], 0
	v_mfma_f32_16x16x32_bf16 v[126:129], v[148:151], v[164:167], v[126:129]
	v_mfma_f32_16x16x32_bf16 v[122:125], v[156:159], v[164:167], v[122:125]
	v_mfma_f32_16x16x32_bf16 v[118:121], v[148:151], v[172:175], v[118:121]
	v_mfma_f32_16x16x32_bf16 v[114:117], v[156:159], v[172:175], v[114:117]
	v_mfma_f32_16x16x32_bf16 v[110:113], v[148:151], v[194:197], v[110:113]
	v_mfma_f32_16x16x32_bf16 v[106:109], v[156:159], v[194:197], v[106:109]
	v_mfma_f32_16x16x32_bf16 v[102:105], v[148:151], v[202:205], v[102:105]
	v_mfma_f32_16x16x32_bf16 v[98:101], v[156:159], v[202:205], v[98:101]
	s_barrier
	s_add_i32 s1, 0, 0x14000
	v_add_u32_e32 v176, s1, v141
	s_add_i32 s0, s0, s25
	ds_read_b128 v[206:209], v176
	ds_read_b128 v[210:213], v176 offset:1024
	ds_read_b128 v[214:217], v176 offset:2048
	ds_read_b128 v[218:221], v176 offset:3072
	v_lshl_add_u64 v[176:177], s[16:17], 0, v[4:5]
	s_mov_b32 m0, s0
	v_lshl_add_u64 v[186:187], s[16:17], 0, v[130:131]
	global_load_lds_dwordx4 v[176:177], off
	s_add_i32 m0, s0, 0x2000
	s_nop 0
	global_load_lds_dwordx4 v[186:187], off
	s_barrier
	s_waitcnt lgkmcnt(0)
	v_mfma_f32_16x16x32_bf16 v[74:77], v[206:209], v[160:163], 0
	v_mfma_f32_16x16x32_bf16 v[66:69], v[214:217], v[160:163], 0
	v_mfma_f32_16x16x32_bf16 v[58:61], v[206:209], v[168:171], 0
	v_mfma_f32_16x16x32_bf16 v[50:53], v[214:217], v[168:171], 0
	v_mfma_f32_16x16x32_bf16 v[46:49], v[206:209], v[190:193], 0
	v_mfma_f32_16x16x32_bf16 v[42:45], v[214:217], v[190:193], 0
	v_mfma_f32_16x16x32_bf16 v[38:41], v[206:209], v[198:201], 0
	v_mfma_f32_16x16x32_bf16 v[34:37], v[214:217], v[198:201], 0
	v_mfma_f32_16x16x32_bf16 v[74:77], v[210:213], v[164:167], v[74:77]
	v_mfma_f32_16x16x32_bf16 v[66:69], v[218:221], v[164:167], v[66:69]
	v_mfma_f32_16x16x32_bf16 v[58:61], v[210:213], v[172:175], v[58:61]
	v_mfma_f32_16x16x32_bf16 v[50:53], v[218:221], v[172:175], v[50:53]
	v_mfma_f32_16x16x32_bf16 v[46:49], v[210:213], v[194:197], v[46:49]
	v_mfma_f32_16x16x32_bf16 v[42:45], v[218:221], v[194:197], v[42:45]
	v_mfma_f32_16x16x32_bf16 v[38:41], v[210:213], v[202:205], v[38:41]
	v_mfma_f32_16x16x32_bf16 v[34:37], v[218:221], v[202:205], v[34:37]
	s_mov_b32 m0, s26
	v_lshl_add_u64 v[222:223], s[18:19], 0, v[134:135]
	s_barrier
	ds_read_b128 v[160:163], v143 offset:16384
	ds_read_b128 v[164:167], v143 offset:17408
	ds_read_b128 v[168:171], v143 offset:18432
	ds_read_b128 v[172:175], v143 offset:19456
	ds_read_b128 v[190:193], v143 offset:20480
	ds_read_b128 v[194:197], v143 offset:21504
	ds_read_b128 v[198:201], v143 offset:22528
	ds_read_b128 v[202:205], v143 offset:23552
	global_load_lds_dwordx4 v[222:223], off
	s_mov_b32 m0, s27
	v_lshl_add_u64 v[224:225], s[18:19], 0, v[132:133]
	global_load_lds_dwordx4 v[224:225], off
	s_barrier
	s_waitcnt lgkmcnt(0)
	v_mfma_f32_16x16x32_bf16 v[94:97], v[144:147], v[160:163], 0
	v_mfma_f32_16x16x32_bf16 v[90:93], v[152:155], v[160:163], 0
	v_mfma_f32_16x16x32_bf16 v[86:89], v[144:147], v[168:171], 0
	v_mfma_f32_16x16x32_bf16 v[82:85], v[152:155], v[168:171], 0
	v_mfma_f32_16x16x32_bf16 v[78:81], v[144:147], v[190:193], 0
	v_mfma_f32_16x16x32_bf16 v[70:73], v[152:155], v[190:193], 0
	v_mfma_f32_16x16x32_bf16 v[62:65], v[144:147], v[198:201], 0
	v_mfma_f32_16x16x32_bf16 v[54:57], v[152:155], v[198:201], 0
	v_mfma_f32_16x16x32_bf16 v[94:97], v[148:151], v[164:167], v[94:97]
	v_mfma_f32_16x16x32_bf16 v[90:93], v[156:159], v[164:167], v[90:93]
	v_mfma_f32_16x16x32_bf16 v[86:89], v[148:151], v[172:175], v[86:89]
	v_mfma_f32_16x16x32_bf16 v[82:85], v[156:159], v[172:175], v[82:85]
	v_mfma_f32_16x16x32_bf16 v[78:81], v[148:151], v[194:197], v[78:81]
	v_mfma_f32_16x16x32_bf16 v[70:73], v[156:159], v[194:197], v[70:73]
	v_mfma_f32_16x16x32_bf16 v[62:65], v[148:151], v[202:205], v[62:65]
	v_mfma_f32_16x16x32_bf16 v[54:57], v[156:159], v[202:205], v[54:57]
	s_barrier
	s_add_u32 s12, s16, 0x18000
	s_addc_u32 s13, s17, 0
	s_add_i32 s0, s1, s25
	s_mov_b32 m0, s0
	v_lshl_add_u64 v[144:145], s[12:13], 0, v[4:5]
	global_load_lds_dwordx4 v[144:145], off
	s_add_i32 m0, s0, 0x2000
	v_lshl_add_u64 v[144:145], s[12:13], 0, v[130:131]
	global_load_lds_dwordx4 v[144:145], off
	s_waitcnt vmcnt(6)
	s_barrier
; #define PG8_STAGE(bufoff, gbase, voff) do { _Pragma("unroll") for (int _i = 0; _i < 2; ++_i) \
;         __builtin_amdgcn_global_load_lds((const unsigned*)((const char*)(gbase) + (voff)[_i]), (LAS unsigned*)(lds + (bufoff) + ldsw + _i * 8192), 16, 0, 0); } while (0)
; #define PG8_LDA(dst, b, h) do { _Pragma("unroll") for (int m = 0; m < 4; ++m) _Pragma("unroll") for (int k = 0; k < 2; ++k) dst[m][k] = *(const LAS bf16x8*)(lds + PG8_SA(b, h) + aoff + m * 2048 + k * 1024); } while (0)
; #define PG8_LDB(dst, b, h) do { _Pragma("unroll") for (int n = 0; n < 2; ++n) _Pragma("unroll") for (int k = 0; k < 2; ++k) dst[n][k] = *(const LAS bf16x8*)(lds + PG8_SB(b, h) + boff + n * 2048 + k * 1024); } while (0)
; #define PG8_MMA(ai, bj, At, Bt) do { __builtin_amdgcn_s_setprio(1); _Pragma("unroll") for (int m = 0; m < 4; ++m) _Pragma("unroll") for (int n = 0; n < 2; ++n) _Pragma("unroll") for (int k = 0; k < 2; ++k) \
;         acc[ai][bj][m][n] = __builtin_amdgcn_mfma_f32_16x16x32_bf16(Bt[n][k], At[m][k], acc[ai][bj][m][n], 0, 0, 0); __builtin_amdgcn_s_setprio(0); } while (0)
; #define PG8_WAIT_V(n) asm volatile("s_waitcnt vmcnt(" #n ")" ::: "memory")
; #define PG8_WAIT_L(n) asm volatile("s_waitcnt lgkmcnt(" #n ")" ::: "memory")
; #define PG8_BAR __builtin_amdgcn_s_barrier()
; #define PG8_SCHED __builtin_amdgcn_sched_barrier(0)
; template <class Epi>
; __device__ __forceinline__ void gemm_phase(LAS unsigned char* lds, const Gemm g, const StaticOrder& S, const Epi& E) {
;     ...
;             PG8_BAR; PG8_WAIT_L(0); PG8_MMA(1, 0, At, B0); PG8_BAR; PG8_SCHED;
;             PG8_STAGE(PG8_SB(0, 1), b2 + hstep, voffB);
;             PG8_WAIT_V(6); PG8_BAR; PG8_MMA(1, 1, At, B1); PG8_BAR;
;             PG8_LDB(B0, 1, 0); PG8_SCHED; PG8_LDA(At, 1, 0); PG8_STAGE(PG8_SA(0, 1), a2 + hstep, voffA);
;             PG8_WAIT_L(8); PG8_BAR; PG8_WAIT_L(0); PG8_MMA(0, 0, At, B0); PG8_BAR; PG8_SCHED;
;             PG8_LDB(B1, 1, 1); PG8_STAGE(PG8_SB(1, 0), b3, voffB);
;             PG8_BAR; PG8_WAIT_L(0); PG8_MMA(0, 1, At, B1); PG8_BAR;
	v_mfma_f32_16x16x32_bf16 v[30:33], v[206:209], v[160:163], 0
	v_mfma_f32_16x16x32_bf16 v[26:29], v[214:217], v[160:163], 0
	v_mfma_f32_16x16x32_bf16 v[22:25], v[206:209], v[168:171], 0
	v_mfma_f32_16x16x32_bf16 v[18:21], v[214:217], v[168:171], 0
	v_mfma_f32_16x16x32_bf16 v[14:17], v[206:209], v[190:193], 0
	v_mfma_f32_16x16x32_bf16 v[10:13], v[214:217], v[190:193], 0
	v_mfma_f32_16x16x32_bf16 v[6:9], v[206:209], v[198:201], 0
	v_mfma_f32_16x16x32_bf16 v[0:3], v[214:217], v[198:201], 0
	v_mfma_f32_16x16x32_bf16 v[30:33], v[210:213], v[164:167], v[30:33]
	v_mfma_f32_16x16x32_bf16 v[26:29], v[218:221], v[164:167], v[26:29]
	v_mfma_f32_16x16x32_bf16 v[22:25], v[210:213], v[172:175], v[22:25]
	v_mfma_f32_16x16x32_bf16 v[18:21], v[218:221], v[172:175], v[18:21]
	v_mfma_f32_16x16x32_bf16 v[14:17], v[210:213], v[194:197], v[14:17]
	v_mfma_f32_16x16x32_bf16 v[10:13], v[218:221], v[194:197], v[10:13]
	v_mfma_f32_16x16x32_bf16 v[6:9], v[210:213], v[202:205], v[6:9]
	v_mfma_f32_16x16x32_bf16 v[0:3], v[218:221], v[202:205], v[0:3]
	s_add_i32 s0, 0, 0x18000
	v_add_u32_e32 v156, s0, v141
	s_barrier
	ds_read_b128 v[144:147], v156
	ds_read_b128 v[148:151], v156 offset:1024
	ds_read_b128 v[152:155], v156 offset:2048
	ds_read_b128 v[156:159], v156 offset:3072
	s_add_u32 s12, s18, 0x18000
	s_addc_u32 s13, s19, 0
	s_mov_b32 m0, s28
	v_lshl_add_u64 v[206:207], s[12:13], 0, v[134:135]
	ds_read_b128 v[160:163], v143 offset:32768
	ds_read_b128 v[164:167], v143 offset:33792
	ds_read_b128 v[168:171], v143 offset:34816
	ds_read_b128 v[172:175], v143 offset:35840
	ds_read_b128 v[190:193], v143 offset:36864
	ds_read_b128 v[194:197], v143 offset:37888
	ds_read_b128 v[198:201], v143 offset:38912
	ds_read_b128 v[202:205], v143 offset:39936
	global_load_lds_dwordx4 v[206:207], off
	s_mov_b32 m0, s29
	v_lshl_add_u64 v[206:207], s[12:13], 0, v[132:133]
	global_load_lds_dwordx4 v[206:207], off
	s_waitcnt lgkmcnt(8)
	s_barrier
	s_waitcnt lgkmcnt(0)
	v_mfma_f32_16x16x32_bf16 v[126:129], v[144:147], v[160:163], v[126:129]
	v_mfma_f32_16x16x32_bf16 v[122:125], v[152:155], v[160:163], v[122:125]
	v_mfma_f32_16x16x32_bf16 v[118:121], v[144:147], v[168:171], v[118:121]
	v_mfma_f32_16x16x32_bf16 v[114:117], v[152:155], v[168:171], v[114:117]
	v_mfma_f32_16x16x32_bf16 v[110:113], v[144:147], v[190:193], v[110:113]
	v_mfma_f32_16x16x32_bf16 v[106:109], v[152:155], v[190:193], v[106:109]
	v_mfma_f32_16x16x32_bf16 v[102:105], v[144:147], v[198:201], v[102:105]
	v_mfma_f32_16x16x32_bf16 v[98:101], v[152:155], v[198:201], v[98:101]
	v_mfma_f32_16x16x32_bf16 v[126:129], v[148:151], v[164:167], v[126:129]
	v_mfma_f32_16x16x32_bf16 v[122:125], v[156:159], v[164:167], v[122:125]
	v_mfma_f32_16x16x32_bf16 v[118:121], v[148:151], v[172:175], v[118:121]
	v_mfma_f32_16x16x32_bf16 v[114:117], v[156:159], v[172:175], v[114:117]
	v_mfma_f32_16x16x32_bf16 v[110:113], v[148:151], v[194:197], v[110:113]
	v_mfma_f32_16x16x32_bf16 v[106:109], v[156:159], v[194:197], v[106:109]
	v_mfma_f32_16x16x32_bf16 v[102:105], v[148:151], v[202:205], v[102:105]
	v_mfma_f32_16x16x32_bf16 v[98:101], v[156:159], v[202:205], v[98:101]
	s_barrier
	s_add_i32 s1, 0, 0x1c000
	s_add_i32 s0, s0, s25
	v_add_u32_e32 v218, s1, v141
	v_lshl_add_u64 v[176:177], v[176:177], 0, s[86:87]
	s_mov_b32 m0, s0
	ds_read_b128 v[206:209], v218
	ds_read_b128 v[210:213], v218 offset:1024
	ds_read_b128 v[214:217], v218 offset:2048
	ds_read_b128 v[218:221], v218 offset:3072
	global_load_lds_dwordx4 v[176:177], off
	s_add_i32 m0, s0, 0x2000
	v_lshl_add_u64 v[176:177], v[186:187], 0, s[86:87]
	global_load_lds_dwordx4 v[176:177], off
	s_barrier
; #define PG8_STAGE(bufoff, gbase, voff) do { _Pragma("unroll") for (int _i = 0; _i < 2; ++_i) \
;         __builtin_amdgcn_global_load_lds((const unsigned*)((const char*)(gbase) + (voff)[_i]), (LAS unsigned*)(lds + (bufoff) + ldsw + _i * 8192), 16, 0, 0); } while (0)
; #define PG8_LDA(dst, b, h) do { _Pragma("unroll") for (int m = 0; m < 4; ++m) _Pragma("unroll") for (int k = 0; k < 2; ++k) dst[m][k] = *(const LAS bf16x8*)(lds + PG8_SA(b, h) + aoff + m * 2048 + k * 1024); } while (0)
; #define PG8_LDB(dst, b, h) do { _Pragma("unroll") for (int n = 0; n < 2; ++n) _Pragma("unroll") for (int k = 0; k < 2; ++k) dst[n][k] = *(const LAS bf16x8*)(lds + PG8_SB(b, h) + boff + n * 2048 + k * 1024); } while (0)
; #define PG8_MMA(ai, bj, At, Bt) do { __builtin_amdgcn_s_setprio(1); _Pragma("unroll") for (int m = 0; m < 4; ++m) _Pragma("unroll") for (int n = 0; n < 2; ++n) _Pragma("unroll") for (int k = 0; k < 2; ++k) \
;         acc[ai][bj][m][n] = __builtin_amdgcn_mfma_f32_16x16x32_bf16(Bt[n][k], At[m][k], acc[ai][bj][m][n], 0, 0, 0); __builtin_amdgcn_s_setprio(0); } while (0)
; #define PG8_WAIT_V(n) asm volatile("s_waitcnt vmcnt(" #n ")" ::: "memory")
; #define PG8_WAIT_L(n) asm volatile("s_waitcnt lgkmcnt(" #n ")" ::: "memory")
; #define PG8_BAR __builtin_amdgcn_s_barrier()
; #define PG8_SCHED __builtin_amdgcn_sched_barrier(0)
; template <class Epi>
; __device__ __forceinline__ void gemm_phase(LAS unsigned char* lds, const Gemm g, const StaticOrder& S, const Epi& E) {
;     ...
;             PG8_WAIT_L(8); PG8_BAR; PG8_WAIT_L(0); PG8_MMA(0, 0, At, B0); PG8_BAR; PG8_SCHED;
;             PG8_LDB(B1, 1, 1); PG8_STAGE(PG8_SB(1, 0), b3, voffB);
;             PG8_BAR; PG8_WAIT_L(0); PG8_MMA(0, 1, At, B1); PG8_BAR;
;             PG8_LDA(At, 1, 1); PG8_STAGE(PG8_SA(1, 0), a3, voffA);
;             PG8_BAR; PG8_WAIT_L(0); PG8_MMA(1, 0, At, B0); PG8_BAR; PG8_SCHED;
;             PG8_STAGE(PG8_SB(1, 1), b3 + hstep, voffB);
;             PG8_WAIT_V(6); PG8_BAR; PG8_MMA(1, 1, At, B1); PG8_BAR;
	s_waitcnt lgkmcnt(0)
	v_mfma_f32_16x16x32_bf16 v[74:77], v[206:209], v[160:163], v[74:77]
	v_mfma_f32_16x16x32_bf16 v[66:69], v[214:217], v[160:163], v[66:69]
	v_mfma_f32_16x16x32_bf16 v[58:61], v[206:209], v[168:171], v[58:61]
	v_mfma_f32_16x16x32_bf16 v[50:53], v[214:217], v[168:171], v[50:53]
	v_mfma_f32_16x16x32_bf16 v[46:49], v[206:209], v[190:193], v[46:49]
	v_mfma_f32_16x16x32_bf16 v[42:45], v[214:217], v[190:193], v[42:45]
	v_mfma_f32_16x16x32_bf16 v[38:41], v[206:209], v[198:201], v[38:41]
	v_mfma_f32_16x16x32_bf16 v[34:37], v[214:217], v[198:201], v[34:37]
	v_mfma_f32_16x16x32_bf16 v[74:77], v[210:213], v[164:167], v[74:77]
	v_mfma_f32_16x16x32_bf16 v[66:69], v[218:221], v[164:167], v[66:69]
	v_mfma_f32_16x16x32_bf16 v[58:61], v[210:213], v[172:175], v[58:61]
	v_mfma_f32_16x16x32_bf16 v[50:53], v[218:221], v[172:175], v[50:53]
	v_mfma_f32_16x16x32_bf16 v[46:49], v[210:213], v[194:197], v[46:49]
	v_mfma_f32_16x16x32_bf16 v[42:45], v[218:221], v[194:197], v[42:45]
	v_mfma_f32_16x16x32_bf16 v[38:41], v[210:213], v[202:205], v[38:41]
	v_mfma_f32_16x16x32_bf16 v[34:37], v[218:221], v[202:205], v[34:37]
	s_mov_b32 m0, s30
	v_lshl_add_u64 v[176:177], v[222:223], 0, s[86:87]
	s_barrier
	ds_read_b128 v[160:163], v143 offset:49152
	ds_read_b128 v[164:167], v143 offset:50176
	ds_read_b128 v[168:171], v143 offset:51200
	ds_read_b128 v[172:175], v143 offset:52224
	ds_read_b128 v[190:193], v143 offset:53248
	ds_read_b128 v[194:197], v143 offset:54272
	ds_read_b128 v[198:201], v143 offset:55296
	ds_read_b128 v[202:205], v143 offset:56320
	global_load_lds_dwordx4 v[176:177], off
	s_mov_b32 m0, s31
	v_lshl_add_u64 v[176:177], v[224:225], 0, s[86:87]
	global_load_lds_dwordx4 v[176:177], off
	s_barrier
	s_waitcnt lgkmcnt(0)
	v_mfma_f32_16x16x32_bf16 v[94:97], v[144:147], v[160:163], v[94:97]
	v_mfma_f32_16x16x32_bf16 v[90:93], v[152:155], v[160:163], v[90:93]
	v_mfma_f32_16x16x32_bf16 v[86:89], v[144:147], v[168:171], v[86:89]
	v_mfma_f32_16x16x32_bf16 v[82:85], v[152:155], v[168:171], v[82:85]
	v_mfma_f32_16x16x32_bf16 v[78:81], v[144:147], v[190:193], v[78:81]
	v_mfma_f32_16x16x32_bf16 v[70:73], v[152:155], v[190:193], v[70:73]
	v_mfma_f32_16x16x32_bf16 v[62:65], v[144:147], v[198:201], v[62:65]
	v_mfma_f32_16x16x32_bf16 v[54:57], v[152:155], v[198:201], v[54:57]
	v_mfma_f32_16x16x32_bf16 v[94:97], v[148:151], v[164:167], v[94:97]
	v_mfma_f32_16x16x32_bf16 v[90:93], v[156:159], v[164:167], v[90:93]
	v_mfma_f32_16x16x32_bf16 v[86:89], v[148:151], v[172:175], v[86:89]
	v_mfma_f32_16x16x32_bf16 v[82:85], v[156:159], v[172:175], v[82:85]
	v_mfma_f32_16x16x32_bf16 v[78:81], v[148:151], v[194:197], v[78:81]
	v_mfma_f32_16x16x32_bf16 v[70:73], v[156:159], v[194:197], v[70:73]
	v_mfma_f32_16x16x32_bf16 v[62:65], v[148:151], v[202:205], v[62:65]
	v_mfma_f32_16x16x32_bf16 v[54:57], v[156:159], v[202:205], v[54:57]
	s_barrier
	s_add_u32 s12, s16, 0x18080
	s_addc_u32 s13, s17, 0
	s_add_i32 s0, s1, s25
	s_mov_b32 m0, s0
	v_lshl_add_u64 v[144:145], s[12:13], 0, v[4:5]
	global_load_lds_dwordx4 v[144:145], off
	s_add_i32 m0, s0, 0x2000
	v_lshl_add_u64 v[144:145], s[12:13], 0, v[130:131]
	global_load_lds_dwordx4 v[144:145], off
	s_waitcnt vmcnt(6)
	s_barrier
	v_mfma_f32_16x16x32_bf16 v[30:33], v[206:209], v[160:163], v[30:33]
	v_mfma_f32_16x16x32_bf16 v[26:29], v[214:217], v[160:163], v[26:29]
	v_mfma_f32_16x16x32_bf16 v[22:25], v[206:209], v[168:171], v[22:25]
	v_mfma_f32_16x16x32_bf16 v[18:21], v[214:217], v[168:171], v[18:21]
	v_mfma_f32_16x16x32_bf16 v[14:17], v[206:209], v[190:193], v[14:17]
	v_mfma_f32_16x16x32_bf16 v[10:13], v[214:217], v[190:193], v[10:13]
	v_mfma_f32_16x16x32_bf16 v[6:9], v[206:209], v[198:201], v[6:9]
	v_mfma_f32_16x16x32_bf16 v[0:3], v[214:217], v[198:201], v[0:3]
	v_mfma_f32_16x16x32_bf16 v[30:33], v[210:213], v[164:167], v[30:33]
	v_mfma_f32_16x16x32_bf16 v[26:29], v[218:221], v[164:167], v[26:29]
	v_mfma_f32_16x16x32_bf16 v[22:25], v[210:213], v[172:175], v[22:25]
	v_mfma_f32_16x16x32_bf16 v[18:21], v[218:221], v[172:175], v[18:21]
	v_mfma_f32_16x16x32_bf16 v[14:17], v[210:213], v[194:197], v[14:17]
	v_mfma_f32_16x16x32_bf16 v[10:13], v[218:221], v[194:197], v[10:13]
	v_mfma_f32_16x16x32_bf16 v[6:9], v[210:213], v[202:205], v[6:9]
	v_mfma_f32_16x16x32_bf16 v[0:3], v[218:221], v[202:205], v[0:3]
	s_add_i32 s41, s41, 2
	s_add_u32 s39, s39, 0x100
	s_addc_u32 s40, s40, 0
	s_cmp_gt_u32 s41, 3
	s_mov_b64 s[12:13], s[14:15]
	s_barrier
	s_cbranch_scc1 .Lpeel_exit_4

; __device__ __forceinline__ unsigned cvt_pk_bf16(float lo, float hi) { unsigned r; asm volatile("s_nop 0\n\tv_cvt_pk_bf16_f32 %0, %1, %2" : "=v"(r) : "v"(lo), "v"(hi)); return r; }
;     __device__ __forceinline__ void operator()(const f32x4 (&acc)[2][2][4][2], const Unit& u, int wr, int wc, int fr, int fq) const {
;         const int row0 = u.pm * 256 + wr * 64 + fr, col0 = u.pn * 256 + wc * 32 + 8 * fq;
;         f32x4 ra = (f32x4){1.f, 1.f, 1.f, 1.f}, rb = ra;
;         f32x4 swv[4] = {(f32x4){0.f, 0.f, 0.f, 0.f}, (f32x4){0.f, 0.f, 0.f, 0.f}, (f32x4){0.f, 0.f, 0.f, 0.f}, (f32x4){0.f, 0.f, 0.f, 0.f}};
;         if (ss) { load_rstd(ss, row0, ra, rb); const float* swp = sw + (size_t)(u.pm >> 3) * ldc + col0;
;             swv[0] = *(const f32x4*)(swp); swv[1] = *(const f32x4*)(swp + 4); swv[2] = *(const f32x4*)(swp + 128); swv[3] = *(const f32x4*)(swp + 132); }
; #pragma unroll
;         for (int bj = 0; bj < 2; ++bj) {
;             const f32x4 s0 = swv[2 * bj], s1 = swv[2 * bj + 1];
; #pragma unroll
;             for (int ai = 0; ai < 2; ++ai)
; #pragma unroll
;                 for (int m = 0; m < 4; ++m) { const int r = row0 + ai * 128 + m * 16;
;                     const float rstd = ai ? rb[m] : ra[m];
;                     const f32x4 v0 = acc[ai][bj][m][0] * rstd + s0, v1 = acc[ai][bj][m][1] * rstd + s1;
;                     uint4 st; st.x = cvt_pk_bf16(v0[0], v0[1]); st.y = cvt_pk_bf16(v0[2], v0[3]); st.z = cvt_pk_bf16(v1[0], v1[1]); st.w = cvt_pk_bf16(v1[2], v1[3]);
;                     *(uint4*)(O + (size_t)r * ldc + col0 + bj * 128) = st; }
.Lpeel_exit_4:
	v_lshl_or_b32 v144, s37, 8, v142
	v_pk_add_f32 v[126:127], v[126:127], 0 op_sel_hi:[1,0]
	v_lshl_add_u32 v148, s38, 8, v140
	v_ashrrev_i32_e32 v145, 31, v144
	v_pk_add_f32 v[128:129], v[128:129], 0 op_sel_hi:[1,0]
	v_pk_add_f32 v[146:147], v[124:125], 0 op_sel_hi:[1,0]
	v_pk_add_f32 v[124:125], v[122:123], 0 op_sel_hi:[1,0]
	s_nop 0
	v_cvt_pk_bf16_f32 v122, v126, v127
	v_mov_b64_e32 v[126:127], s[10:11]
	s_nop 0
	v_cvt_pk_bf16_f32 v123, v128, v129
	v_mad_i64_i32 v[128:129], s[12:13], v148, s83, v[126:127]
	v_lshlrev_b64 v[144:145], 1, v[144:145]
	s_nop 0
	v_cvt_pk_bf16_f32 v124, v124, v125
	v_lshl_add_u64 v[128:129], v[128:129], 0, v[144:145]
	s_nop 0
	v_cvt_pk_bf16_f32 v125, v146, v147
	global_store_dwordx4 v[128:129], v[122:125], off
	v_pk_add_f32 v[118:119], v[118:119], 0 op_sel_hi:[1,0]
	v_pk_add_f32 v[120:121], v[120:121], 0 op_sel_hi:[1,0]
	v_or_b32_e32 v124, 16, v148
	v_pk_add_f32 v[122:123], v[116:117], 0 op_sel_hi:[1,0]
	v_pk_add_f32 v[116:117], v[114:115], 0 op_sel_hi:[1,0]
	s_nop 0
	v_cvt_pk_bf16_f32 v114, v118, v119
	v_mad_i64_i32 v[118:119], s[12:13], v124, s83, v[126:127]
	s_nop 0
	v_cvt_pk_bf16_f32 v115, v120, v121
	s_nop 0
	v_cvt_pk_bf16_f32 v116, v116, v117
	v_lshl_add_u64 v[118:119], v[118:119], 0, v[144:145]
	s_nop 0
	v_cvt_pk_bf16_f32 v117, v122, v123
	global_store_dwordx4 v[118:119], v[114:117], off
	v_pk_add_f32 v[110:111], v[110:111], 0 op_sel_hi:[1,0]
	v_pk_add_f32 v[112:113], v[112:113], 0 op_sel_hi:[1,0]
	v_or_b32_e32 v116, 32, v148
	v_pk_add_f32 v[114:115], v[108:109], 0 op_sel_hi:[1,0]
	v_pk_add_f32 v[108:109], v[106:107], 0 op_sel_hi:[1,0]
	s_nop 0
	v_cvt_pk_bf16_f32 v106, v110, v111
	v_mad_i64_i32 v[110:111], s[12:13], v116, s83, v[126:127]
	s_nop 0
	v_cvt_pk_bf16_f32 v107, v112, v113
	s_nop 0
	v_cvt_pk_bf16_f32 v108, v108, v109
	v_lshl_add_u64 v[110:111], v[110:111], 0, v[144:145]
	s_nop 0
	v_cvt_pk_bf16_f32 v109, v114, v115
	global_store_dwordx4 v[110:111], v[106:109], off
	v_pk_add_f32 v[102:103], v[102:103], 0 op_sel_hi:[1,0]
	v_pk_add_f32 v[104:105], v[104:105], 0 op_sel_hi:[1,0]
	v_or_b32_e32 v108, 48, v148
	v_pk_add_f32 v[106:107], v[100:101], 0 op_sel_hi:[1,0]
	v_pk_add_f32 v[100:101], v[98:99], 0 op_sel_hi:[1,0]
	s_nop 0
	v_cvt_pk_bf16_f32 v98, v102, v103
	v_mad_i64_i32 v[102:103], s[12:13], v108, s83, v[126:127]
	s_nop 0
	v_cvt_pk_bf16_f32 v99, v104, v105
	s_nop 0
	v_cvt_pk_bf16_f32 v100, v100, v101
	v_lshl_add_u64 v[102:103], v[102:103], 0, v[144:145]
	s_nop 0
	v_cvt_pk_bf16_f32 v101, v106, v107
	global_store_dwordx4 v[102:103], v[98:101], off
	v_pk_add_f32 v[94:95], v[94:95], 0 op_sel_hi:[1,0]
	v_pk_add_f32 v[96:97], v[96:97], 0 op_sel_hi:[1,0]
	v_add_u32_e32 v100, 0x80, v148
	v_pk_add_f32 v[98:99], v[92:93], 0 op_sel_hi:[1,0]
	v_pk_add_f32 v[92:93], v[90:91], 0 op_sel_hi:[1,0]
	s_nop 0
	v_cvt_pk_bf16_f32 v90, v94, v95
	v_mad_i64_i32 v[94:95], s[12:13], v100, s83, v[126:127]
	s_nop 0
	v_cvt_pk_bf16_f32 v91, v96, v97
	s_nop 0
	v_cvt_pk_bf16_f32 v92, v92, v93
	v_lshl_add_u64 v[94:95], v[94:95], 0, v[144:145]
	s_nop 0
	v_cvt_pk_bf16_f32 v93, v98, v99
	global_store_dwordx4 v[94:95], v[90:93], off
	v_pk_add_f32 v[86:87], v[86:87], 0 op_sel_hi:[1,0]
	v_pk_add_f32 v[88:89], v[88:89], 0 op_sel_hi:[1,0]
	v_add_u32_e32 v92, 0x90, v148
	v_pk_add_f32 v[90:91], v[84:85], 0 op_sel_hi:[1,0]
	v_pk_add_f32 v[84:85], v[82:83], 0 op_sel_hi:[1,0]
	s_nop 0
	v_cvt_pk_bf16_f32 v82, v86, v87
	v_mad_i64_i32 v[86:87], s[12:13], v92, s83, v[126:127]
	s_nop 0
	v_cvt_pk_bf16_f32 v83, v88, v89
	s_nop 0
	v_cvt_pk_bf16_f32 v84, v84, v85
	v_lshl_add_u64 v[86:87], v[86:87], 0, v[144:145]
	s_nop 0
	v_cvt_pk_bf16_f32 v85, v90, v91
	global_store_dwordx4 v[86:87], v[82:85], off
	v_pk_add_f32 v[78:79], v[78:79], 0 op_sel_hi:[1,0]
	v_pk_add_f32 v[80:81], v[80:81], 0 op_sel_hi:[1,0]
	v_add_u32_e32 v84, 0xa0, v148
	v_pk_add_f32 v[82:83], v[72:73], 0 op_sel_hi:[1,0]
	v_pk_add_f32 v[72:73], v[70:71], 0 op_sel_hi:[1,0]
	s_nop 0
	v_cvt_pk_bf16_f32 v70, v78, v79
	v_mad_i64_i32 v[78:79], s[12:13], v84, s83, v[126:127]
	s_nop 0
	v_cvt_pk_bf16_f32 v71, v80, v81
	s_nop 0
	v_cvt_pk_bf16_f32 v72, v72, v73
	v_lshl_add_u64 v[78:79], v[78:79], 0, v[144:145]
	s_nop 0
	v_cvt_pk_bf16_f32 v73, v82, v83
	global_store_dwordx4 v[78:79], v[70:73], off
; __device__ __forceinline__ unsigned cvt_pk_bf16(float lo, float hi) { unsigned r; asm volatile("s_nop 0\n\tv_cvt_pk_bf16_f32 %0, %1, %2" : "=v"(r) : "v"(lo), "v"(hi)); return r; }
; #define PG8_WAIT_V(n) asm volatile("s_waitcnt vmcnt(" #n ")" ::: "memory")
; #define PG8_BAR __builtin_amdgcn_s_barrier()
; template <class Epi>
; __device__ __forceinline__ void gemm_phase(LAS unsigned char* lds, const Gemm g, const StaticOrder& S, const Epi& E) {
;     ...
;         E(acc, cur, wr, wc, fr, fq);
;         if (!has_next) break;
; #pragma unroll
;         for (int a = 0; a < 2; ++a)
; #pragma unroll
;             for (int b = 0; b < 2; ++b)
; #pragma unroll
;                 for (int m = 0; m < 4; ++m)
; #pragma unroll
;                     for (int n = 0; n < 2; ++n) acc[a][b][m][n] = (f32x4){0.f, 0.f, 0.f, 0.f};
;         cur = nxt; cA = nA; cB = nB; ++ui;
;     }
;     PG8_WAIT_V(0);
;     if (wr == 0) PG8_BAR;
;     __device__ __forceinline__ void operator()(const f32x4 (&acc)[2][2][4][2], const Unit& u, int wr, int wc, int fr, int fq) const {
;     ...
;         for (int bj = 0; bj < 2; ++bj) {
;             const f32x4 s0 = swv[2 * bj], s1 = swv[2 * bj + 1];
; #pragma unroll
;             for (int ai = 0; ai < 2; ++ai)
; #pragma unroll
;                 for (int m = 0; m < 4; ++m) { const int r = row0 + ai * 128 + m * 16;
;                     const float rstd = ai ? rb[m] : ra[m];
;                     const f32x4 v0 = acc[ai][bj][m][0] * rstd + s0, v1 = acc[ai][bj][m][1] * rstd + s1;
;                     uint4 st; st.x = cvt_pk_bf16(v0[0], v0[1]); st.y = cvt_pk_bf16(v0[2], v0[3]); st.z = cvt_pk_bf16(v1[0], v1[1]); st.w = cvt_pk_bf16(v1[2], v1[3]);
;                     *(uint4*)(O + (size_t)r * ldc + col0 + bj * 128) = st; }
	v_pk_add_f32 v[62:63], v[62:63], 0 op_sel_hi:[1,0]
	v_pk_add_f32 v[64:65], v[64:65], 0 op_sel_hi:[1,0]
	v_add_u32_e32 v72, 0xb0, v148
	v_pk_add_f32 v[70:71], v[56:57], 0 op_sel_hi:[1,0]
	v_pk_add_f32 v[56:57], v[54:55], 0 op_sel_hi:[1,0]
	s_nop 0
	v_cvt_pk_bf16_f32 v54, v62, v63
	v_mad_i64_i32 v[62:63], s[12:13], v72, s83, v[126:127]
	s_nop 0
	v_cvt_pk_bf16_f32 v55, v64, v65
	s_nop 0
	v_cvt_pk_bf16_f32 v56, v56, v57
	s_nop 0
	v_cvt_pk_bf16_f32 v57, v70, v71
	v_lshl_add_u64 v[62:63], v[62:63], 0, v[144:145]
	global_store_dwordx4 v[62:63], v[54:57], off
	v_pk_add_f32 v[64:65], v[68:69], 0 op_sel_hi:[1,0]
	v_pk_add_f32 v[66:67], v[66:67], 0 op_sel_hi:[1,0]
	v_pk_add_f32 v[56:57], v[76:77], 0 op_sel_hi:[1,0]
	v_pk_add_f32 v[54:55], v[74:75], 0 op_sel_hi:[1,0]
	v_pk_add_f32 v[48:49], v[48:49], 0 op_sel_hi:[1,0]
	s_nop 0
	v_cvt_pk_bf16_f32 v54, v54, v55
	s_nop 0
	v_cvt_pk_bf16_f32 v55, v56, v57
	s_nop 0
	v_cvt_pk_bf16_f32 v56, v66, v67
	s_nop 0
	v_cvt_pk_bf16_f32 v57, v64, v65
	global_store_dwordx4 v[128:129], v[54:57], off offset:256
	v_pk_add_f32 v[46:47], v[46:47], 0 op_sel_hi:[1,0]
	v_pk_add_f32 v[40:41], v[40:41], 0 op_sel_hi:[1,0]
	v_pk_add_f32 v[54:55], v[60:61], 0 op_sel_hi:[1,0]
	v_pk_add_f32 v[56:57], v[58:59], 0 op_sel_hi:[1,0]
	v_pk_add_f32 v[58:59], v[52:53], 0 op_sel_hi:[1,0]
	v_pk_add_f32 v[52:53], v[50:51], 0 op_sel_hi:[1,0]
	s_nop 0
	v_cvt_pk_bf16_f32 v50, v56, v57
	s_nop 0
	v_cvt_pk_bf16_f32 v51, v54, v55
	v_pk_add_f32 v[38:39], v[38:39], 0 op_sel_hi:[1,0]
	s_nop 0
	v_cvt_pk_bf16_f32 v52, v52, v53
	s_nop 0
	v_cvt_pk_bf16_f32 v53, v58, v59
	global_store_dwordx4 v[118:119], v[50:53], off offset:256
	v_pk_add_f32 v[32:33], v[32:33], 0 op_sel_hi:[1,0]
	v_pk_add_f32 v[30:31], v[30:31], 0 op_sel_hi:[1,0]
	v_pk_add_f32 v[50:51], v[44:45], 0 op_sel_hi:[1,0]
	v_pk_add_f32 v[44:45], v[42:43], 0 op_sel_hi:[1,0]
	s_nop 0
	v_cvt_pk_bf16_f32 v42, v46, v47
	s_nop 0
	v_cvt_pk_bf16_f32 v43, v48, v49
	v_pk_add_f32 v[24:25], v[24:25], 0 op_sel_hi:[1,0]
	s_nop 0
	v_cvt_pk_bf16_f32 v44, v44, v45
	s_nop 0
	v_cvt_pk_bf16_f32 v45, v50, v51
	global_store_dwordx4 v[110:111], v[42:45], off offset:256
	v_pk_add_f32 v[22:23], v[22:23], 0 op_sel_hi:[1,0]
	v_pk_add_f32 v[16:17], v[16:17], 0 op_sel_hi:[1,0]
	v_pk_add_f32 v[42:43], v[36:37], 0 op_sel_hi:[1,0]
	v_pk_add_f32 v[36:37], v[34:35], 0 op_sel_hi:[1,0]
	s_nop 0
	v_cvt_pk_bf16_f32 v34, v38, v39
	s_nop 0
	v_cvt_pk_bf16_f32 v35, v40, v41
	v_pk_add_f32 v[14:15], v[14:15], 0 op_sel_hi:[1,0]
	s_nop 0
	v_cvt_pk_bf16_f32 v36, v36, v37
	s_nop 0
	v_cvt_pk_bf16_f32 v37, v42, v43
	global_store_dwordx4 v[102:103], v[34:37], off offset:256
	s_and_b64 vcc, exec, s[4:5]
	s_mov_b32 s37, s35
	v_pk_add_f32 v[34:35], v[28:29], 0 op_sel_hi:[1,0]
	v_pk_add_f32 v[28:29], v[26:27], 0 op_sel_hi:[1,0]
	s_nop 0
	v_cvt_pk_bf16_f32 v26, v30, v31
	s_nop 0
	v_cvt_pk_bf16_f32 v27, v32, v33
	s_mov_b32 s38, s36
	s_nop 0
	v_cvt_pk_bf16_f32 v28, v28, v29
	s_nop 0
	v_cvt_pk_bf16_f32 v29, v34, v35
	global_store_dwordx4 v[94:95], v[26:29], off offset:256
	s_mov_b64 s[14:15], s[8:9]
	s_mov_b64 s[12:13], s[6:7]
	v_pk_add_f32 v[26:27], v[20:21], 0 op_sel_hi:[1,0]
	v_pk_add_f32 v[20:21], v[18:19], 0 op_sel_hi:[1,0]
	s_nop 0
	v_cvt_pk_bf16_f32 v18, v22, v23
	s_nop 0
	v_cvt_pk_bf16_f32 v19, v24, v25
	v_pk_add_f32 v[8:9], v[8:9], 0 op_sel_hi:[1,0]
	s_nop 0
	v_cvt_pk_bf16_f32 v20, v20, v21
	s_nop 0
	v_cvt_pk_bf16_f32 v21, v26, v27
	global_store_dwordx4 v[86:87], v[18:21], off offset:256
	v_pk_add_f32 v[6:7], v[6:7], 0 op_sel_hi:[1,0]
	s_nop 0
	v_pk_add_f32 v[18:19], v[12:13], 0 op_sel_hi:[1,0]
	v_pk_add_f32 v[12:13], v[10:11], 0 op_sel_hi:[1,0]
	s_nop 0
	v_cvt_pk_bf16_f32 v10, v14, v15
	s_nop 0
	v_cvt_pk_bf16_f32 v11, v16, v17
	s_nop 0
	s_nop 0
	v_cvt_pk_bf16_f32 v12, v12, v13
	s_nop 0
	v_cvt_pk_bf16_f32 v13, v18, v19
	global_store_dwordx4 v[78:79], v[10:13], off offset:256
	s_nop 1
	v_pk_add_f32 v[10:11], v[2:3], 0 op_sel_hi:[1,0]
	v_pk_add_f32 v[2:3], v[0:1], 0 op_sel_hi:[1,0]
	s_nop 0
	v_cvt_pk_bf16_f32 v0, v6, v7
	s_nop 0
	v_cvt_pk_bf16_f32 v1, v8, v9
	s_nop 0
	s_nop 0
	v_cvt_pk_bf16_f32 v2, v2, v3
	s_nop 0
	v_cvt_pk_bf16_f32 v3, v10, v11
	global_store_dwordx4 v[62:63], v[0:3], off offset:256
	s_cbranch_vccz .LBB0_2396
	s_waitcnt vmcnt(0)
	s_cmpk_gt_u32 s20, 0xff
	s_cbranch_scc1 .LBB0_2407
	s_barrier

; #define PG8_STAGE(bufoff, gbase, voff) do { _Pragma("unroll") for (int _i = 0; _i < 2; ++_i) \
;         __builtin_amdgcn_global_load_lds((const unsigned*)((const char*)(gbase) + (voff)[_i]), (LAS unsigned*)(lds + (bufoff) + ldsw + _i * 8192), 16, 0, 0); } while (0)
; #define PG8_LDA(dst, b, h) do { _Pragma("unroll") for (int m = 0; m < 4; ++m) _Pragma("unroll") for (int k = 0; k < 2; ++k) dst[m][k] = *(const LAS bf16x8*)(lds + PG8_SA(b, h) + aoff + m * 2048 + k * 1024); } while (0)
; #define PG8_LDB(dst, b, h) do { _Pragma("unroll") for (int n = 0; n < 2; ++n) _Pragma("unroll") for (int k = 0; k < 2; ++k) dst[n][k] = *(const LAS bf16x8*)(lds + PG8_SB(b, h) + boff + n * 2048 + k * 1024); } while (0)
; #define PG8_WAIT_L(n) asm volatile("s_waitcnt lgkmcnt(" #n ")" ::: "memory")
; #define PG8_BAR __builtin_amdgcn_s_barrier()
; #define PG8_SCHED __builtin_amdgcn_sched_barrier(0)
; template <class Epi>
; __device__ __forceinline__ void gemm_phase(LAS unsigned char* lds, const Gemm g, const StaticOrder& S, const Epi& E) {
;     ...
;         const bool has_next = S.next(ui + 1, nxt);
;         const char* nA = has_next ? (const char*)g.A + (size_t)nxt.pm * tstep : cA; const char* nB = has_next ? (const char*)g.Bt + (size_t)nxt.pn * tstep : cB;
;         for (int t = 0; t < nt; t += 2) {
;             const bool last = (t == nt - 2);
;             const char* a1 = cA + (size_t)(t + 1) * kstep;
;             const char* a2 = last ? nA : cA + (size_t)(t + 2) * kstep; const char* b2 = last ? nB : cB + (size_t)(t + 2) * kstep;
;             const char* a3 = a2 + kstep; const char* b3 = b2 + kstep;
;             PG8_LDB(B0, 0, 0); PG8_SCHED; PG8_LDA(At, 0, 0); PG8_STAGE(PG8_SA(1, 1), a1 + hstep, voffA);
;             PG8_WAIT_L(8); PG8_BAR; PG8_WAIT_L(0); PG8_MMA(0, 0, At, B0); PG8_BAR; PG8_SCHED;
;             PG8_LDB(B1, 0, 1); PG8_STAGE(PG8_SB(0, 0), b2, voffB);
;             PG8_BAR; PG8_WAIT_L(0); PG8_MMA(0, 1, At, B1); PG8_BAR;
;             PG8_LDA(At, 0, 1); PG8_STAGE(PG8_SA(0, 0), a2, voffA);
;             PG8_BAR; PG8_WAIT_L(0); PG8_MMA(1, 0, At, B0); PG8_BAR; PG8_SCHED;
;     ...
; #pragma unroll
;         for (int a = 0; a < 2; ++a)
; #pragma unroll
;             for (int b = 0; b < 2; ++b)
; #pragma unroll
;                 for (int m = 0; m < 4; ++m)
; #pragma unroll
;                     for (int n = 0; n < 2; ++n) acc[a][b][m][n] = (f32x4){0.f, 0.f, 0.f, 0.f};
.LBB0_2731:
	s_ashr_i32 s11, s10, 31
	s_lshl_b64 s[0:1], s[10:11], 18
	v_cmp_lt_i64_e32 vcc, s[12:13], v[184:185]
	s_add_u32 s12, s23, s0
	s_addc_u32 s13, s24, s1
	s_and_b64 s[0:1], vcc, exec
	s_cselect_b32 s11, s13, s17
	s_cselect_b32 s39, s12, s16
	s_ashr_i32 s9, s8, 31
	s_lshl_b64 s[0:1], s[8:9], 18
	s_add_u32 s14, s25, s0
	s_addc_u32 s15, s26, s1
	s_and_b64 s[0:1], vcc, exec
	s_cselect_b32 s9, s15, s19
	s_cselect_b32 s40, s14, s18
	s_add_u32 s16, s16, 0x20080
	s_addc_u32 s17, s17, 0
	s_add_u32 s41, s18, 0x100
	s_addc_u32 s42, s19, 0
	s_mov_b32 s43, -2
	s_add_u32 s0, s16, 0xfffe0080
	s_addc_u32 s1, s17, -1
	s_add_i32 s48, 0, 0x10000
	v_add_u32_e32 v156, s48, v141
	ds_read_b128 v[144:147], v156
	ds_read_b128 v[148:151], v156 offset:1024
	ds_read_b128 v[152:155], v156 offset:2048
	ds_read_b128 v[156:159], v156 offset:3072
	s_cmp_eq_u32 s43, 4
	s_cselect_b32 s21, s11, s1
	s_cselect_b32 s20, s39, s0
	s_cselect_b32 s19, s9, s42
	s_cselect_b32 s18, s40, s41
	v_lshl_add_u64 v[176:177], s[16:17], 0, v[136:137]
	s_add_i32 m0, s28, 0xc000
	ds_read_b128 v[160:163], v143
	ds_read_b128 v[164:167], v143 offset:1024
	ds_read_b128 v[168:171], v143 offset:2048
	ds_read_b128 v[172:175], v143 offset:3072
	ds_read_b128 v[190:193], v143 offset:4096
	ds_read_b128 v[194:197], v143 offset:5120
	ds_read_b128 v[198:201], v143 offset:6144
	ds_read_b128 v[202:205], v143 offset:7168
	global_load_lds_dwordx4 v[176:177], off
	s_add_i32 m0, s28, 0xe000
	v_lshl_add_u64 v[176:177], s[16:17], 0, v[138:139]
	global_load_lds_dwordx4 v[176:177], off
	s_waitcnt lgkmcnt(8)
	s_barrier
	s_waitcnt lgkmcnt(0)
	v_mfma_f32_16x16x32_bf16 v[126:129], v[144:147], v[160:163], 0
	v_mfma_f32_16x16x32_bf16 v[122:125], v[152:155], v[160:163], 0
	v_mfma_f32_16x16x32_bf16 v[118:121], v[144:147], v[168:171], 0
	v_mfma_f32_16x16x32_bf16 v[114:117], v[152:155], v[168:171], 0
	v_mfma_f32_16x16x32_bf16 v[110:113], v[144:147], v[190:193], 0
	v_mfma_f32_16x16x32_bf16 v[106:109], v[152:155], v[190:193], 0
	v_mfma_f32_16x16x32_bf16 v[102:105], v[144:147], v[198:201], 0
	v_mfma_f32_16x16x32_bf16 v[98:101], v[152:155], v[198:201], 0
	v_mfma_f32_16x16x32_bf16 v[126:129], v[148:151], v[164:167], v[126:129]
	v_mfma_f32_16x16x32_bf16 v[122:125], v[156:159], v[164:167], v[122:125]
	v_mfma_f32_16x16x32_bf16 v[118:121], v[148:151], v[172:175], v[118:121]
	v_mfma_f32_16x16x32_bf16 v[114:117], v[156:159], v[172:175], v[114:117]
	v_mfma_f32_16x16x32_bf16 v[110:113], v[148:151], v[194:197], v[110:113]
	v_mfma_f32_16x16x32_bf16 v[106:109], v[156:159], v[194:197], v[106:109]
	v_mfma_f32_16x16x32_bf16 v[102:105], v[148:151], v[202:205], v[102:105]
	v_mfma_f32_16x16x32_bf16 v[98:101], v[156:159], v[202:205], v[98:101]
	s_barrier
	s_add_i32 s49, 0, 0x14000
	v_add_u32_e32 v176, s49, v141
	s_add_i32 s0, s48, s27
	ds_read_b128 v[206:209], v176
	ds_read_b128 v[210:213], v176 offset:1024
	ds_read_b128 v[214:217], v176 offset:2048
	ds_read_b128 v[218:221], v176 offset:3072
	v_lshl_add_u64 v[176:177], s[18:19], 0, v[4:5]
	s_mov_b32 m0, s0
	v_lshl_add_u64 v[186:187], s[18:19], 0, v[130:131]
	global_load_lds_dwordx4 v[176:177], off
	s_add_i32 m0, s0, 0x2000
	s_nop 0
	global_load_lds_dwordx4 v[186:187], off
	s_barrier
	s_waitcnt lgkmcnt(0)
	v_mfma_f32_16x16x32_bf16 v[70:73], v[206:209], v[160:163], 0
	v_mfma_f32_16x16x32_bf16 v[66:69], v[214:217], v[160:163], 0
	v_mfma_f32_16x16x32_bf16 v[54:57], v[206:209], v[168:171], 0
	v_mfma_f32_16x16x32_bf16 v[50:53], v[214:217], v[168:171], 0
	v_mfma_f32_16x16x32_bf16 v[46:49], v[206:209], v[190:193], 0
	v_mfma_f32_16x16x32_bf16 v[42:45], v[214:217], v[190:193], 0
	v_mfma_f32_16x16x32_bf16 v[38:41], v[206:209], v[198:201], 0
	v_mfma_f32_16x16x32_bf16 v[34:37], v[214:217], v[198:201], 0
	v_mfma_f32_16x16x32_bf16 v[70:73], v[210:213], v[164:167], v[70:73]
	v_mfma_f32_16x16x32_bf16 v[66:69], v[218:221], v[164:167], v[66:69]
	v_mfma_f32_16x16x32_bf16 v[54:57], v[210:213], v[172:175], v[54:57]
	v_mfma_f32_16x16x32_bf16 v[50:53], v[218:221], v[172:175], v[50:53]
	v_mfma_f32_16x16x32_bf16 v[46:49], v[210:213], v[194:197], v[46:49]
	v_mfma_f32_16x16x32_bf16 v[42:45], v[218:221], v[194:197], v[42:45]
	v_mfma_f32_16x16x32_bf16 v[38:41], v[210:213], v[202:205], v[38:41]
	v_mfma_f32_16x16x32_bf16 v[34:37], v[218:221], v[202:205], v[34:37]
	s_mov_b32 m0, s28
	v_lshl_add_u64 v[222:223], s[20:21], 0, v[134:135]
	s_barrier
	ds_read_b128 v[160:163], v143 offset:16384
	ds_read_b128 v[164:167], v143 offset:17408
	ds_read_b128 v[168:171], v143 offset:18432
	ds_read_b128 v[172:175], v143 offset:19456
	ds_read_b128 v[190:193], v143 offset:20480
	ds_read_b128 v[194:197], v143 offset:21504
	ds_read_b128 v[198:201], v143 offset:22528
	ds_read_b128 v[202:205], v143 offset:23552
	global_load_lds_dwordx4 v[222:223], off
	s_mov_b32 m0, s29
	v_lshl_add_u64 v[224:225], s[20:21], 0, v[132:133]
	global_load_lds_dwordx4 v[224:225], off
	s_barrier
	s_waitcnt lgkmcnt(0)
	v_mfma_f32_16x16x32_bf16 v[94:97], v[144:147], v[160:163], 0
	v_mfma_f32_16x16x32_bf16 v[90:93], v[152:155], v[160:163], 0
	v_mfma_f32_16x16x32_bf16 v[86:89], v[144:147], v[168:171], 0
	v_mfma_f32_16x16x32_bf16 v[82:85], v[152:155], v[168:171], 0
	v_mfma_f32_16x16x32_bf16 v[78:81], v[144:147], v[190:193], 0
	v_mfma_f32_16x16x32_bf16 v[74:77], v[152:155], v[190:193], 0
	v_mfma_f32_16x16x32_bf16 v[62:65], v[144:147], v[198:201], 0
	v_mfma_f32_16x16x32_bf16 v[58:61], v[152:155], v[198:201], 0
	v_mfma_f32_16x16x32_bf16 v[94:97], v[148:151], v[164:167], v[94:97]
	v_mfma_f32_16x16x32_bf16 v[90:93], v[156:159], v[164:167], v[90:93]
	v_mfma_f32_16x16x32_bf16 v[86:89], v[148:151], v[172:175], v[86:89]
	v_mfma_f32_16x16x32_bf16 v[82:85], v[156:159], v[172:175], v[82:85]
	v_mfma_f32_16x16x32_bf16 v[78:81], v[148:151], v[194:197], v[78:81]
	v_mfma_f32_16x16x32_bf16 v[74:77], v[156:159], v[194:197], v[74:77]
	v_mfma_f32_16x16x32_bf16 v[62:65], v[148:151], v[202:205], v[62:65]
	v_mfma_f32_16x16x32_bf16 v[58:61], v[156:159], v[202:205], v[58:61]
	s_barrier
; #define PG8_STAGE(bufoff, gbase, voff) do { _Pragma("unroll") for (int _i = 0; _i < 2; ++_i) \
;         __builtin_amdgcn_global_load_lds((const unsigned*)((const char*)(gbase) + (voff)[_i]), (LAS unsigned*)(lds + (bufoff) + ldsw + _i * 8192), 16, 0, 0); } while (0)
; #define PG8_LDA(dst, b, h) do { _Pragma("unroll") for (int m = 0; m < 4; ++m) _Pragma("unroll") for (int k = 0; k < 2; ++k) dst[m][k] = *(const LAS bf16x8*)(lds + PG8_SA(b, h) + aoff + m * 2048 + k * 1024); } while (0)
; #define PG8_LDB(dst, b, h) do { _Pragma("unroll") for (int n = 0; n < 2; ++n) _Pragma("unroll") for (int k = 0; k < 2; ++k) dst[n][k] = *(const LAS bf16x8*)(lds + PG8_SB(b, h) + boff + n * 2048 + k * 1024); } while (0)
; #define PG8_MMA(ai, bj, At, Bt) do { __builtin_amdgcn_s_setprio(1); _Pragma("unroll") for (int m = 0; m < 4; ++m) _Pragma("unroll") for (int n = 0; n < 2; ++n) _Pragma("unroll") for (int k = 0; k < 2; ++k) \
;         acc[ai][bj][m][n] = __builtin_amdgcn_mfma_f32_16x16x32_bf16(Bt[n][k], At[m][k], acc[ai][bj][m][n], 0, 0, 0); __builtin_amdgcn_s_setprio(0); } while (0)
; #define PG8_WAIT_V(n) asm volatile("s_waitcnt vmcnt(" #n ")" ::: "memory")
; #define PG8_WAIT_L(n) asm volatile("s_waitcnt lgkmcnt(" #n ")" ::: "memory")
; #define PG8_BAR __builtin_amdgcn_s_barrier()
; #define PG8_SCHED __builtin_amdgcn_sched_barrier(0)
; template <class Epi>
; __device__ __forceinline__ void gemm_phase(LAS unsigned char* lds, const Gemm g, const StaticOrder& S, const Epi& E) {
;     ...
;             PG8_STAGE(PG8_SB(0, 1), b2 + hstep, voffB);
;             PG8_WAIT_V(6); PG8_BAR; PG8_MMA(1, 1, At, B1); PG8_BAR;
;             PG8_LDB(B0, 1, 0); PG8_SCHED; PG8_LDA(At, 1, 0); PG8_STAGE(PG8_SA(0, 1), a2 + hstep, voffA);
;             PG8_WAIT_L(8); PG8_BAR; PG8_WAIT_L(0); PG8_MMA(0, 0, At, B0); PG8_BAR; PG8_SCHED;
;             PG8_LDB(B1, 1, 1); PG8_STAGE(PG8_SB(1, 0), b3, voffB);
	s_add_u32 s0, s18, 0x20000
	s_addc_u32 s1, s19, 0
	s_add_i32 s48, s49, s27
	s_mov_b32 m0, s48
	v_lshl_add_u64 v[144:145], s[0:1], 0, v[4:5]
	global_load_lds_dwordx4 v[144:145], off
	s_add_i32 m0, s48, 0x2000
	v_lshl_add_u64 v[144:145], s[0:1], 0, v[130:131]
	global_load_lds_dwordx4 v[144:145], off
	s_waitcnt vmcnt(6)
	s_barrier
	v_mfma_f32_16x16x32_bf16 v[30:33], v[206:209], v[160:163], 0
	v_mfma_f32_16x16x32_bf16 v[26:29], v[214:217], v[160:163], 0
	v_mfma_f32_16x16x32_bf16 v[22:25], v[206:209], v[168:171], 0
	v_mfma_f32_16x16x32_bf16 v[18:21], v[214:217], v[168:171], 0
	v_mfma_f32_16x16x32_bf16 v[14:17], v[206:209], v[190:193], 0
	v_mfma_f32_16x16x32_bf16 v[10:13], v[214:217], v[190:193], 0
	v_mfma_f32_16x16x32_bf16 v[6:9], v[206:209], v[198:201], 0
	v_mfma_f32_16x16x32_bf16 v[0:3], v[214:217], v[198:201], 0
	v_mfma_f32_16x16x32_bf16 v[30:33], v[210:213], v[164:167], v[30:33]
	v_mfma_f32_16x16x32_bf16 v[26:29], v[218:221], v[164:167], v[26:29]
	v_mfma_f32_16x16x32_bf16 v[22:25], v[210:213], v[172:175], v[22:25]
	v_mfma_f32_16x16x32_bf16 v[18:21], v[218:221], v[172:175], v[18:21]
	v_mfma_f32_16x16x32_bf16 v[14:17], v[210:213], v[194:197], v[14:17]
	v_mfma_f32_16x16x32_bf16 v[10:13], v[218:221], v[194:197], v[10:13]
	v_mfma_f32_16x16x32_bf16 v[6:9], v[210:213], v[202:205], v[6:9]
	v_mfma_f32_16x16x32_bf16 v[0:3], v[218:221], v[202:205], v[0:3]
	s_add_i32 s48, 0, 0x18000
	v_add_u32_e32 v156, s48, v141
	s_barrier
	ds_read_b128 v[144:147], v156
	ds_read_b128 v[148:151], v156 offset:1024
	ds_read_b128 v[152:155], v156 offset:2048
	ds_read_b128 v[156:159], v156 offset:3072
	s_add_u32 s0, s20, 0x20000
	s_addc_u32 s1, s21, 0
	s_mov_b32 m0, s30
	v_lshl_add_u64 v[206:207], s[0:1], 0, v[134:135]
	ds_read_b128 v[160:163], v143 offset:32768
	ds_read_b128 v[164:167], v143 offset:33792
	ds_read_b128 v[168:171], v143 offset:34816
	ds_read_b128 v[172:175], v143 offset:35840
	ds_read_b128 v[190:193], v143 offset:36864
	ds_read_b128 v[194:197], v143 offset:37888
	ds_read_b128 v[198:201], v143 offset:38912
	ds_read_b128 v[202:205], v143 offset:39936
	global_load_lds_dwordx4 v[206:207], off
	s_mov_b32 m0, s31
	v_lshl_add_u64 v[206:207], s[0:1], 0, v[132:133]
	global_load_lds_dwordx4 v[206:207], off
	s_waitcnt lgkmcnt(8)
	s_barrier
	s_waitcnt lgkmcnt(0)
	v_mfma_f32_16x16x32_bf16 v[126:129], v[144:147], v[160:163], v[126:129]
	v_mfma_f32_16x16x32_bf16 v[122:125], v[152:155], v[160:163], v[122:125]
	v_mfma_f32_16x16x32_bf16 v[118:121], v[144:147], v[168:171], v[118:121]
	v_mfma_f32_16x16x32_bf16 v[114:117], v[152:155], v[168:171], v[114:117]
	v_mfma_f32_16x16x32_bf16 v[110:113], v[144:147], v[190:193], v[110:113]
	v_mfma_f32_16x16x32_bf16 v[106:109], v[152:155], v[190:193], v[106:109]
	v_mfma_f32_16x16x32_bf16 v[102:105], v[144:147], v[198:201], v[102:105]
	v_mfma_f32_16x16x32_bf16 v[98:101], v[152:155], v[198:201], v[98:101]
	v_mfma_f32_16x16x32_bf16 v[126:129], v[148:151], v[164:167], v[126:129]
	v_mfma_f32_16x16x32_bf16 v[122:125], v[156:159], v[164:167], v[122:125]
	v_mfma_f32_16x16x32_bf16 v[118:121], v[148:151], v[172:175], v[118:121]
	v_mfma_f32_16x16x32_bf16 v[114:117], v[156:159], v[172:175], v[114:117]
	v_mfma_f32_16x16x32_bf16 v[110:113], v[148:151], v[194:197], v[110:113]
	v_mfma_f32_16x16x32_bf16 v[106:109], v[156:159], v[194:197], v[106:109]
	v_mfma_f32_16x16x32_bf16 v[102:105], v[148:151], v[202:205], v[102:105]
	v_mfma_f32_16x16x32_bf16 v[98:101], v[156:159], v[202:205], v[98:101]
	s_barrier
	s_add_i32 s20, 0, 0x1c000
	s_add_i32 s0, s48, s27
	v_add_u32_e32 v218, s20, v141
	v_lshl_add_u64 v[176:177], v[176:177], 0, s[86:87]
	s_mov_b32 m0, s0
	ds_read_b128 v[206:209], v218
	ds_read_b128 v[210:213], v218 offset:1024
	ds_read_b128 v[214:217], v218 offset:2048
	ds_read_b128 v[218:221], v218 offset:3072
	global_load_lds_dwordx4 v[176:177], off
	s_add_i32 m0, s0, 0x2000
	v_lshl_add_u64 v[176:177], v[186:187], 0, s[86:87]
	global_load_lds_dwordx4 v[176:177], off
	s_barrier
; #define PG8_STAGE(bufoff, gbase, voff) do { _Pragma("unroll") for (int _i = 0; _i < 2; ++_i) \
;         __builtin_amdgcn_global_load_lds((const unsigned*)((const char*)(gbase) + (voff)[_i]), (LAS unsigned*)(lds + (bufoff) + ldsw + _i * 8192), 16, 0, 0); } while (0)
; #define PG8_LDA(dst, b, h) do { _Pragma("unroll") for (int m = 0; m < 4; ++m) _Pragma("unroll") for (int k = 0; k < 2; ++k) dst[m][k] = *(const LAS bf16x8*)(lds + PG8_SA(b, h) + aoff + m * 2048 + k * 1024); } while (0)
; #define PG8_LDB(dst, b, h) do { _Pragma("unroll") for (int n = 0; n < 2; ++n) _Pragma("unroll") for (int k = 0; k < 2; ++k) dst[n][k] = *(const LAS bf16x8*)(lds + PG8_SB(b, h) + boff + n * 2048 + k * 1024); } while (0)
; #define PG8_MMA(ai, bj, At, Bt) do { __builtin_amdgcn_s_setprio(1); _Pragma("unroll") for (int m = 0; m < 4; ++m) _Pragma("unroll") for (int n = 0; n < 2; ++n) _Pragma("unroll") for (int k = 0; k < 2; ++k) \
;         acc[ai][bj][m][n] = __builtin_amdgcn_mfma_f32_16x16x32_bf16(Bt[n][k], At[m][k], acc[ai][bj][m][n], 0, 0, 0); __builtin_amdgcn_s_setprio(0); } while (0)
; #define PG8_WAIT_V(n) asm volatile("s_waitcnt vmcnt(" #n ")" ::: "memory")
; #define PG8_WAIT_L(n) asm volatile("s_waitcnt lgkmcnt(" #n ")" ::: "memory")
; #define PG8_BAR __builtin_amdgcn_s_barrier()
; #define PG8_SCHED __builtin_amdgcn_sched_barrier(0)
; template <class Epi>
; __device__ __forceinline__ void gemm_phase(LAS unsigned char* lds, const Gemm g, const StaticOrder& S, const Epi& E) {
;     ...
;         for (int t = 0; t < nt; t += 2) {
;     ...
;             PG8_LDB(B1, 1, 1); PG8_STAGE(PG8_SB(1, 0), b3, voffB);
;             PG8_BAR; PG8_WAIT_L(0); PG8_MMA(0, 1, At, B1); PG8_BAR;
;             PG8_LDA(At, 1, 1); PG8_STAGE(PG8_SA(1, 0), a3, voffA);
;             PG8_BAR; PG8_WAIT_L(0); PG8_MMA(1, 0, At, B0); PG8_BAR; PG8_SCHED;
;             PG8_STAGE(PG8_SB(1, 1), b3 + hstep, voffB);
;             PG8_WAIT_V(6); PG8_BAR; PG8_MMA(1, 1, At, B1); PG8_BAR;
	s_waitcnt lgkmcnt(0)
	v_mfma_f32_16x16x32_bf16 v[70:73], v[206:209], v[160:163], v[70:73]
	v_mfma_f32_16x16x32_bf16 v[66:69], v[214:217], v[160:163], v[66:69]
	v_mfma_f32_16x16x32_bf16 v[54:57], v[206:209], v[168:171], v[54:57]
	v_mfma_f32_16x16x32_bf16 v[50:53], v[214:217], v[168:171], v[50:53]
	v_mfma_f32_16x16x32_bf16 v[46:49], v[206:209], v[190:193], v[46:49]
	v_mfma_f32_16x16x32_bf16 v[42:45], v[214:217], v[190:193], v[42:45]
	v_mfma_f32_16x16x32_bf16 v[38:41], v[206:209], v[198:201], v[38:41]
	v_mfma_f32_16x16x32_bf16 v[34:37], v[214:217], v[198:201], v[34:37]
	v_mfma_f32_16x16x32_bf16 v[70:73], v[210:213], v[164:167], v[70:73]
	v_mfma_f32_16x16x32_bf16 v[66:69], v[218:221], v[164:167], v[66:69]
	v_mfma_f32_16x16x32_bf16 v[54:57], v[210:213], v[172:175], v[54:57]
	v_mfma_f32_16x16x32_bf16 v[50:53], v[218:221], v[172:175], v[50:53]
	v_mfma_f32_16x16x32_bf16 v[46:49], v[210:213], v[194:197], v[46:49]
	v_mfma_f32_16x16x32_bf16 v[42:45], v[218:221], v[194:197], v[42:45]
	v_mfma_f32_16x16x32_bf16 v[38:41], v[210:213], v[202:205], v[38:41]
	v_mfma_f32_16x16x32_bf16 v[34:37], v[218:221], v[202:205], v[34:37]
	s_mov_b32 m0, s34
	v_lshl_add_u64 v[176:177], v[222:223], 0, s[86:87]
	s_barrier
	ds_read_b128 v[160:163], v143 offset:49152
	ds_read_b128 v[164:167], v143 offset:50176
	ds_read_b128 v[168:171], v143 offset:51200
	ds_read_b128 v[172:175], v143 offset:52224
	ds_read_b128 v[190:193], v143 offset:53248
	ds_read_b128 v[194:197], v143 offset:54272
	ds_read_b128 v[198:201], v143 offset:55296
	ds_read_b128 v[202:205], v143 offset:56320
	global_load_lds_dwordx4 v[176:177], off
	s_mov_b32 m0, s35
	v_lshl_add_u64 v[176:177], v[224:225], 0, s[86:87]
	global_load_lds_dwordx4 v[176:177], off
	s_barrier
	s_waitcnt lgkmcnt(0)
	v_mfma_f32_16x16x32_bf16 v[94:97], v[144:147], v[160:163], v[94:97]
	v_mfma_f32_16x16x32_bf16 v[90:93], v[152:155], v[160:163], v[90:93]
	v_mfma_f32_16x16x32_bf16 v[86:89], v[144:147], v[168:171], v[86:89]
	v_mfma_f32_16x16x32_bf16 v[82:85], v[152:155], v[168:171], v[82:85]
	v_mfma_f32_16x16x32_bf16 v[78:81], v[144:147], v[190:193], v[78:81]
	v_mfma_f32_16x16x32_bf16 v[74:77], v[152:155], v[190:193], v[74:77]
	v_mfma_f32_16x16x32_bf16 v[62:65], v[144:147], v[198:201], v[62:65]
	v_mfma_f32_16x16x32_bf16 v[58:61], v[152:155], v[198:201], v[58:61]
	v_mfma_f32_16x16x32_bf16 v[94:97], v[148:151], v[164:167], v[94:97]
	v_mfma_f32_16x16x32_bf16 v[90:93], v[156:159], v[164:167], v[90:93]
	v_mfma_f32_16x16x32_bf16 v[86:89], v[148:151], v[172:175], v[86:89]
	v_mfma_f32_16x16x32_bf16 v[82:85], v[156:159], v[172:175], v[82:85]
	v_mfma_f32_16x16x32_bf16 v[78:81], v[148:151], v[194:197], v[78:81]
	v_mfma_f32_16x16x32_bf16 v[74:77], v[156:159], v[194:197], v[74:77]
	v_mfma_f32_16x16x32_bf16 v[62:65], v[148:151], v[202:205], v[62:65]
	v_mfma_f32_16x16x32_bf16 v[58:61], v[156:159], v[202:205], v[58:61]
	s_barrier
	s_add_u32 s0, s18, 0x20080
	s_addc_u32 s1, s19, 0
	s_add_i32 s18, s20, s27
	s_mov_b32 m0, s18
	v_lshl_add_u64 v[144:145], s[0:1], 0, v[4:5]
	global_load_lds_dwordx4 v[144:145], off
	s_add_i32 m0, s18, 0x2000
	v_lshl_add_u64 v[144:145], s[0:1], 0, v[130:131]
	global_load_lds_dwordx4 v[144:145], off
	s_waitcnt vmcnt(6)
	s_barrier
	v_mfma_f32_16x16x32_bf16 v[30:33], v[206:209], v[160:163], v[30:33]
	v_mfma_f32_16x16x32_bf16 v[26:29], v[214:217], v[160:163], v[26:29]
	v_mfma_f32_16x16x32_bf16 v[22:25], v[206:209], v[168:171], v[22:25]
	v_mfma_f32_16x16x32_bf16 v[18:21], v[214:217], v[168:171], v[18:21]
	v_mfma_f32_16x16x32_bf16 v[14:17], v[206:209], v[190:193], v[14:17]
	v_mfma_f32_16x16x32_bf16 v[10:13], v[214:217], v[190:193], v[10:13]
	v_mfma_f32_16x16x32_bf16 v[6:9], v[206:209], v[198:201], v[6:9]
	v_mfma_f32_16x16x32_bf16 v[0:3], v[214:217], v[198:201], v[0:3]
	v_mfma_f32_16x16x32_bf16 v[30:33], v[210:213], v[164:167], v[30:33]
	v_mfma_f32_16x16x32_bf16 v[26:29], v[218:221], v[164:167], v[26:29]
	v_mfma_f32_16x16x32_bf16 v[22:25], v[210:213], v[172:175], v[22:25]
	v_mfma_f32_16x16x32_bf16 v[18:21], v[218:221], v[172:175], v[18:21]
	v_mfma_f32_16x16x32_bf16 v[14:17], v[210:213], v[194:197], v[14:17]
	v_mfma_f32_16x16x32_bf16 v[10:13], v[218:221], v[194:197], v[10:13]
	v_mfma_f32_16x16x32_bf16 v[6:9], v[210:213], v[202:205], v[6:9]
	v_mfma_f32_16x16x32_bf16 v[0:3], v[218:221], v[202:205], v[0:3]
	s_add_i32 s43, s43, 2
	s_add_u32 s16, s16, 0x100
	s_addc_u32 s17, s17, 0
	s_add_u32 s41, s41, 0x100
	s_addc_u32 s42, s42, 0
	s_cmp_gt_u32 s43, 5
	s_barrier
	s_cbranch_scc1 .Lpeel_exit_3

; __device__ __forceinline__ unsigned cvt_pk_bf16(float lo, float hi) { unsigned r; asm volatile("s_nop 0\n\tv_cvt_pk_bf16_f32 %0, %1, %2" : "=v"(r) : "v"(lo), "v"(hi)); return r; }
;     __device__ __forceinline__ void operator()(const f32x4 (&acc)[2][2][4][2], const Unit& u, int wr, int wc, int fr, int fq) const {
;         const int row0 = u.pm * 256 + wr * 64 + fr, col0 = u.pn * 256 + wc * 32 + 8 * fq;
;         f32x4 ra = (f32x4){1.f, 1.f, 1.f, 1.f}, rb = ra;
;         f32x4 swv[4] = {(f32x4){0.f, 0.f, 0.f, 0.f}, (f32x4){0.f, 0.f, 0.f, 0.f}, (f32x4){0.f, 0.f, 0.f, 0.f}, (f32x4){0.f, 0.f, 0.f, 0.f}};
;         if (ss) { load_rstd(ss, row0, ra, rb); const float* swp = sw + (size_t)(u.pm >> 3) * ldc + col0;
;             swv[0] = *(const f32x4*)(swp); swv[1] = *(const f32x4*)(swp + 4); swv[2] = *(const f32x4*)(swp + 128); swv[3] = *(const f32x4*)(swp + 132); }
; #pragma unroll
;         for (int bj = 0; bj < 2; ++bj) {
;             const f32x4 s0 = swv[2 * bj], s1 = swv[2 * bj + 1];
; #pragma unroll
;             for (int ai = 0; ai < 2; ++ai)
; #pragma unroll
;                 for (int m = 0; m < 4; ++m) { const int r = row0 + ai * 128 + m * 16;
;                     const float rstd = ai ? rb[m] : ra[m];
;                     const f32x4 v0 = acc[ai][bj][m][0] * rstd + s0, v1 = acc[ai][bj][m][1] * rstd + s1;
;                     uint4 st; st.x = cvt_pk_bf16(v0[0], v0[1]); st.y = cvt_pk_bf16(v0[2], v0[3]); st.z = cvt_pk_bf16(v1[0], v1[1]); st.w = cvt_pk_bf16(v1[2], v1[3]);
;                     *(uint4*)(O + (size_t)r * ldc + col0 + bj * 128) = st; }
.Lpeel_exit_3:
	v_lshl_add_u32 v144, s38, 8, v140
	v_lshl_or_b32 v146, s37, 8, v142
	v_ashrrev_i32_e32 v145, 31, v144
	v_pk_add_f32 v[126:127], v[126:127], 0 op_sel_hi:[1,0]
	v_ashrrev_i32_e32 v147, 31, v146
	v_pk_add_f32 v[128:129], v[128:129], 0 op_sel_hi:[1,0]
	v_pk_add_f32 v[148:149], v[124:125], 0 op_sel_hi:[1,0]
	v_pk_add_f32 v[124:125], v[122:123], 0 op_sel_hi:[1,0]
	s_nop 0
	v_cvt_pk_bf16_f32 v122, v126, v127
	v_lshlrev_b64 v[126:127], 11, v[144:145]
	s_nop 0
	v_cvt_pk_bf16_f32 v123, v128, v129
	v_lshl_add_u64 v[126:127], s[6:7], 0, v[126:127]
	v_lshlrev_b64 v[128:129], 1, v[146:147]
	v_lshl_add_u64 v[126:127], v[126:127], 0, v[128:129]
	s_nop 0
	v_cvt_pk_bf16_f32 v124, v124, v125
	s_nop 0
	v_cvt_pk_bf16_f32 v125, v148, v149
	global_store_dwordx4 v[126:127], v[122:125], off
	v_pk_add_f32 v[118:119], v[118:119], 0 op_sel_hi:[1,0]
	v_pk_add_f32 v[120:121], v[120:121], 0 op_sel_hi:[1,0]
	v_or_b32_e32 v122, 16, v144
	v_ashrrev_i32_e32 v123, 31, v122
	v_pk_add_f32 v[124:125], v[116:117], 0 op_sel_hi:[1,0]
	v_pk_add_f32 v[116:117], v[114:115], 0 op_sel_hi:[1,0]
	s_nop 0
	v_cvt_pk_bf16_f32 v114, v118, v119
	v_lshlrev_b64 v[118:119], 11, v[122:123]
	v_lshl_add_u64 v[118:119], s[6:7], 0, v[118:119]
	v_lshl_add_u64 v[118:119], v[118:119], 0, v[128:129]
	s_nop 0
	v_cvt_pk_bf16_f32 v115, v120, v121
	s_nop 0
	v_cvt_pk_bf16_f32 v116, v116, v117
	s_nop 0
	v_cvt_pk_bf16_f32 v117, v124, v125
	global_store_dwordx4 v[118:119], v[114:117], off
	v_pk_add_f32 v[110:111], v[110:111], 0 op_sel_hi:[1,0]
	v_pk_add_f32 v[112:113], v[112:113], 0 op_sel_hi:[1,0]
	v_or_b32_e32 v114, 32, v144
	v_ashrrev_i32_e32 v115, 31, v114
	v_pk_add_f32 v[116:117], v[108:109], 0 op_sel_hi:[1,0]
	v_pk_add_f32 v[108:109], v[106:107], 0 op_sel_hi:[1,0]
	s_nop 0
	v_cvt_pk_bf16_f32 v106, v110, v111
	v_lshlrev_b64 v[110:111], 11, v[114:115]
	v_lshl_add_u64 v[110:111], s[6:7], 0, v[110:111]
	v_lshl_add_u64 v[110:111], v[110:111], 0, v[128:129]
	s_nop 0
	v_cvt_pk_bf16_f32 v107, v112, v113
	s_nop 0
	v_cvt_pk_bf16_f32 v108, v108, v109
	s_nop 0
	v_cvt_pk_bf16_f32 v109, v116, v117
	global_store_dwordx4 v[110:111], v[106:109], off
	v_pk_add_f32 v[102:103], v[102:103], 0 op_sel_hi:[1,0]
	v_pk_add_f32 v[104:105], v[104:105], 0 op_sel_hi:[1,0]
	v_or_b32_e32 v106, 48, v144
	v_ashrrev_i32_e32 v107, 31, v106
	v_pk_add_f32 v[108:109], v[100:101], 0 op_sel_hi:[1,0]
	v_pk_add_f32 v[100:101], v[98:99], 0 op_sel_hi:[1,0]
	s_nop 0
	v_cvt_pk_bf16_f32 v98, v102, v103
	v_lshlrev_b64 v[102:103], 11, v[106:107]
	v_lshl_add_u64 v[102:103], s[6:7], 0, v[102:103]
	s_nop 0
	v_cvt_pk_bf16_f32 v99, v104, v105
	v_lshl_add_u64 v[102:103], v[102:103], 0, v[128:129]
	v_pk_add_f32 v[96:97], v[96:97], 0 op_sel_hi:[1,0]
	s_nop 0
	v_cvt_pk_bf16_f32 v100, v100, v101
	s_nop 0
	v_cvt_pk_bf16_f32 v101, v108, v109
	global_store_dwordx4 v[102:103], v[98:101], off
	v_pk_add_f32 v[94:95], v[94:95], 0 op_sel_hi:[1,0]
	s_mov_b64 s[0:1], 0x40000
	v_pk_add_f32 v[98:99], v[92:93], 0 op_sel_hi:[1,0]
	v_pk_add_f32 v[92:93], v[90:91], 0 op_sel_hi:[1,0]
	s_nop 0
	v_cvt_pk_bf16_f32 v90, v94, v95
	s_nop 0
	v_cvt_pk_bf16_f32 v91, v96, v97
	v_add_co_u32_e32 v96, vcc, s85, v126
	v_lshl_add_u64 v[94:95], v[126:127], 0, s[0:1]
	s_nop 0
	v_addc_co_u32_e32 v97, vcc, 0, v127, vcc
	v_pk_add_f32 v[86:87], v[86:87], 0 op_sel_hi:[1,0]
	s_mov_b64 s[0:1], 0x48000
	s_nop 0
	v_cvt_pk_bf16_f32 v92, v92, v93
	s_nop 0
	v_cvt_pk_bf16_f32 v93, v98, v99
	global_store_dwordx4 v[96:97], v[90:93], off
	v_pk_add_f32 v[88:89], v[88:89], 0 op_sel_hi:[1,0]
	v_pk_add_f32 v[78:79], v[78:79], 0 op_sel_hi:[1,0]
	v_pk_add_f32 v[90:91], v[84:85], 0 op_sel_hi:[1,0]
	v_pk_add_f32 v[84:85], v[82:83], 0 op_sel_hi:[1,0]
	s_nop 0
	v_cvt_pk_bf16_f32 v82, v86, v87
	v_lshl_add_u64 v[86:87], v[126:127], 0, s[0:1]
	s_mov_b32 s0, 0x48000
	s_nop 0
	v_cvt_pk_bf16_f32 v83, v88, v89
	v_add_co_u32_e32 v88, vcc, s0, v126
	s_mov_b64 s[0:1], 0x50000
	s_nop 0
	v_addc_co_u32_e32 v89, vcc, 0, v127, vcc
	s_nop 0
	v_cvt_pk_bf16_f32 v84, v84, v85
	s_nop 0
	v_cvt_pk_bf16_f32 v85, v90, v91
	global_store_dwordx4 v[88:89], v[82:85], off
	v_pk_add_f32 v[80:81], v[80:81], 0 op_sel_hi:[1,0]
	v_pk_add_f32 v[62:63], v[62:63], 0 op_sel_hi:[1,0]
	v_pk_add_f32 v[82:83], v[76:77], 0 op_sel_hi:[1,0]
	v_pk_add_f32 v[76:77], v[74:75], 0 op_sel_hi:[1,0]
	s_nop 0
	v_cvt_pk_bf16_f32 v74, v78, v79
	v_lshl_add_u64 v[78:79], v[126:127], 0, s[0:1]
	s_mov_b32 s0, 0x50000
	s_nop 0
	v_cvt_pk_bf16_f32 v75, v80, v81
	v_add_co_u32_e32 v80, vcc, s0, v126
; __device__ __forceinline__ unsigned cvt_pk_bf16(float lo, float hi) { unsigned r; asm volatile("s_nop 0\n\tv_cvt_pk_bf16_f32 %0, %1, %2" : "=v"(r) : "v"(lo), "v"(hi)); return r; }
; #define PG8_WAIT_V(n) asm volatile("s_waitcnt vmcnt(" #n ")" ::: "memory")
; #define PG8_BAR __builtin_amdgcn_s_barrier()
; template <class Epi>
; __device__ __forceinline__ void gemm_phase(LAS unsigned char* lds, const Gemm g, const StaticOrder& S, const Epi& E) {
;     ...
;         E(acc, cur, wr, wc, fr, fq);
;         if (!has_next) break;
; #pragma unroll
;         for (int a = 0; a < 2; ++a)
; #pragma unroll
;             for (int b = 0; b < 2; ++b)
; #pragma unroll
;                 for (int m = 0; m < 4; ++m)
; #pragma unroll
;                     for (int n = 0; n < 2; ++n) acc[a][b][m][n] = (f32x4){0.f, 0.f, 0.f, 0.f};
;         cur = nxt; cA = nA; cB = nB; ++ui;
;     }
;     PG8_WAIT_V(0);
;     if (wr == 0) PG8_BAR;
;     __device__ __forceinline__ void operator()(const f32x4 (&acc)[2][2][4][2], const Unit& u, int wr, int wc, int fr, int fq) const {
;     ...
;         for (int bj = 0; bj < 2; ++bj) {
;             const f32x4 s0 = swv[2 * bj], s1 = swv[2 * bj + 1];
; #pragma unroll
;             for (int ai = 0; ai < 2; ++ai)
; #pragma unroll
;                 for (int m = 0; m < 4; ++m) { const int r = row0 + ai * 128 + m * 16;
;                     const float rstd = ai ? rb[m] : ra[m];
;                     const f32x4 v0 = acc[ai][bj][m][0] * rstd + s0, v1 = acc[ai][bj][m][1] * rstd + s1;
;                     uint4 st; st.x = cvt_pk_bf16(v0[0], v0[1]); st.y = cvt_pk_bf16(v0[2], v0[3]); st.z = cvt_pk_bf16(v1[0], v1[1]); st.w = cvt_pk_bf16(v1[2], v1[3]);
;                     *(uint4*)(O + (size_t)r * ldc + col0 + bj * 128) = st; }
	s_mov_b64 s[0:1], 0x58000
	s_nop 0
	v_addc_co_u32_e32 v81, vcc, 0, v127, vcc
	s_nop 0
	v_cvt_pk_bf16_f32 v76, v76, v77
	s_nop 0
	v_cvt_pk_bf16_f32 v77, v82, v83
	global_store_dwordx4 v[80:81], v[74:77], off
	v_pk_add_f32 v[64:65], v[64:65], 0 op_sel_hi:[1,0]
	v_pk_add_f32 v[66:67], v[66:67], 0 op_sel_hi:[1,0]
	v_pk_add_f32 v[74:75], v[60:61], 0 op_sel_hi:[1,0]
	v_pk_add_f32 v[60:61], v[58:59], 0 op_sel_hi:[1,0]
	s_nop 0
	v_cvt_pk_bf16_f32 v58, v62, v63
	v_lshl_add_u64 v[62:63], v[126:127], 0, s[0:1]
	s_mov_b32 s0, 0x58000
	s_nop 0
	v_cvt_pk_bf16_f32 v59, v64, v65
	v_add_co_u32_e32 v64, vcc, s0, v126
	s_nop 0
	v_cvt_pk_bf16_f32 v60, v60, v61
	s_nop 0
	v_cvt_pk_bf16_f32 v61, v74, v75
	v_pk_add_f32 v[56:57], v[56:57], 0 op_sel_hi:[1,0]
	s_nop 0
	v_addc_co_u32_e32 v65, vcc, 0, v127, vcc
	global_store_dwordx4 v[64:65], v[58:61], off
	v_pk_add_f32 v[64:65], v[68:69], 0 op_sel_hi:[1,0]
	v_pk_add_f32 v[54:55], v[54:55], 0 op_sel_hi:[1,0]
	v_pk_add_f32 v[58:59], v[70:71], 0 op_sel_hi:[1,0]
	v_pk_add_f32 v[60:61], v[72:73], 0 op_sel_hi:[1,0]
	s_nop 0
	v_cvt_pk_bf16_f32 v58, v58, v59
	v_pk_add_f32 v[48:49], v[48:49], 0 op_sel_hi:[1,0]
	s_nop 0
	v_cvt_pk_bf16_f32 v59, v60, v61
	s_nop 0
	v_cvt_pk_bf16_f32 v60, v66, v67
	s_nop 0
	v_cvt_pk_bf16_f32 v61, v64, v65
	global_store_dwordx4 v[126:127], v[58:61], off offset:256
	v_pk_add_f32 v[46:47], v[46:47], 0 op_sel_hi:[1,0]
	v_pk_add_f32 v[40:41], v[40:41], 0 op_sel_hi:[1,0]
	v_pk_add_f32 v[58:59], v[52:53], 0 op_sel_hi:[1,0]
	v_pk_add_f32 v[52:53], v[50:51], 0 op_sel_hi:[1,0]
	s_nop 0
	v_cvt_pk_bf16_f32 v50, v54, v55
	s_nop 0
	v_cvt_pk_bf16_f32 v51, v56, v57
	v_pk_add_f32 v[38:39], v[38:39], 0 op_sel_hi:[1,0]
	s_nop 0
	v_cvt_pk_bf16_f32 v52, v52, v53
	s_nop 0
	v_cvt_pk_bf16_f32 v53, v58, v59
	global_store_dwordx4 v[118:119], v[50:53], off offset:256
	v_pk_add_f32 v[32:33], v[32:33], 0 op_sel_hi:[1,0]
	v_pk_add_f32 v[30:31], v[30:31], 0 op_sel_hi:[1,0]
	v_pk_add_f32 v[50:51], v[44:45], 0 op_sel_hi:[1,0]
	v_pk_add_f32 v[44:45], v[42:43], 0 op_sel_hi:[1,0]
	s_nop 0
	v_cvt_pk_bf16_f32 v42, v46, v47
	s_nop 0
	v_cvt_pk_bf16_f32 v43, v48, v49
	v_pk_add_f32 v[24:25], v[24:25], 0 op_sel_hi:[1,0]
	s_nop 0
	v_cvt_pk_bf16_f32 v44, v44, v45
	s_nop 0
	v_cvt_pk_bf16_f32 v45, v50, v51
	global_store_dwordx4 v[110:111], v[42:45], off offset:256
	v_pk_add_f32 v[22:23], v[22:23], 0 op_sel_hi:[1,0]
	v_pk_add_f32 v[16:17], v[16:17], 0 op_sel_hi:[1,0]
	v_pk_add_f32 v[42:43], v[36:37], 0 op_sel_hi:[1,0]
	v_pk_add_f32 v[36:37], v[34:35], 0 op_sel_hi:[1,0]
	s_nop 0
	v_cvt_pk_bf16_f32 v34, v38, v39
	s_nop 0
	v_cvt_pk_bf16_f32 v35, v40, v41
	v_pk_add_f32 v[14:15], v[14:15], 0 op_sel_hi:[1,0]
	s_nop 0
	v_cvt_pk_bf16_f32 v36, v36, v37
	s_nop 0
	v_cvt_pk_bf16_f32 v37, v42, v43
	global_store_dwordx4 v[102:103], v[34:37], off offset:256
	s_and_b64 vcc, exec, s[4:5]
	s_mov_b32 s37, s8
	v_pk_add_f32 v[34:35], v[28:29], 0 op_sel_hi:[1,0]
	v_pk_add_f32 v[28:29], v[26:27], 0 op_sel_hi:[1,0]
	s_nop 0
	v_cvt_pk_bf16_f32 v26, v30, v31
	s_nop 0
	v_cvt_pk_bf16_f32 v27, v32, v33
	s_mov_b32 s38, s10
	s_nop 0
	v_cvt_pk_bf16_f32 v28, v28, v29
	s_nop 0
	v_cvt_pk_bf16_f32 v29, v34, v35
	global_store_dwordx4 v[94:95], v[26:29], off offset:256
	s_mov_b64 s[18:19], s[14:15]
	s_mov_b64 s[16:17], s[12:13]
	v_pk_add_f32 v[26:27], v[20:21], 0 op_sel_hi:[1,0]
	v_pk_add_f32 v[20:21], v[18:19], 0 op_sel_hi:[1,0]
	s_nop 0
	v_cvt_pk_bf16_f32 v18, v22, v23
	s_nop 0
	v_cvt_pk_bf16_f32 v19, v24, v25
	v_pk_add_f32 v[8:9], v[8:9], 0 op_sel_hi:[1,0]
	s_nop 0
	v_cvt_pk_bf16_f32 v20, v20, v21
	s_nop 0
	v_cvt_pk_bf16_f32 v21, v26, v27
	global_store_dwordx4 v[86:87], v[18:21], off offset:256
	v_pk_add_f32 v[6:7], v[6:7], 0 op_sel_hi:[1,0]
	s_nop 0
	v_pk_add_f32 v[18:19], v[12:13], 0 op_sel_hi:[1,0]
	v_pk_add_f32 v[12:13], v[10:11], 0 op_sel_hi:[1,0]
	s_nop 0
	v_cvt_pk_bf16_f32 v10, v14, v15
	s_nop 0
	v_cvt_pk_bf16_f32 v11, v16, v17
	s_nop 0
	s_nop 0
	v_cvt_pk_bf16_f32 v12, v12, v13
	s_nop 0
	v_cvt_pk_bf16_f32 v13, v18, v19
	global_store_dwordx4 v[78:79], v[10:13], off offset:256
	s_nop 1
	v_pk_add_f32 v[10:11], v[2:3], 0 op_sel_hi:[1,0]
	v_pk_add_f32 v[2:3], v[0:1], 0 op_sel_hi:[1,0]
	s_nop 0
	v_cvt_pk_bf16_f32 v0, v6, v7
	s_nop 0
	v_cvt_pk_bf16_f32 v1, v8, v9
	s_nop 0
	s_nop 0
	v_cvt_pk_bf16_f32 v2, v2, v3
	s_nop 0
	v_cvt_pk_bf16_f32 v3, v10, v11
	global_store_dwordx4 v[62:63], v[0:3], off offset:256
	s_cbranch_vccz .LBB0_2725
	s_waitcnt vmcnt(0)
	s_cmpk_gt_u32 s22, 0xff
	s_cbranch_scc1 .LBB0_2736
	s_barrier

; #define PG8_STAGE(bufoff, gbase, voff) do { _Pragma("unroll") for (int _i = 0; _i < 2; ++_i) \
;         __builtin_amdgcn_global_load_lds((const unsigned*)((const char*)(gbase) + (voff)[_i]), (LAS unsigned*)(lds + (bufoff) + ldsw + _i * 8192), 16, 0, 0); } while (0)
; #define PG8_LDA(dst, b, h) do { _Pragma("unroll") for (int m = 0; m < 4; ++m) _Pragma("unroll") for (int k = 0; k < 2; ++k) dst[m][k] = *(const LAS bf16x8*)(lds + PG8_SA(b, h) + aoff + m * 2048 + k * 1024); } while (0)
; #define PG8_LDB(dst, b, h) do { _Pragma("unroll") for (int n = 0; n < 2; ++n) _Pragma("unroll") for (int k = 0; k < 2; ++k) dst[n][k] = *(const LAS bf16x8*)(lds + PG8_SB(b, h) + boff + n * 2048 + k * 1024); } while (0)
; #define PG8_WAIT_L(n) asm volatile("s_waitcnt lgkmcnt(" #n ")" ::: "memory")
; #define PG8_BAR __builtin_amdgcn_s_barrier()
; #define PG8_SCHED __builtin_amdgcn_sched_barrier(0)
; template <class Epi>
; __device__ __forceinline__ void gemm_phase(LAS unsigned char* lds, const Gemm g, const StaticOrder& S, const Epi& E) {
;     ...
;         const bool has_next = S.next(ui + 1, nxt);
;         const char* nA = has_next ? (const char*)g.A + (size_t)nxt.pm * tstep : cA; const char* nB = has_next ? (const char*)g.Bt + (size_t)nxt.pn * tstep : cB;
;         for (int t = 0; t < nt; t += 2) {
;             const bool last = (t == nt - 2);
;             const char* a1 = cA + (size_t)(t + 1) * kstep;
;             const char* a2 = last ? nA : cA + (size_t)(t + 2) * kstep; const char* b2 = last ? nB : cB + (size_t)(t + 2) * kstep;
;             const char* a3 = a2 + kstep; const char* b3 = b2 + kstep;
;             PG8_LDB(B0, 0, 0); PG8_SCHED; PG8_LDA(At, 0, 0); PG8_STAGE(PG8_SA(1, 1), a1 + hstep, voffA);
;             PG8_WAIT_L(8); PG8_BAR; PG8_WAIT_L(0); PG8_MMA(0, 0, At, B0); PG8_BAR; PG8_SCHED;
;             PG8_LDB(B1, 0, 1); PG8_STAGE(PG8_SB(0, 0), b2, voffB);
;             PG8_BAR; PG8_WAIT_L(0); PG8_MMA(0, 1, At, B1); PG8_BAR;
;             PG8_LDA(At, 0, 1); PG8_STAGE(PG8_SA(0, 0), a2, voffA);
;             PG8_BAR; PG8_WAIT_L(0); PG8_MMA(1, 0, At, B0); PG8_BAR; PG8_SCHED;
;     ...
; #pragma unroll
;         for (int a = 0; a < 2; ++a)
; #pragma unroll
;             for (int b = 0; b < 2; ++b)
; #pragma unroll
;                 for (int m = 0; m < 4; ++m)
; #pragma unroll
;                     for (int n = 0; n < 2; ++n) acc[a][b][m][n] = (f32x4){0.f, 0.f, 0.f, 0.f};
.LBB0_2800:
	s_ashr_i32 s17, s16, 31
	s_lshl_b64 s[0:1], s[16:17], 19
	v_cmp_lt_i64_e32 vcc, s[18:19], v[184:185]
	s_add_u32 s18, s27, s0
	s_addc_u32 s19, s28, s1
	s_and_b64 s[0:1], vcc, exec
	s_cselect_b32 s17, s19, s7
	s_cselect_b32 s49, s18, s6
	s_ashr_i32 s15, s14, 31
	s_lshl_b64 s[0:1], s[14:15], 19
	s_add_u32 s20, s29, s0
	s_addc_u32 s21, s30, s1
	s_and_b64 s[0:1], vcc, exec
	s_cselect_b32 s15, s21, s23
	s_cselect_b32 s50, s20, s22
	s_add_u32 s6, s6, 0x40080
	s_addc_u32 s7, s7, 0
	s_add_u32 s51, s22, 0x100
	s_addc_u32 s52, s23, 0
	s_mov_b32 s54, -2
	s_add_u32 s0, s6, 0xfffc0080
	s_addc_u32 s1, s7, -1
	s_add_i32 s55, 0, 0x10000
	v_add_u32_e32 v130, s55, v243
	ds_read_b128 v[34:37], v130
	ds_read_b128 v[38:41], v130 offset:1024
	ds_read_b128 v[122:125], v130 offset:2048
	ds_read_b128 v[130:133], v130 offset:3072
	s_cmp_eq_u32 s54, 12
	s_cselect_b32 s25, s17, s1
	s_cselect_b32 s24, s49, s0
	s_cselect_b32 s23, s15, s52
	s_cselect_b32 s22, s50, s51
	v_lshl_add_u64 v[186:187], s[6:7], 0, v[196:197]
	s_add_i32 m0, s34, 0xc000
	ds_read_b128 v[146:149], v245
	ds_read_b128 v[150:153], v245 offset:1024
	ds_read_b128 v[154:157], v245 offset:2048
	ds_read_b128 v[158:161], v245 offset:3072
	ds_read_b128 v[162:165], v245 offset:4096
	ds_read_b128 v[166:169], v245 offset:5120
	ds_read_b128 v[170:173], v245 offset:6144
	ds_read_b128 v[174:177], v245 offset:7168
	global_load_lds_dwordx4 v[186:187], off
	s_add_i32 m0, s34, 0xe000
	v_lshl_add_u64 v[186:187], s[6:7], 0, v[198:199]
	global_load_lds_dwordx4 v[186:187], off
	s_waitcnt lgkmcnt(8)
	s_barrier
	s_waitcnt lgkmcnt(0)
	v_mfma_f32_16x16x32_bf16 v[142:145], v[34:37], v[146:149], 0
	v_mfma_f32_16x16x32_bf16 v[138:141], v[122:125], v[146:149], 0
	v_mfma_f32_16x16x32_bf16 v[134:137], v[34:37], v[154:157], 0
	v_mfma_f32_16x16x32_bf16 v[126:129], v[122:125], v[154:157], 0
	v_mfma_f32_16x16x32_bf16 v[118:121], v[34:37], v[162:165], 0
	v_mfma_f32_16x16x32_bf16 v[114:117], v[122:125], v[162:165], 0
	v_mfma_f32_16x16x32_bf16 v[110:113], v[34:37], v[170:173], 0
	v_mfma_f32_16x16x32_bf16 v[106:109], v[122:125], v[170:173], 0
	v_mfma_f32_16x16x32_bf16 v[142:145], v[38:41], v[150:153], v[142:145]
	v_mfma_f32_16x16x32_bf16 v[138:141], v[130:133], v[150:153], v[138:141]
	v_mfma_f32_16x16x32_bf16 v[134:137], v[38:41], v[158:161], v[134:137]
	v_mfma_f32_16x16x32_bf16 v[126:129], v[130:133], v[158:161], v[126:129]
	v_mfma_f32_16x16x32_bf16 v[118:121], v[38:41], v[166:169], v[118:121]
	v_mfma_f32_16x16x32_bf16 v[114:117], v[130:133], v[166:169], v[114:117]
	v_mfma_f32_16x16x32_bf16 v[110:113], v[38:41], v[174:177], v[110:113]
	v_mfma_f32_16x16x32_bf16 v[106:109], v[130:133], v[174:177], v[106:109]
	s_barrier
	s_add_i32 s56, 0, 0x14000
	v_add_u32_e32 v186, s56, v243
	s_add_i32 s0, s55, s31
	ds_read_b128 v[200:203], v186
	ds_read_b128 v[204:207], v186 offset:1024
	ds_read_b128 v[208:211], v186 offset:2048
	ds_read_b128 v[212:215], v186 offset:3072
	v_lshl_add_u64 v[186:187], s[22:23], 0, v[4:5]
	s_mov_b32 m0, s0
	v_lshl_add_u64 v[216:217], s[22:23], 0, v[190:191]
	global_load_lds_dwordx4 v[186:187], off
	s_add_i32 m0, s0, 0x2000
	s_nop 0
	global_load_lds_dwordx4 v[216:217], off
	s_barrier
	s_waitcnt lgkmcnt(0)
	v_mfma_f32_16x16x32_bf16 v[70:73], v[200:203], v[146:149], 0
	v_mfma_f32_16x16x32_bf16 v[66:69], v[208:211], v[146:149], 0
	v_mfma_f32_16x16x32_bf16 v[62:65], v[200:203], v[154:157], 0
	v_mfma_f32_16x16x32_bf16 v[58:61], v[208:211], v[154:157], 0
	v_mfma_f32_16x16x32_bf16 v[54:57], v[200:203], v[162:165], 0
	v_mfma_f32_16x16x32_bf16 v[50:53], v[208:211], v[162:165], 0
	v_mfma_f32_16x16x32_bf16 v[46:49], v[200:203], v[170:173], 0
	v_mfma_f32_16x16x32_bf16 v[42:45], v[208:211], v[170:173], 0
	v_mfma_f32_16x16x32_bf16 v[70:73], v[204:207], v[150:153], v[70:73]
	v_mfma_f32_16x16x32_bf16 v[66:69], v[212:215], v[150:153], v[66:69]
	v_mfma_f32_16x16x32_bf16 v[62:65], v[204:207], v[158:161], v[62:65]
	v_mfma_f32_16x16x32_bf16 v[58:61], v[212:215], v[158:161], v[58:61]
	v_mfma_f32_16x16x32_bf16 v[54:57], v[204:207], v[166:169], v[54:57]
	v_mfma_f32_16x16x32_bf16 v[50:53], v[212:215], v[166:169], v[50:53]
	v_mfma_f32_16x16x32_bf16 v[46:49], v[204:207], v[174:177], v[46:49]
	v_mfma_f32_16x16x32_bf16 v[42:45], v[212:215], v[174:177], v[42:45]
	s_mov_b32 m0, s34
	v_lshl_add_u64 v[218:219], s[24:25], 0, v[194:195]
	s_barrier
	ds_read_b128 v[146:149], v245 offset:16384
	ds_read_b128 v[150:153], v245 offset:17408
	ds_read_b128 v[154:157], v245 offset:18432
	ds_read_b128 v[158:161], v245 offset:19456
	ds_read_b128 v[162:165], v245 offset:20480
	ds_read_b128 v[166:169], v245 offset:21504
	ds_read_b128 v[170:173], v245 offset:22528
	ds_read_b128 v[174:177], v245 offset:23552
	global_load_lds_dwordx4 v[218:219], off
	s_mov_b32 m0, s35
	v_lshl_add_u64 v[220:221], s[24:25], 0, v[192:193]
	global_load_lds_dwordx4 v[220:221], off
	s_barrier
	s_waitcnt lgkmcnt(0)
	v_mfma_f32_16x16x32_bf16 v[102:105], v[34:37], v[146:149], 0
	v_mfma_f32_16x16x32_bf16 v[98:101], v[122:125], v[146:149], 0
	v_mfma_f32_16x16x32_bf16 v[94:97], v[34:37], v[154:157], 0
	v_mfma_f32_16x16x32_bf16 v[90:93], v[122:125], v[154:157], 0
	v_mfma_f32_16x16x32_bf16 v[86:89], v[34:37], v[162:165], 0
	v_mfma_f32_16x16x32_bf16 v[82:85], v[122:125], v[162:165], 0
	v_mfma_f32_16x16x32_bf16 v[34:37], v[34:37], v[170:173], 0
	v_mfma_f32_16x16x32_bf16 v[102:105], v[38:41], v[150:153], v[102:105]
	v_mfma_f32_16x16x32_bf16 v[98:101], v[130:133], v[150:153], v[98:101]
	v_mfma_f32_16x16x32_bf16 v[94:97], v[38:41], v[158:161], v[94:97]
	v_mfma_f32_16x16x32_bf16 v[90:93], v[130:133], v[158:161], v[90:93]
	v_mfma_f32_16x16x32_bf16 v[86:89], v[38:41], v[166:169], v[86:89]
	v_mfma_f32_16x16x32_bf16 v[82:85], v[130:133], v[166:169], v[82:85]
	v_mfma_f32_16x16x32_bf16 v[34:37], v[38:41], v[174:177], v[34:37]
	v_mfma_f32_16x16x32_bf16 v[38:41], v[122:125], v[170:173], 0
	v_mfma_f32_16x16x32_bf16 v[38:41], v[130:133], v[174:177], v[38:41]
	s_barrier
; #define PG8_STAGE(bufoff, gbase, voff) do { _Pragma("unroll") for (int _i = 0; _i < 2; ++_i) \
;         __builtin_amdgcn_global_load_lds((const unsigned*)((const char*)(gbase) + (voff)[_i]), (LAS unsigned*)(lds + (bufoff) + ldsw + _i * 8192), 16, 0, 0); } while (0)
; #define PG8_LDA(dst, b, h) do { _Pragma("unroll") for (int m = 0; m < 4; ++m) _Pragma("unroll") for (int k = 0; k < 2; ++k) dst[m][k] = *(const LAS bf16x8*)(lds + PG8_SA(b, h) + aoff + m * 2048 + k * 1024); } while (0)
; #define PG8_LDB(dst, b, h) do { _Pragma("unroll") for (int n = 0; n < 2; ++n) _Pragma("unroll") for (int k = 0; k < 2; ++k) dst[n][k] = *(const LAS bf16x8*)(lds + PG8_SB(b, h) + boff + n * 2048 + k * 1024); } while (0)
; #define PG8_MMA(ai, bj, At, Bt) do { __builtin_amdgcn_s_setprio(1); _Pragma("unroll") for (int m = 0; m < 4; ++m) _Pragma("unroll") for (int n = 0; n < 2; ++n) _Pragma("unroll") for (int k = 0; k < 2; ++k) \
;         acc[ai][bj][m][n] = __builtin_amdgcn_mfma_f32_16x16x32_bf16(Bt[n][k], At[m][k], acc[ai][bj][m][n], 0, 0, 0); __builtin_amdgcn_s_setprio(0); } while (0)
; #define PG8_WAIT_V(n) asm volatile("s_waitcnt vmcnt(" #n ")" ::: "memory")
; #define PG8_WAIT_L(n) asm volatile("s_waitcnt lgkmcnt(" #n ")" ::: "memory")
; #define PG8_BAR __builtin_amdgcn_s_barrier()
; #define PG8_SCHED __builtin_amdgcn_sched_barrier(0)
; template <class Epi>
; __device__ __forceinline__ void gemm_phase(LAS unsigned char* lds, const Gemm g, const StaticOrder& S, const Epi& E) {
;     ...
;             PG8_STAGE(PG8_SB(0, 1), b2 + hstep, voffB);
;             PG8_WAIT_V(6); PG8_BAR; PG8_MMA(1, 1, At, B1); PG8_BAR;
;             PG8_LDB(B0, 1, 0); PG8_SCHED; PG8_LDA(At, 1, 0); PG8_STAGE(PG8_SA(0, 1), a2 + hstep, voffA);
;             PG8_WAIT_L(8); PG8_BAR; PG8_WAIT_L(0); PG8_MMA(0, 0, At, B0); PG8_BAR; PG8_SCHED;
;             PG8_LDB(B1, 1, 1); PG8_STAGE(PG8_SB(1, 0), b3, voffB);
	s_add_u32 s0, s22, 0x40000
	s_addc_u32 s1, s23, 0
	s_add_i32 s55, s56, s31
	s_mov_b32 m0, s55
	v_lshl_add_u64 v[74:75], s[0:1], 0, v[4:5]
	global_load_lds_dwordx4 v[74:75], off
	s_add_i32 m0, s55, 0x2000
	v_lshl_add_u64 v[74:75], s[0:1], 0, v[190:191]
	global_load_lds_dwordx4 v[74:75], off
	s_waitcnt vmcnt(6)
	s_barrier
	v_mfma_f32_16x16x32_bf16 v[30:33], v[200:203], v[146:149], 0
	v_mfma_f32_16x16x32_bf16 v[26:29], v[208:211], v[146:149], 0
	v_mfma_f32_16x16x32_bf16 v[22:25], v[200:203], v[154:157], 0
	v_mfma_f32_16x16x32_bf16 v[18:21], v[208:211], v[154:157], 0
	v_mfma_f32_16x16x32_bf16 v[14:17], v[200:203], v[162:165], 0
	v_mfma_f32_16x16x32_bf16 v[10:13], v[208:211], v[162:165], 0
	v_mfma_f32_16x16x32_bf16 v[6:9], v[200:203], v[170:173], 0
	v_mfma_f32_16x16x32_bf16 v[0:3], v[208:211], v[170:173], 0
	v_mfma_f32_16x16x32_bf16 v[30:33], v[204:207], v[150:153], v[30:33]
	v_mfma_f32_16x16x32_bf16 v[26:29], v[212:215], v[150:153], v[26:29]
	v_mfma_f32_16x16x32_bf16 v[22:25], v[204:207], v[158:161], v[22:25]
	v_mfma_f32_16x16x32_bf16 v[18:21], v[212:215], v[158:161], v[18:21]
	v_mfma_f32_16x16x32_bf16 v[14:17], v[204:207], v[166:169], v[14:17]
	v_mfma_f32_16x16x32_bf16 v[10:13], v[212:215], v[166:169], v[10:13]
	v_mfma_f32_16x16x32_bf16 v[6:9], v[204:207], v[174:177], v[6:9]
	v_mfma_f32_16x16x32_bf16 v[0:3], v[212:215], v[174:177], v[0:3]
	s_add_i32 s55, 0, 0x18000
	v_add_u32_e32 v130, s55, v243
	s_barrier
	ds_read_b128 v[74:77], v130
	ds_read_b128 v[78:81], v130 offset:1024
	ds_read_b128 v[122:125], v130 offset:2048
	ds_read_b128 v[130:133], v130 offset:3072
	s_add_u32 s0, s24, 0x40000
	s_addc_u32 s1, s25, 0
	s_mov_b32 m0, s36
	v_lshl_add_u64 v[200:201], s[0:1], 0, v[194:195]
	ds_read_b128 v[146:149], v245 offset:32768
	ds_read_b128 v[150:153], v245 offset:33792
	ds_read_b128 v[154:157], v245 offset:34816
	ds_read_b128 v[158:161], v245 offset:35840
	ds_read_b128 v[162:165], v245 offset:36864
	ds_read_b128 v[166:169], v245 offset:37888
	ds_read_b128 v[170:173], v245 offset:38912
	ds_read_b128 v[174:177], v245 offset:39936
	global_load_lds_dwordx4 v[200:201], off
	s_mov_b32 m0, s37
	v_lshl_add_u64 v[200:201], s[0:1], 0, v[192:193]
	global_load_lds_dwordx4 v[200:201], off
	s_waitcnt lgkmcnt(8)
	s_barrier
	s_waitcnt lgkmcnt(0)
	v_mfma_f32_16x16x32_bf16 v[142:145], v[74:77], v[146:149], v[142:145]
	v_mfma_f32_16x16x32_bf16 v[138:141], v[122:125], v[146:149], v[138:141]
	v_mfma_f32_16x16x32_bf16 v[134:137], v[74:77], v[154:157], v[134:137]
	v_mfma_f32_16x16x32_bf16 v[126:129], v[122:125], v[154:157], v[126:129]
	v_mfma_f32_16x16x32_bf16 v[118:121], v[74:77], v[162:165], v[118:121]
	v_mfma_f32_16x16x32_bf16 v[114:117], v[122:125], v[162:165], v[114:117]
	v_mfma_f32_16x16x32_bf16 v[110:113], v[74:77], v[170:173], v[110:113]
	v_mfma_f32_16x16x32_bf16 v[106:109], v[122:125], v[170:173], v[106:109]
	v_mfma_f32_16x16x32_bf16 v[142:145], v[78:81], v[150:153], v[142:145]
	v_mfma_f32_16x16x32_bf16 v[138:141], v[130:133], v[150:153], v[138:141]
	v_mfma_f32_16x16x32_bf16 v[134:137], v[78:81], v[158:161], v[134:137]
	v_mfma_f32_16x16x32_bf16 v[126:129], v[130:133], v[158:161], v[126:129]
	v_mfma_f32_16x16x32_bf16 v[118:121], v[78:81], v[166:169], v[118:121]
	v_mfma_f32_16x16x32_bf16 v[114:117], v[130:133], v[166:169], v[114:117]
	v_mfma_f32_16x16x32_bf16 v[110:113], v[78:81], v[174:177], v[110:113]
	v_mfma_f32_16x16x32_bf16 v[106:109], v[130:133], v[174:177], v[106:109]
	s_barrier
	s_add_i32 s24, 0, 0x1c000
	s_add_i32 s0, s55, s31
	v_add_u32_e32 v212, s24, v243
	v_lshl_add_u64 v[186:187], v[186:187], 0, s[86:87]
	s_mov_b32 m0, s0
	ds_read_b128 v[200:203], v212
	ds_read_b128 v[204:207], v212 offset:1024
	ds_read_b128 v[208:211], v212 offset:2048
	ds_read_b128 v[212:215], v212 offset:3072
	global_load_lds_dwordx4 v[186:187], off
	s_add_i32 m0, s0, 0x2000
	v_lshl_add_u64 v[186:187], v[216:217], 0, s[86:87]
	global_load_lds_dwordx4 v[186:187], off
	s_barrier
; #define PG8_STAGE(bufoff, gbase, voff) do { _Pragma("unroll") for (int _i = 0; _i < 2; ++_i) \
;         __builtin_amdgcn_global_load_lds((const unsigned*)((const char*)(gbase) + (voff)[_i]), (LAS unsigned*)(lds + (bufoff) + ldsw + _i * 8192), 16, 0, 0); } while (0)
; #define PG8_LDA(dst, b, h) do { _Pragma("unroll") for (int m = 0; m < 4; ++m) _Pragma("unroll") for (int k = 0; k < 2; ++k) dst[m][k] = *(const LAS bf16x8*)(lds + PG8_SA(b, h) + aoff + m * 2048 + k * 1024); } while (0)
; #define PG8_LDB(dst, b, h) do { _Pragma("unroll") for (int n = 0; n < 2; ++n) _Pragma("unroll") for (int k = 0; k < 2; ++k) dst[n][k] = *(const LAS bf16x8*)(lds + PG8_SB(b, h) + boff + n * 2048 + k * 1024); } while (0)
; #define PG8_MMA(ai, bj, At, Bt) do { __builtin_amdgcn_s_setprio(1); _Pragma("unroll") for (int m = 0; m < 4; ++m) _Pragma("unroll") for (int n = 0; n < 2; ++n) _Pragma("unroll") for (int k = 0; k < 2; ++k) \
;         acc[ai][bj][m][n] = __builtin_amdgcn_mfma_f32_16x16x32_bf16(Bt[n][k], At[m][k], acc[ai][bj][m][n], 0, 0, 0); __builtin_amdgcn_s_setprio(0); } while (0)
; #define PG8_WAIT_V(n) asm volatile("s_waitcnt vmcnt(" #n ")" ::: "memory")
; #define PG8_WAIT_L(n) asm volatile("s_waitcnt lgkmcnt(" #n ")" ::: "memory")
; #define PG8_BAR __builtin_amdgcn_s_barrier()
; #define PG8_SCHED __builtin_amdgcn_sched_barrier(0)
; template <class Epi>
; __device__ __forceinline__ void gemm_phase(LAS unsigned char* lds, const Gemm g, const StaticOrder& S, const Epi& E) {
;     ...
;         for (int t = 0; t < nt; t += 2) {
;     ...
;             PG8_LDB(B1, 1, 1); PG8_STAGE(PG8_SB(1, 0), b3, voffB);
;             PG8_BAR; PG8_WAIT_L(0); PG8_MMA(0, 1, At, B1); PG8_BAR;
;             PG8_LDA(At, 1, 1); PG8_STAGE(PG8_SA(1, 0), a3, voffA);
;             PG8_BAR; PG8_WAIT_L(0); PG8_MMA(1, 0, At, B0); PG8_BAR; PG8_SCHED;
;             PG8_STAGE(PG8_SB(1, 1), b3 + hstep, voffB);
;             PG8_WAIT_V(6); PG8_BAR; PG8_MMA(1, 1, At, B1); PG8_BAR;
	s_waitcnt lgkmcnt(0)
	v_mfma_f32_16x16x32_bf16 v[70:73], v[200:203], v[146:149], v[70:73]
	v_mfma_f32_16x16x32_bf16 v[66:69], v[208:211], v[146:149], v[66:69]
	v_mfma_f32_16x16x32_bf16 v[62:65], v[200:203], v[154:157], v[62:65]
	v_mfma_f32_16x16x32_bf16 v[58:61], v[208:211], v[154:157], v[58:61]
	v_mfma_f32_16x16x32_bf16 v[54:57], v[200:203], v[162:165], v[54:57]
	v_mfma_f32_16x16x32_bf16 v[50:53], v[208:211], v[162:165], v[50:53]
	v_mfma_f32_16x16x32_bf16 v[46:49], v[200:203], v[170:173], v[46:49]
	v_mfma_f32_16x16x32_bf16 v[42:45], v[208:211], v[170:173], v[42:45]
	v_mfma_f32_16x16x32_bf16 v[70:73], v[204:207], v[150:153], v[70:73]
	v_mfma_f32_16x16x32_bf16 v[66:69], v[212:215], v[150:153], v[66:69]
	v_mfma_f32_16x16x32_bf16 v[62:65], v[204:207], v[158:161], v[62:65]
	v_mfma_f32_16x16x32_bf16 v[58:61], v[212:215], v[158:161], v[58:61]
	v_mfma_f32_16x16x32_bf16 v[54:57], v[204:207], v[166:169], v[54:57]
	v_mfma_f32_16x16x32_bf16 v[50:53], v[212:215], v[166:169], v[50:53]
	v_mfma_f32_16x16x32_bf16 v[46:49], v[204:207], v[174:177], v[46:49]
	v_mfma_f32_16x16x32_bf16 v[42:45], v[212:215], v[174:177], v[42:45]
	s_mov_b32 m0, s40
	v_lshl_add_u64 v[186:187], v[218:219], 0, s[86:87]
	s_barrier
	ds_read_b128 v[146:149], v245 offset:49152
	ds_read_b128 v[150:153], v245 offset:50176
	ds_read_b128 v[154:157], v245 offset:51200
	ds_read_b128 v[158:161], v245 offset:52224
	ds_read_b128 v[162:165], v245 offset:53248
	ds_read_b128 v[166:169], v245 offset:54272
	ds_read_b128 v[170:173], v245 offset:55296
	ds_read_b128 v[174:177], v245 offset:56320
	global_load_lds_dwordx4 v[186:187], off
	s_mov_b32 m0, s41
	v_lshl_add_u64 v[186:187], v[220:221], 0, s[86:87]
	global_load_lds_dwordx4 v[186:187], off
	s_barrier
	s_waitcnt lgkmcnt(0)
	v_mfma_f32_16x16x32_bf16 v[102:105], v[74:77], v[146:149], v[102:105]
	v_mfma_f32_16x16x32_bf16 v[94:97], v[74:77], v[154:157], v[94:97]
	v_mfma_f32_16x16x32_bf16 v[86:89], v[74:77], v[162:165], v[86:89]
	v_mfma_f32_16x16x32_bf16 v[34:37], v[74:77], v[170:173], v[34:37]
	v_mfma_f32_16x16x32_bf16 v[102:105], v[78:81], v[150:153], v[102:105]
	v_mfma_f32_16x16x32_bf16 v[98:101], v[122:125], v[146:149], v[98:101]
	v_mfma_f32_16x16x32_bf16 v[94:97], v[78:81], v[158:161], v[94:97]
	v_mfma_f32_16x16x32_bf16 v[90:93], v[122:125], v[154:157], v[90:93]
	v_mfma_f32_16x16x32_bf16 v[86:89], v[78:81], v[166:169], v[86:89]
	v_mfma_f32_16x16x32_bf16 v[82:85], v[122:125], v[162:165], v[82:85]
	v_mfma_f32_16x16x32_bf16 v[78:81], v[78:81], v[174:177], v[34:37]
	v_mfma_f32_16x16x32_bf16 v[34:37], v[122:125], v[170:173], v[38:41]
	v_mfma_f32_16x16x32_bf16 v[98:101], v[130:133], v[150:153], v[98:101]
	v_mfma_f32_16x16x32_bf16 v[90:93], v[130:133], v[158:161], v[90:93]
	v_mfma_f32_16x16x32_bf16 v[82:85], v[130:133], v[166:169], v[82:85]
	v_mfma_f32_16x16x32_bf16 v[74:77], v[130:133], v[174:177], v[34:37]
	s_barrier
	s_add_u32 s0, s22, 0x40080
	s_addc_u32 s1, s23, 0
	s_add_i32 s22, s24, s31
	s_mov_b32 m0, s22
	v_lshl_add_u64 v[34:35], s[0:1], 0, v[4:5]
	global_load_lds_dwordx4 v[34:35], off
	s_add_i32 m0, s22, 0x2000
	v_lshl_add_u64 v[34:35], s[0:1], 0, v[190:191]
	global_load_lds_dwordx4 v[34:35], off
	s_waitcnt vmcnt(6)
	s_barrier
	v_mfma_f32_16x16x32_bf16 v[30:33], v[200:203], v[146:149], v[30:33]
	v_mfma_f32_16x16x32_bf16 v[26:29], v[208:211], v[146:149], v[26:29]
	v_mfma_f32_16x16x32_bf16 v[22:25], v[200:203], v[154:157], v[22:25]
	v_mfma_f32_16x16x32_bf16 v[18:21], v[208:211], v[154:157], v[18:21]
	v_mfma_f32_16x16x32_bf16 v[14:17], v[200:203], v[162:165], v[14:17]
	v_mfma_f32_16x16x32_bf16 v[10:13], v[208:211], v[162:165], v[10:13]
	v_mfma_f32_16x16x32_bf16 v[6:9], v[200:203], v[170:173], v[6:9]
	v_mfma_f32_16x16x32_bf16 v[0:3], v[208:211], v[170:173], v[0:3]
	v_mfma_f32_16x16x32_bf16 v[30:33], v[204:207], v[150:153], v[30:33]
	v_mfma_f32_16x16x32_bf16 v[26:29], v[212:215], v[150:153], v[26:29]
	v_mfma_f32_16x16x32_bf16 v[22:25], v[204:207], v[158:161], v[22:25]
	v_mfma_f32_16x16x32_bf16 v[18:21], v[212:215], v[158:161], v[18:21]
	v_mfma_f32_16x16x32_bf16 v[14:17], v[204:207], v[166:169], v[14:17]
	v_mfma_f32_16x16x32_bf16 v[10:13], v[212:215], v[166:169], v[10:13]
	v_mfma_f32_16x16x32_bf16 v[6:9], v[204:207], v[174:177], v[6:9]
	v_mfma_f32_16x16x32_bf16 v[0:3], v[212:215], v[174:177], v[0:3]
	s_add_i32 s54, s54, 2
	s_add_u32 s6, s6, 0x100
	s_addc_u32 s7, s7, 0
	s_add_u32 s51, s51, 0x100
	s_addc_u32 s52, s52, 0
	s_cmp_gt_u32 s54, 13
	s_barrier
	s_cbranch_scc1 .Lpeel_exit_2

;     __device__ __forceinline__ void operator()(const f32x4 (&acc)[2][2][4][2], const Unit& u, int wr, int wc, int fr, int fq) const {
;         const int row0 = u.pm * 256 + wr * 64 + fr, col0 = u.pn * 256 + wc * 32 + 8 * fq;
;         f32x4 ra, rb; load_rstd(ss, row0, ra, rb);
;         const float* swp = sw + (size_t)(u.pm >> 3) * 3072 + col0;
;         const f32x4 swv[4] = {*(const f32x4*)(swp), *(const f32x4*)(swp + 4), *(const f32x4*)(swp + 128), *(const f32x4*)(swp + 132)};
; #pragma unroll
;         for (int bj = 0; bj < 2; ++bj) {
;             const f32x4 s0 = swv[2 * bj], s1 = swv[2 * bj + 1];
; #pragma unroll
;             for (int ai = 0; ai < 2; ++ai) {
;                 uint4 yld[4], zld[4];
; #pragma unroll
;                 for (int i = 0; i < 4; ++i) { const size_t off = (size_t)(row0 + ai * 128 + i * 16) * DM + col0 + bj * 128;
;                     yld[i] = *(const uint4*)(Y + off); zld[i] = first ? make_uint4(0u, 0u, 0u, 0u) : *(const uint4*)(Z + off); }
.Lpeel_exit_2:
	v_lshl_add_u32 v218, s43, 8, v242
	v_ashrrev_i32_e32 v219, 31, v218
	v_lshl_add_u64 v[34:35], v[218:219], 2, s[12:13]
	s_ashr_i32 s0, s43, 3
	global_load_dword v206, v[34:35], off
	global_load_dword v204, v[34:35], off offset:64
	global_load_dword v187, v[34:35], off offset:128
	global_load_dword v186, v[34:35], off offset:192
	global_load_dword v246, v[34:35], off offset:512
	global_load_dword v209, v[34:35], off offset:576
	global_load_dword v207, v[34:35], off offset:640
	global_load_dword v205, v[34:35], off offset:704
	s_mul_hi_i32 s1, s0, 0x3000
	s_mulk_i32 s0, 0x3000
	v_lshl_or_b32 v200, s48, 8, v244
	s_add_u32 s0, s38, s0
	s_addc_u32 s1, s39, s1
	v_ashrrev_i32_e32 v201, 31, v200
	v_lshl_add_u64 v[38:39], v[200:201], 2, s[0:1]
	v_lshlrev_b64 v[210:211], 10, v[218:219]
	global_load_dwordx4 v[122:125], v[38:39], off offset:16
	global_load_dwordx4 v[130:133], v[38:39], off
	global_load_dwordx4 v[34:37], v[38:39], off offset:528
	s_nop 0
	global_load_dwordx4 v[38:41], v[38:39], off offset:512
	v_lshl_add_u64 v[146:147], v[210:211], 0, v[200:201]
	v_lshl_add_u64 v[148:149], v[146:147], 1, s[10:11]
	global_load_dwordx4 v[174:177], v[148:149], off
	v_cndmask_b32_e64 v148, 0, 1, s[88:89]
	v_mov_b32_e32 v162, 0
	v_cmp_ne_u32_e64 s[6:7], 1, v148
	s_andn2_b64 vcc, exec, s[88:89]
	v_mov_b32_e32 v170, 0
	v_mov_b32_e32 v171, 0
	v_mov_b32_e32 v172, 0
	v_mov_b32_e32 v173, 0
	s_cbranch_vccnz .LBB0_2804
	v_lshl_add_u64 v[146:147], v[146:147], 1, s[8:9]
	global_load_dwordx4 v[170:173], v[146:147], off

; #define PG8_STAGE(bufoff, gbase, voff) do { _Pragma("unroll") for (int _i = 0; _i < 2; ++_i) \
;         __builtin_amdgcn_global_load_lds((const unsigned*)((const char*)(gbase) + (voff)[_i]), (LAS unsigned*)(lds + (bufoff) + ldsw + _i * 8192), 16, 0, 0); } while (0)
; #define PG8_LDA(dst, b, h) do { _Pragma("unroll") for (int m = 0; m < 4; ++m) _Pragma("unroll") for (int k = 0; k < 2; ++k) dst[m][k] = *(const LAS bf16x8*)(lds + PG8_SA(b, h) + aoff + m * 2048 + k * 1024); } while (0)
; #define PG8_LDB(dst, b, h) do { _Pragma("unroll") for (int n = 0; n < 2; ++n) _Pragma("unroll") for (int k = 0; k < 2; ++k) dst[n][k] = *(const LAS bf16x8*)(lds + PG8_SB(b, h) + boff + n * 2048 + k * 1024); } while (0)
; #define PG8_WAIT_L(n) asm volatile("s_waitcnt lgkmcnt(" #n ")" ::: "memory")
; #define PG8_BAR __builtin_amdgcn_s_barrier()
; #define PG8_SCHED __builtin_amdgcn_sched_barrier(0)
; template <class Epi>
; __device__ __forceinline__ void gemm_phase(LAS unsigned char* lds, const Gemm g, const StaticOrder& S, const Epi& E) {
;     ...
;         const bool has_next = S.next(ui + 1, nxt);
;         const char* nA = has_next ? (const char*)g.A + (size_t)nxt.pm * tstep : cA; const char* nB = has_next ? (const char*)g.Bt + (size_t)nxt.pn * tstep : cB;
;         for (int t = 0; t < nt; t += 2) {
;             const bool last = (t == nt - 2);
;             const char* a1 = cA + (size_t)(t + 1) * kstep;
;             const char* a2 = last ? nA : cA + (size_t)(t + 2) * kstep; const char* b2 = last ? nB : cB + (size_t)(t + 2) * kstep;
;             const char* a3 = a2 + kstep; const char* b3 = b2 + kstep;
;             PG8_LDB(B0, 0, 0); PG8_SCHED; PG8_LDA(At, 0, 0); PG8_STAGE(PG8_SA(1, 1), a1 + hstep, voffA);
;             PG8_WAIT_L(8); PG8_BAR; PG8_WAIT_L(0); PG8_MMA(0, 0, At, B0); PG8_BAR; PG8_SCHED;
;             PG8_LDB(B1, 0, 1); PG8_STAGE(PG8_SB(0, 0), b2, voffB);
;             PG8_BAR; PG8_WAIT_L(0); PG8_MMA(0, 1, At, B1); PG8_BAR;
;             PG8_LDA(At, 0, 1); PG8_STAGE(PG8_SA(0, 0), a2, voffA);
;             PG8_BAR; PG8_WAIT_L(0); PG8_MMA(1, 0, At, B0); PG8_BAR; PG8_SCHED;
;     ...
; #pragma unroll
;         for (int a = 0; a < 2; ++a)
; #pragma unroll
;             for (int b = 0; b < 2; ++b)
; #pragma unroll
;                 for (int m = 0; m < 4; ++m)
; #pragma unroll
;                     for (int n = 0; n < 2; ++n) acc[a][b][m][n] = (f32x4){0.f, 0.f, 0.f, 0.f};
.LBB0_2896:
	v_mov_b64_e32 v[0:1], 0x1600
	s_ashr_i32 s13, s12, 31
	v_cmp_lt_i64_e32 vcc, s[14:15], v[0:1]
	s_lshl_b64 s[14:15], s[12:13], 19
	s_add_u32 s14, s25, s14
	s_addc_u32 s15, s26, s15
	s_and_b64 s[16:17], vcc, exec
	s_cselect_b32 s13, s15, s19
	s_cselect_b32 s48, s14, s18
	s_ashr_i32 s11, s10, 31
	s_lshl_b64 s[16:17], s[10:11], 19
	s_add_u32 s16, s27, s16
	s_addc_u32 s17, s28, s17
	s_and_b64 s[22:23], vcc, exec
	s_cselect_b32 s11, s17, s21
	s_cselect_b32 s49, s16, s20
	s_add_u32 s18, s18, 0x40080
	s_addc_u32 s19, s19, 0
	s_add_u32 s50, s20, 0x100
	s_addc_u32 s51, s21, 0
	s_mov_b32 s52, -2
	s_add_u32 s0, s18, 0xfffc0080
	s_addc_u32 s1, s19, -1
	s_add_i32 s54, 0, 0x10000
	v_add_u32_e32 v78, s54, v161
	ds_read_b128 v[66:69], v78
	ds_read_b128 v[70:73], v78 offset:1024
	ds_read_b128 v[74:77], v78 offset:2048
	ds_read_b128 v[78:81], v78 offset:3072
	s_cmp_eq_u32 s52, 12
	s_cselect_b32 s23, s13, s1
	s_cselect_b32 s22, s48, s0
	s_cselect_b32 s21, s11, s51
	s_cselect_b32 s20, s49, s50
	v_lshl_add_u64 v[156:157], s[18:19], 0, v[152:153]
	s_add_i32 m0, s30, 0xc000
	ds_read_b128 v[168:171], v165
	ds_read_b128 v[172:175], v165 offset:1024
	ds_read_b128 v[190:193], v165 offset:2048
	ds_read_b128 v[194:197], v165 offset:3072
	ds_read_b128 v[198:201], v165 offset:4096
	ds_read_b128 v[202:205], v165 offset:5120
	ds_read_b128 v[206:209], v165 offset:6144
	ds_read_b128 v[210:213], v165 offset:7168
	global_load_lds_dwordx4 v[156:157], off
	s_add_i32 m0, s30, 0xe000
	v_lshl_add_u64 v[156:157], s[18:19], 0, v[154:155]
	global_load_lds_dwordx4 v[156:157], off
	s_waitcnt lgkmcnt(8)
	s_barrier
	s_waitcnt lgkmcnt(0)
	v_mfma_f32_16x16x32_bf16 v[142:145], v[66:69], v[168:171], 0
	v_mfma_f32_16x16x32_bf16 v[138:141], v[74:77], v[168:171], 0
	v_mfma_f32_16x16x32_bf16 v[126:129], v[66:69], v[190:193], 0
	v_mfma_f32_16x16x32_bf16 v[122:125], v[74:77], v[190:193], 0
	v_mfma_f32_16x16x32_bf16 v[110:113], v[66:69], v[198:201], 0
	v_mfma_f32_16x16x32_bf16 v[106:109], v[74:77], v[198:201], 0
	v_mfma_f32_16x16x32_bf16 v[94:97], v[66:69], v[206:209], 0
	v_mfma_f32_16x16x32_bf16 v[90:93], v[74:77], v[206:209], 0
	v_mfma_f32_16x16x32_bf16 v[142:145], v[70:73], v[172:175], v[142:145]
	v_mfma_f32_16x16x32_bf16 v[138:141], v[78:81], v[172:175], v[138:141]
	v_mfma_f32_16x16x32_bf16 v[126:129], v[70:73], v[194:197], v[126:129]
	v_mfma_f32_16x16x32_bf16 v[122:125], v[78:81], v[194:197], v[122:125]
	v_mfma_f32_16x16x32_bf16 v[110:113], v[70:73], v[202:205], v[110:113]
	v_mfma_f32_16x16x32_bf16 v[106:109], v[78:81], v[202:205], v[106:109]
	v_mfma_f32_16x16x32_bf16 v[94:97], v[70:73], v[210:213], v[94:97]
	v_mfma_f32_16x16x32_bf16 v[90:93], v[78:81], v[210:213], v[90:93]
	s_barrier
	s_add_i32 s0, 0, 0x14000
	v_add_u32_e32 v156, s0, v161
	s_add_i32 s1, s54, s29
	ds_read_b128 v[214:217], v156
	ds_read_b128 v[218:221], v156 offset:1024
	ds_read_b128 v[222:225], v156 offset:2048
	ds_read_b128 v[242:245], v156 offset:3072
	v_lshl_add_u64 v[156:157], s[20:21], 0, v[4:5]
	s_mov_b32 m0, s1
	v_lshl_add_u64 v[176:177], s[20:21], 0, v[146:147]
	global_load_lds_dwordx4 v[156:157], off
	s_add_i32 m0, s1, 0x2000
	s_nop 0
	global_load_lds_dwordx4 v[176:177], off
	s_barrier
	s_waitcnt lgkmcnt(0)
	v_mfma_f32_16x16x32_bf16 v[134:137], v[214:217], v[168:171], 0
	v_mfma_f32_16x16x32_bf16 v[130:133], v[222:225], v[168:171], 0
	v_mfma_f32_16x16x32_bf16 v[118:121], v[214:217], v[190:193], 0
	v_mfma_f32_16x16x32_bf16 v[114:117], v[222:225], v[190:193], 0
	v_mfma_f32_16x16x32_bf16 v[102:105], v[214:217], v[198:201], 0
	v_mfma_f32_16x16x32_bf16 v[98:101], v[222:225], v[198:201], 0
	v_mfma_f32_16x16x32_bf16 v[86:89], v[214:217], v[206:209], 0
	v_mfma_f32_16x16x32_bf16 v[82:85], v[222:225], v[206:209], 0
	v_mfma_f32_16x16x32_bf16 v[134:137], v[218:221], v[172:175], v[134:137]
	v_mfma_f32_16x16x32_bf16 v[130:133], v[242:245], v[172:175], v[130:133]
	v_mfma_f32_16x16x32_bf16 v[118:121], v[218:221], v[194:197], v[118:121]
	v_mfma_f32_16x16x32_bf16 v[114:117], v[242:245], v[194:197], v[114:117]
	v_mfma_f32_16x16x32_bf16 v[102:105], v[218:221], v[202:205], v[102:105]
	v_mfma_f32_16x16x32_bf16 v[98:101], v[242:245], v[202:205], v[98:101]
	v_mfma_f32_16x16x32_bf16 v[86:89], v[218:221], v[210:213], v[86:89]
	v_mfma_f32_16x16x32_bf16 v[82:85], v[242:245], v[210:213], v[82:85]
	s_mov_b32 m0, s30
	v_lshl_add_u64 v[186:187], s[22:23], 0, v[150:151]
	s_barrier
	ds_read_b128 v[168:171], v165 offset:16384
	ds_read_b128 v[172:175], v165 offset:17408
	ds_read_b128 v[190:193], v165 offset:18432
	ds_read_b128 v[194:197], v165 offset:19456
	ds_read_b128 v[198:201], v165 offset:20480
	ds_read_b128 v[202:205], v165 offset:21504
	ds_read_b128 v[206:209], v165 offset:22528
	ds_read_b128 v[210:213], v165 offset:23552
	global_load_lds_dwordx4 v[186:187], off
	s_mov_b32 m0, s31
	v_lshl_add_u64 v[226:227], s[22:23], 0, v[148:149]
	global_load_lds_dwordx4 v[226:227], off
	s_barrier
	s_waitcnt lgkmcnt(0)
	v_mfma_f32_16x16x32_bf16 v[62:65], v[66:69], v[168:171], 0
	v_mfma_f32_16x16x32_bf16 v[58:61], v[74:77], v[168:171], 0
	v_mfma_f32_16x16x32_bf16 v[46:49], v[66:69], v[190:193], 0
	v_mfma_f32_16x16x32_bf16 v[42:45], v[74:77], v[190:193], 0
	v_mfma_f32_16x16x32_bf16 v[30:33], v[66:69], v[198:201], 0
	v_mfma_f32_16x16x32_bf16 v[26:29], v[74:77], v[198:201], 0
	v_mfma_f32_16x16x32_bf16 v[14:17], v[66:69], v[206:209], 0
	v_mfma_f32_16x16x32_bf16 v[10:13], v[74:77], v[206:209], 0
	v_mfma_f32_16x16x32_bf16 v[62:65], v[70:73], v[172:175], v[62:65]
	v_mfma_f32_16x16x32_bf16 v[58:61], v[78:81], v[172:175], v[58:61]
	v_mfma_f32_16x16x32_bf16 v[46:49], v[70:73], v[194:197], v[46:49]
	v_mfma_f32_16x16x32_bf16 v[42:45], v[78:81], v[194:197], v[42:45]
	v_mfma_f32_16x16x32_bf16 v[30:33], v[70:73], v[202:205], v[30:33]
	v_mfma_f32_16x16x32_bf16 v[26:29], v[78:81], v[202:205], v[26:29]
	v_mfma_f32_16x16x32_bf16 v[14:17], v[70:73], v[210:213], v[14:17]
	v_mfma_f32_16x16x32_bf16 v[10:13], v[78:81], v[210:213], v[10:13]
	s_barrier
; #define PG8_STAGE(bufoff, gbase, voff) do { _Pragma("unroll") for (int _i = 0; _i < 2; ++_i) \
;         __builtin_amdgcn_global_load_lds((const unsigned*)((const char*)(gbase) + (voff)[_i]), (LAS unsigned*)(lds + (bufoff) + ldsw + _i * 8192), 16, 0, 0); } while (0)
; #define PG8_LDA(dst, b, h) do { _Pragma("unroll") for (int m = 0; m < 4; ++m) _Pragma("unroll") for (int k = 0; k < 2; ++k) dst[m][k] = *(const LAS bf16x8*)(lds + PG8_SA(b, h) + aoff + m * 2048 + k * 1024); } while (0)
; #define PG8_LDB(dst, b, h) do { _Pragma("unroll") for (int n = 0; n < 2; ++n) _Pragma("unroll") for (int k = 0; k < 2; ++k) dst[n][k] = *(const LAS bf16x8*)(lds + PG8_SB(b, h) + boff + n * 2048 + k * 1024); } while (0)
; #define PG8_MMA(ai, bj, At, Bt) do { __builtin_amdgcn_s_setprio(1); _Pragma("unroll") for (int m = 0; m < 4; ++m) _Pragma("unroll") for (int n = 0; n < 2; ++n) _Pragma("unroll") for (int k = 0; k < 2; ++k) \
;         acc[ai][bj][m][n] = __builtin_amdgcn_mfma_f32_16x16x32_bf16(Bt[n][k], At[m][k], acc[ai][bj][m][n], 0, 0, 0); __builtin_amdgcn_s_setprio(0); } while (0)
; #define PG8_WAIT_V(n) asm volatile("s_waitcnt vmcnt(" #n ")" ::: "memory")
; #define PG8_WAIT_L(n) asm volatile("s_waitcnt lgkmcnt(" #n ")" ::: "memory")
; #define PG8_BAR __builtin_amdgcn_s_barrier()
; #define PG8_SCHED __builtin_amdgcn_sched_barrier(0)
; template <class Epi>
; __device__ __forceinline__ void gemm_phase(LAS unsigned char* lds, const Gemm g, const StaticOrder& S, const Epi& E) {
;     ...
;             PG8_STAGE(PG8_SB(0, 1), b2 + hstep, voffB);
;             PG8_WAIT_V(6); PG8_BAR; PG8_MMA(1, 1, At, B1); PG8_BAR;
;             PG8_LDB(B0, 1, 0); PG8_SCHED; PG8_LDA(At, 1, 0); PG8_STAGE(PG8_SA(0, 1), a2 + hstep, voffA);
;             PG8_WAIT_L(8); PG8_BAR; PG8_WAIT_L(0); PG8_MMA(0, 0, At, B0); PG8_BAR; PG8_SCHED;
;             PG8_LDB(B1, 1, 1); PG8_STAGE(PG8_SB(1, 0), b3, voffB);
	s_add_u32 s54, s20, 0x40000
	s_addc_u32 s55, s21, 0
	s_add_i32 s0, s0, s29
	s_mov_b32 m0, s0
	v_lshl_add_u64 v[66:67], s[54:55], 0, v[4:5]
	global_load_lds_dwordx4 v[66:67], off
	s_add_i32 m0, s0, 0x2000
	v_lshl_add_u64 v[66:67], s[54:55], 0, v[146:147]
	global_load_lds_dwordx4 v[66:67], off
	s_waitcnt vmcnt(6)
	s_barrier
	v_mfma_f32_16x16x32_bf16 v[54:57], v[214:217], v[168:171], 0
	v_mfma_f32_16x16x32_bf16 v[50:53], v[222:225], v[168:171], 0
	v_mfma_f32_16x16x32_bf16 v[38:41], v[214:217], v[190:193], 0
	v_mfma_f32_16x16x32_bf16 v[34:37], v[222:225], v[190:193], 0
	v_mfma_f32_16x16x32_bf16 v[22:25], v[214:217], v[198:201], 0
	v_mfma_f32_16x16x32_bf16 v[18:21], v[222:225], v[198:201], 0
	v_mfma_f32_16x16x32_bf16 v[6:9], v[214:217], v[206:209], 0
	v_mfma_f32_16x16x32_bf16 v[0:3], v[222:225], v[206:209], 0
	v_mfma_f32_16x16x32_bf16 v[54:57], v[218:221], v[172:175], v[54:57]
	v_mfma_f32_16x16x32_bf16 v[50:53], v[242:245], v[172:175], v[50:53]
	v_mfma_f32_16x16x32_bf16 v[38:41], v[218:221], v[194:197], v[38:41]
	v_mfma_f32_16x16x32_bf16 v[34:37], v[242:245], v[194:197], v[34:37]
	v_mfma_f32_16x16x32_bf16 v[22:25], v[218:221], v[202:205], v[22:25]
	v_mfma_f32_16x16x32_bf16 v[18:21], v[242:245], v[202:205], v[18:21]
	v_mfma_f32_16x16x32_bf16 v[6:9], v[218:221], v[210:213], v[6:9]
	v_mfma_f32_16x16x32_bf16 v[0:3], v[242:245], v[210:213], v[0:3]
	s_add_i32 s0, 0, 0x18000
	v_add_u32_e32 v78, s0, v161
	s_barrier
	ds_read_b128 v[66:69], v78
	ds_read_b128 v[70:73], v78 offset:1024
	ds_read_b128 v[74:77], v78 offset:2048
	ds_read_b128 v[78:81], v78 offset:3072
	s_add_u32 s22, s22, 0x40000
	s_addc_u32 s23, s23, 0
	s_mov_b32 m0, s34
	v_lshl_add_u64 v[214:215], s[22:23], 0, v[150:151]
	ds_read_b128 v[168:171], v165 offset:32768
	ds_read_b128 v[172:175], v165 offset:33792
	ds_read_b128 v[190:193], v165 offset:34816
	ds_read_b128 v[194:197], v165 offset:35840
	ds_read_b128 v[198:201], v165 offset:36864
	ds_read_b128 v[202:205], v165 offset:37888
	ds_read_b128 v[206:209], v165 offset:38912
	ds_read_b128 v[210:213], v165 offset:39936
	global_load_lds_dwordx4 v[214:215], off
	s_mov_b32 m0, s35
	v_lshl_add_u64 v[214:215], s[22:23], 0, v[148:149]
	global_load_lds_dwordx4 v[214:215], off
	s_waitcnt lgkmcnt(8)
	s_barrier
	s_waitcnt lgkmcnt(0)
	v_mfma_f32_16x16x32_bf16 v[142:145], v[66:69], v[168:171], v[142:145]
	v_mfma_f32_16x16x32_bf16 v[138:141], v[74:77], v[168:171], v[138:141]
	v_mfma_f32_16x16x32_bf16 v[126:129], v[66:69], v[190:193], v[126:129]
	v_mfma_f32_16x16x32_bf16 v[122:125], v[74:77], v[190:193], v[122:125]
	v_mfma_f32_16x16x32_bf16 v[110:113], v[66:69], v[198:201], v[110:113]
	v_mfma_f32_16x16x32_bf16 v[106:109], v[74:77], v[198:201], v[106:109]
	v_mfma_f32_16x16x32_bf16 v[94:97], v[66:69], v[206:209], v[94:97]
	v_mfma_f32_16x16x32_bf16 v[90:93], v[74:77], v[206:209], v[90:93]
	v_mfma_f32_16x16x32_bf16 v[142:145], v[70:73], v[172:175], v[142:145]
	v_mfma_f32_16x16x32_bf16 v[138:141], v[78:81], v[172:175], v[138:141]
	v_mfma_f32_16x16x32_bf16 v[126:129], v[70:73], v[194:197], v[126:129]
	v_mfma_f32_16x16x32_bf16 v[122:125], v[78:81], v[194:197], v[122:125]
	v_mfma_f32_16x16x32_bf16 v[110:113], v[70:73], v[202:205], v[110:113]
	v_mfma_f32_16x16x32_bf16 v[106:109], v[78:81], v[202:205], v[106:109]
	v_mfma_f32_16x16x32_bf16 v[94:97], v[70:73], v[210:213], v[94:97]
	v_mfma_f32_16x16x32_bf16 v[90:93], v[78:81], v[210:213], v[90:93]
	s_barrier
	s_add_i32 s1, 0, 0x1c000
	s_add_i32 s0, s0, s29
	v_add_u32_e32 v158, s1, v161
	v_lshl_add_u64 v[156:157], v[156:157], 0, s[86:87]
	s_mov_b32 m0, s0
	ds_read_b128 v[214:217], v158
	ds_read_b128 v[218:221], v158 offset:1024
	ds_read_b128 v[222:225], v158 offset:2048
	ds_read_b128 v[242:245], v158 offset:3072
	global_load_lds_dwordx4 v[156:157], off
	s_add_i32 m0, s0, 0x2000
	v_lshl_add_u64 v[156:157], v[176:177], 0, s[86:87]
	global_load_lds_dwordx4 v[156:157], off
	s_barrier
; #define PG8_STAGE(bufoff, gbase, voff) do { _Pragma("unroll") for (int _i = 0; _i < 2; ++_i) \
;         __builtin_amdgcn_global_load_lds((const unsigned*)((const char*)(gbase) + (voff)[_i]), (LAS unsigned*)(lds + (bufoff) + ldsw + _i * 8192), 16, 0, 0); } while (0)
; #define PG8_LDA(dst, b, h) do { _Pragma("unroll") for (int m = 0; m < 4; ++m) _Pragma("unroll") for (int k = 0; k < 2; ++k) dst[m][k] = *(const LAS bf16x8*)(lds + PG8_SA(b, h) + aoff + m * 2048 + k * 1024); } while (0)
; #define PG8_LDB(dst, b, h) do { _Pragma("unroll") for (int n = 0; n < 2; ++n) _Pragma("unroll") for (int k = 0; k < 2; ++k) dst[n][k] = *(const LAS bf16x8*)(lds + PG8_SB(b, h) + boff + n * 2048 + k * 1024); } while (0)
; #define PG8_MMA(ai, bj, At, Bt) do { __builtin_amdgcn_s_setprio(1); _Pragma("unroll") for (int m = 0; m < 4; ++m) _Pragma("unroll") for (int n = 0; n < 2; ++n) _Pragma("unroll") for (int k = 0; k < 2; ++k) \
;         acc[ai][bj][m][n] = __builtin_amdgcn_mfma_f32_16x16x32_bf16(Bt[n][k], At[m][k], acc[ai][bj][m][n], 0, 0, 0); __builtin_amdgcn_s_setprio(0); } while (0)
; #define PG8_WAIT_V(n) asm volatile("s_waitcnt vmcnt(" #n ")" ::: "memory")
; #define PG8_WAIT_L(n) asm volatile("s_waitcnt lgkmcnt(" #n ")" ::: "memory")
; #define PG8_BAR __builtin_amdgcn_s_barrier()
; #define PG8_SCHED __builtin_amdgcn_sched_barrier(0)
; template <class Epi>
; __device__ __forceinline__ void gemm_phase(LAS unsigned char* lds, const Gemm g, const StaticOrder& S, const Epi& E) {
;     ...
;         for (int t = 0; t < nt; t += 2) {
;     ...
;             PG8_LDB(B1, 1, 1); PG8_STAGE(PG8_SB(1, 0), b3, voffB);
;             PG8_BAR; PG8_WAIT_L(0); PG8_MMA(0, 1, At, B1); PG8_BAR;
;             PG8_LDA(At, 1, 1); PG8_STAGE(PG8_SA(1, 0), a3, voffA);
;             PG8_BAR; PG8_WAIT_L(0); PG8_MMA(1, 0, At, B0); PG8_BAR; PG8_SCHED;
;             PG8_STAGE(PG8_SB(1, 1), b3 + hstep, voffB);
;             PG8_WAIT_V(6); PG8_BAR; PG8_MMA(1, 1, At, B1); PG8_BAR;
	s_waitcnt lgkmcnt(0)
	v_mfma_f32_16x16x32_bf16 v[134:137], v[214:217], v[168:171], v[134:137]
	v_mfma_f32_16x16x32_bf16 v[130:133], v[222:225], v[168:171], v[130:133]
	v_mfma_f32_16x16x32_bf16 v[118:121], v[214:217], v[190:193], v[118:121]
	v_mfma_f32_16x16x32_bf16 v[114:117], v[222:225], v[190:193], v[114:117]
	v_mfma_f32_16x16x32_bf16 v[102:105], v[214:217], v[198:201], v[102:105]
	v_mfma_f32_16x16x32_bf16 v[98:101], v[222:225], v[198:201], v[98:101]
	v_mfma_f32_16x16x32_bf16 v[86:89], v[214:217], v[206:209], v[86:89]
	v_mfma_f32_16x16x32_bf16 v[82:85], v[222:225], v[206:209], v[82:85]
	v_mfma_f32_16x16x32_bf16 v[134:137], v[218:221], v[172:175], v[134:137]
	v_mfma_f32_16x16x32_bf16 v[130:133], v[242:245], v[172:175], v[130:133]
	v_mfma_f32_16x16x32_bf16 v[118:121], v[218:221], v[194:197], v[118:121]
	v_mfma_f32_16x16x32_bf16 v[114:117], v[242:245], v[194:197], v[114:117]
	v_mfma_f32_16x16x32_bf16 v[102:105], v[218:221], v[202:205], v[102:105]
	v_mfma_f32_16x16x32_bf16 v[98:101], v[242:245], v[202:205], v[98:101]
	v_mfma_f32_16x16x32_bf16 v[86:89], v[218:221], v[210:213], v[86:89]
	v_mfma_f32_16x16x32_bf16 v[82:85], v[242:245], v[210:213], v[82:85]
	s_mov_b32 m0, s38
	v_lshl_add_u64 v[156:157], v[186:187], 0, s[86:87]
	s_barrier
	ds_read_b128 v[168:171], v165 offset:49152
	ds_read_b128 v[172:175], v165 offset:50176
	ds_read_b128 v[190:193], v165 offset:51200
	ds_read_b128 v[194:197], v165 offset:52224
	ds_read_b128 v[198:201], v165 offset:53248
	ds_read_b128 v[202:205], v165 offset:54272
	ds_read_b128 v[206:209], v165 offset:55296
	ds_read_b128 v[210:213], v165 offset:56320
	global_load_lds_dwordx4 v[156:157], off
	s_mov_b32 m0, s39
	v_lshl_add_u64 v[156:157], v[226:227], 0, s[86:87]
	global_load_lds_dwordx4 v[156:157], off
	s_barrier
	s_waitcnt lgkmcnt(0)
	v_mfma_f32_16x16x32_bf16 v[62:65], v[66:69], v[168:171], v[62:65]
	v_mfma_f32_16x16x32_bf16 v[58:61], v[74:77], v[168:171], v[58:61]
	v_mfma_f32_16x16x32_bf16 v[46:49], v[66:69], v[190:193], v[46:49]
	v_mfma_f32_16x16x32_bf16 v[42:45], v[74:77], v[190:193], v[42:45]
	v_mfma_f32_16x16x32_bf16 v[30:33], v[66:69], v[198:201], v[30:33]
	v_mfma_f32_16x16x32_bf16 v[26:29], v[74:77], v[198:201], v[26:29]
	v_mfma_f32_16x16x32_bf16 v[14:17], v[66:69], v[206:209], v[14:17]
	v_mfma_f32_16x16x32_bf16 v[10:13], v[74:77], v[206:209], v[10:13]
	v_mfma_f32_16x16x32_bf16 v[62:65], v[70:73], v[172:175], v[62:65]
	v_mfma_f32_16x16x32_bf16 v[58:61], v[78:81], v[172:175], v[58:61]
	v_mfma_f32_16x16x32_bf16 v[46:49], v[70:73], v[194:197], v[46:49]
	v_mfma_f32_16x16x32_bf16 v[42:45], v[78:81], v[194:197], v[42:45]
	v_mfma_f32_16x16x32_bf16 v[30:33], v[70:73], v[202:205], v[30:33]
	v_mfma_f32_16x16x32_bf16 v[26:29], v[78:81], v[202:205], v[26:29]
	v_mfma_f32_16x16x32_bf16 v[14:17], v[70:73], v[210:213], v[14:17]
	v_mfma_f32_16x16x32_bf16 v[10:13], v[78:81], v[210:213], v[10:13]
	s_barrier
	s_add_u32 s20, s20, 0x40080
	s_addc_u32 s21, s21, 0
	s_add_i32 s0, s1, s29
	s_mov_b32 m0, s0
	v_lshl_add_u64 v[66:67], s[20:21], 0, v[4:5]
	global_load_lds_dwordx4 v[66:67], off
	s_add_i32 m0, s0, 0x2000
	v_lshl_add_u64 v[66:67], s[20:21], 0, v[146:147]
	global_load_lds_dwordx4 v[66:67], off
	s_waitcnt vmcnt(6)
	s_barrier
	v_mfma_f32_16x16x32_bf16 v[54:57], v[214:217], v[168:171], v[54:57]
	v_mfma_f32_16x16x32_bf16 v[50:53], v[222:225], v[168:171], v[50:53]
	v_mfma_f32_16x16x32_bf16 v[38:41], v[214:217], v[190:193], v[38:41]
	v_mfma_f32_16x16x32_bf16 v[34:37], v[222:225], v[190:193], v[34:37]
	v_mfma_f32_16x16x32_bf16 v[22:25], v[214:217], v[198:201], v[22:25]
	v_mfma_f32_16x16x32_bf16 v[18:21], v[222:225], v[198:201], v[18:21]
	v_mfma_f32_16x16x32_bf16 v[6:9], v[214:217], v[206:209], v[6:9]
	v_mfma_f32_16x16x32_bf16 v[0:3], v[222:225], v[206:209], v[0:3]
	v_mfma_f32_16x16x32_bf16 v[54:57], v[218:221], v[172:175], v[54:57]
	v_mfma_f32_16x16x32_bf16 v[50:53], v[242:245], v[172:175], v[50:53]
	v_mfma_f32_16x16x32_bf16 v[38:41], v[218:221], v[194:197], v[38:41]
	v_mfma_f32_16x16x32_bf16 v[34:37], v[242:245], v[194:197], v[34:37]
	v_mfma_f32_16x16x32_bf16 v[22:25], v[218:221], v[202:205], v[22:25]
	v_mfma_f32_16x16x32_bf16 v[18:21], v[242:245], v[202:205], v[18:21]
	v_mfma_f32_16x16x32_bf16 v[6:9], v[218:221], v[210:213], v[6:9]
	v_mfma_f32_16x16x32_bf16 v[0:3], v[242:245], v[210:213], v[0:3]
	s_add_i32 s52, s52, 2
	s_add_u32 s18, s18, 0x100
	s_addc_u32 s19, s19, 0
	s_add_u32 s50, s50, 0x100
	s_addc_u32 s51, s51, 0
	s_cmp_gt_u32 s52, 13
	s_barrier
	s_cbranch_scc1 .Lpeel_exit_1

; __device__ __forceinline__ unsigned cvt_pk_bf16(float lo, float hi) { unsigned r; asm volatile("s_nop 0\n\tv_cvt_pk_bf16_f32 %0, %1, %2" : "=v"(r) : "v"(lo), "v"(hi)); return r; }
; __device__ __forceinline__ float siluf_(float x) { return x * __builtin_amdgcn_rcpf(1.f + __expf(-x)); }
; __device__ __forceinline__ void load_rstd(const float* ss, int row0, f32x4& ra, f32x4& rb) {
;     float t[8];
; #pragma unroll
;     for (int i = 0; i < 8; ++i) t[i] = ss[row0 + (i >> 2) * 128 + (i & 3) * 16];
; #pragma unroll
;     for (int i = 0; i < 4; ++i) { ra[i] = __builtin_amdgcn_rsqf(t[i] * (1.f / 1024.f) + 1e-6f); rb[i] = __builtin_amdgcn_rsqf(t[4 + i] * (1.f / 1024.f) + 1e-6f); }
; }
;     __device__ __forceinline__ void operator()(const f32x4 (&acc)[2][2][4][2], const Unit& u, int wr, int wc, int fr, int fq) const {
;         const int row0 = u.pm * 256 + wr * 64 + fr, hc0 = u.pn * 128 + wc * 32 + fq * 8;
;         const float* swp = sw + (size_t)(u.pm >> 3) * 5632 + u.pn * 256 + wc * 32 + 8 * fq;
;         f32x4 ra, rb; load_rstd(ss, row0, ra, rb);
;         const f32x4 sg0 = *(const f32x4*)(swp), sg1 = *(const f32x4*)(swp + 4), su0 = *(const f32x4*)(swp + 128), su1 = *(const f32x4*)(swp + 132);
; #pragma unroll
;         for (int ai = 0; ai < 2; ++ai)
; #pragma unroll
;             for (int m = 0; m < 4; ++m) { const int r = row0 + ai * 128 + m * 16;
;                 const float rstd = ai ? rb[m] : ra[m];
;                 const f32x4 g0 = acc[ai][0][m][0] * rstd + sg0, g1 = acc[ai][0][m][1] * rstd + sg1, u0 = acc[ai][1][m][0] * rstd + su0, u1 = acc[ai][1][m][1] * rstd + su1;
;                 uint4 st; st.x = cvt_pk_bf16(siluf_(g0[0]) * u0[0], siluf_(g0[1]) * u0[1]); st.y = cvt_pk_bf16(siluf_(g0[2]) * u0[2], siluf_(g0[3]) * u0[3]);
;                 st.z = cvt_pk_bf16(siluf_(g1[0]) * u1[0], siluf_(g1[1]) * u1[1]); st.w = cvt_pk_bf16(siluf_(g1[2]) * u1[2], siluf_(g1[3]) * u1[3]);
;                 *(uint4*)(hid + (size_t)r * DFF + hc0) = st; }
.Lpeel_exit_1:
	v_lshl_add_u32 v156, s43, 8, v159
	v_ashrrev_i32_e32 v157, 31, v156
	v_lshl_add_u64 v[66:67], v[156:157], 2, s[8:9]
	global_load_dword v190, v[66:67], off
	global_load_dword v191, v[66:67], off offset:64
	global_load_dword v192, v[66:67], off offset:128
	global_load_dword v193, v[66:67], off offset:192
	global_load_dword v194, v[66:67], off offset:512
	global_load_dword v195, v[66:67], off offset:576
	global_load_dword v196, v[66:67], off offset:640
	global_load_dword v197, v[66:67], off offset:704
	s_ashr_i32 s0, s43, 3
	s_mul_hi_i32 s1, s0, 0x5800
	s_mulk_i32 s0, 0x5800
	s_add_u32 s0, s36, s0
	s_addc_u32 s1, s37, s1
	s_lshl_b32 s18, s42, 8
	s_ashr_i32 s19, s18, 31
	s_lshl_b64 s[18:19], s[18:19], 2
	s_add_u32 s0, s0, s18
	s_addc_u32 s1, s1, s19
	s_add_u32 s18, s0, s41
	s_addc_u32 s19, s1, 0
	v_lshl_or_b32 v170, s42, 7, v163
	v_ashrrev_i32_e32 v171, 31, v170
	global_load_dwordx4 v[66:69], v167, s[18:19] offset:16
	global_load_dwordx4 v[74:77], v167, s[18:19]
	global_load_dwordx4 v[70:73], v167, s[18:19] offset:528
	global_load_dwordx4 v[78:81], v167, s[18:19] offset:512
	s_and_b64 vcc, exec, s[4:5]
	s_mov_b32 s42, s10
	s_mov_b32 s43, s12
	s_mov_b64 s[20:21], s[16:17]
	s_waitcnt vmcnt(4)
	v_fmamk_f32 v198, v190, 0x3a800000, v229
	v_rsq_f32_e32 v174, v198
	v_fmamk_f32 v198, v194, 0x3a800000, v229
	v_rsq_f32_e32 v164, v198
	v_fmamk_f32 v198, v191, 0x3a800000, v229
	v_rsq_f32_e32 v172, v198
	v_fmamk_f32 v198, v195, 0x3a800000, v229
	v_rsq_f32_e32 v162, v198
	v_fmamk_f32 v198, v192, 0x3a800000, v229
	v_rsq_f32_e32 v168, v198
	v_fmamk_f32 v198, v196, 0x3a800000, v229
	v_rsq_f32_e32 v160, v198
	v_fmamk_f32 v198, v193, 0x3a800000, v229
	v_fmamk_f32 v199, v197, 0x3a800000, v229
	v_rsq_f32_e32 v166, v198
	v_rsq_f32_e32 v158, v199
	s_waitcnt vmcnt(0)
	v_pk_fma_f32 v[138:139], v[138:139], v[174:175], v[66:67] op_sel_hi:[1,0,1]
	v_pk_fma_f32 v[142:143], v[142:143], v[174:175], v[74:75] op_sel_hi:[1,0,1]
	v_pk_fma_f32 v[144:145], v[144:145], v[174:175], v[76:77] op_sel_hi:[1,0,1]
	v_pk_fma_f32 v[176:177], v[134:135], v[174:175], v[78:79] op_sel_hi:[1,0,1]
	v_pk_fma_f32 v[134:135], v[132:133], v[174:175], v[72:73] op_sel_hi:[1,0,1]
	v_pk_fma_f32 v[132:133], v[130:131], v[174:175], v[70:71] op_sel_hi:[1,0,1]
	v_mul_f32_e32 v130, 0xbfb8aa3b, v142
	v_mul_f32_e32 v131, 0xbfb8aa3b, v143
	v_exp_f32_e32 v130, v130
	v_exp_f32_e32 v131, v131
	v_pk_fma_f32 v[136:137], v[136:137], v[174:175], v[80:81] op_sel_hi:[1,0,1]
	v_pk_fma_f32 v[140:141], v[140:141], v[174:175], v[68:69] op_sel_hi:[1,0,1]
	v_add_f32_e32 v130, 1.0, v130
	v_add_f32_e32 v131, 1.0, v131
	v_rcp_f32_e32 v130, v130
	v_rcp_f32_e32 v131, v131
	v_pk_fma_f32 v[126:127], v[126:127], v[172:173], v[74:75] op_sel_hi:[1,0,1]
	v_pk_fma_f32 v[118:119], v[118:119], v[172:173], v[78:79] op_sel_hi:[1,0,1]
	v_mul_f32_e32 v130, v142, v130
	v_mul_f32_e32 v131, v143, v131
	v_mul_f32_e32 v130, v176, v130
	v_mul_f32_e32 v131, v177, v131
	s_nop 0
	v_cvt_pk_bf16_f32 v130, v130, v131
	v_mul_f32_e32 v131, 0xbfb8aa3b, v144
	v_exp_f32_e32 v131, v131
	v_pk_fma_f32 v[128:129], v[128:129], v[172:173], v[76:77] op_sel_hi:[1,0,1]
	v_pk_fma_f32 v[120:121], v[120:121], v[172:173], v[80:81] op_sel_hi:[1,0,1]
	v_pk_fma_f32 v[122:123], v[122:123], v[172:173], v[66:67] op_sel_hi:[1,0,1]
	v_add_f32_e32 v131, 1.0, v131
	v_rcp_f32_e32 v131, v131
	v_pk_fma_f32 v[124:125], v[124:125], v[172:173], v[68:69] op_sel_hi:[1,0,1]
	v_pk_fma_f32 v[110:111], v[110:111], v[168:169], v[74:75] op_sel_hi:[1,0,1]
	v_pk_fma_f32 v[102:103], v[102:103], v[168:169], v[78:79] op_sel_hi:[1,0,1]
	v_mul_f32_e32 v131, v144, v131
	v_mul_f32_e32 v131, v136, v131
	v_mul_f32_e32 v136, 0xbfb8aa3b, v145
	v_exp_f32_e32 v136, v136
	v_pk_fma_f32 v[112:113], v[112:113], v[168:169], v[76:77] op_sel_hi:[1,0,1]
	v_pk_fma_f32 v[104:105], v[104:105], v[168:169], v[80:81] op_sel_hi:[1,0,1]
	v_pk_fma_f32 v[106:107], v[106:107], v[168:169], v[66:67] op_sel_hi:[1,0,1]
	v_add_f32_e32 v136, 1.0, v136
	v_rcp_f32_e32 v136, v136
	v_pk_fma_f32 v[108:109], v[108:109], v[168:169], v[68:69] op_sel_hi:[1,0,1]
	v_pk_fma_f32 v[94:95], v[94:95], v[166:167], v[74:75] op_sel_hi:[1,0,1]
	v_pk_fma_f32 v[86:87], v[86:87], v[166:167], v[78:79] op_sel_hi:[1,0,1]
	v_mul_f32_e32 v136, v145, v136
	v_mul_f32_e32 v136, v137, v136
	s_nop 0
	v_cvt_pk_bf16_f32 v131, v131, v136
	v_mul_f32_e32 v136, 0xbfb8aa3b, v138
	v_exp_f32_e32 v136, v136
	v_pk_fma_f32 v[96:97], v[96:97], v[166:167], v[76:77] op_sel_hi:[1,0,1]
	v_pk_fma_f32 v[88:89], v[88:89], v[166:167], v[80:81] op_sel_hi:[1,0,1]
	v_pk_fma_f32 v[90:91], v[90:91], v[166:167], v[66:67] op_sel_hi:[1,0,1]
	v_add_f32_e32 v136, 1.0, v136
	v_rcp_f32_e32 v136, v136
	v_pk_fma_f32 v[92:93], v[92:93], v[166:167], v[68:69] op_sel_hi:[1,0,1]
	v_pk_fma_f32 v[62:63], v[62:63], v[164:165], v[74:75] op_sel_hi:[1,0,1]
	v_pk_fma_f32 v[54:55], v[54:55], v[164:165], v[78:79] op_sel_hi:[1,0,1]
	v_mul_f32_e32 v136, v138, v136
	v_mul_f32_e32 v132, v132, v136
	v_mul_f32_e32 v136, 0xbfb8aa3b, v139
	v_exp_f32_e32 v136, v136
	v_pk_fma_f32 v[64:65], v[64:65], v[164:165], v[76:77] op_sel_hi:[1,0,1]
	v_pk_fma_f32 v[56:57], v[56:57], v[164:165], v[80:81] op_sel_hi:[1,0,1]
	v_pk_fma_f32 v[58:59], v[58:59], v[164:165], v[66:67] op_sel_hi:[1,0,1]
	v_add_f32_e32 v136, 1.0, v136
	v_rcp_f32_e32 v136, v136
	v_pk_fma_f32 v[60:61], v[60:61], v[164:165], v[68:69] op_sel_hi:[1,0,1]
	v_pk_fma_f32 v[46:47], v[46:47], v[162:163], v[74:75] op_sel_hi:[1,0,1]
	v_pk_fma_f32 v[38:39], v[38:39], v[162:163], v[78:79] op_sel_hi:[1,0,1]
	v_mul_f32_e32 v136, v139, v136
	v_mul_f32_e32 v133, v133, v136
	s_nop 0
	v_cvt_pk_bf16_f32 v132, v132, v133
	v_mul_f32_e32 v133, 0xbfb8aa3b, v140
; __device__ __forceinline__ unsigned cvt_pk_bf16(float lo, float hi) { unsigned r; asm volatile("s_nop 0\n\tv_cvt_pk_bf16_f32 %0, %1, %2" : "=v"(r) : "v"(lo), "v"(hi)); return r; }
; __device__ __forceinline__ float siluf_(float x) { return x * __builtin_amdgcn_rcpf(1.f + __expf(-x)); }
;     __device__ __forceinline__ void operator()(const f32x4 (&acc)[2][2][4][2], const Unit& u, int wr, int wc, int fr, int fq) const {
;     ...
;             for (int m = 0; m < 4; ++m) { const int r = row0 + ai * 128 + m * 16;
;                 const float rstd = ai ? rb[m] : ra[m];
;                 const f32x4 g0 = acc[ai][0][m][0] * rstd + sg0, g1 = acc[ai][0][m][1] * rstd + sg1, u0 = acc[ai][1][m][0] * rstd + su0, u1 = acc[ai][1][m][1] * rstd + su1;
;                 uint4 st; st.x = cvt_pk_bf16(siluf_(g0[0]) * u0[0], siluf_(g0[1]) * u0[1]); st.y = cvt_pk_bf16(siluf_(g0[2]) * u0[2], siluf_(g0[3]) * u0[3]);
;                 st.z = cvt_pk_bf16(siluf_(g1[0]) * u1[0], siluf_(g1[1]) * u1[1]); st.w = cvt_pk_bf16(siluf_(g1[2]) * u1[2], siluf_(g1[3]) * u1[3]);
;                 *(uint4*)(hid + (size_t)r * DFF + hc0) = st; }
	v_exp_f32_e32 v133, v133
	v_lshlrev_b64 v[136:137], 1, v[170:171]
	v_pk_fma_f32 v[48:49], v[48:49], v[162:163], v[76:77] op_sel_hi:[1,0,1]
	v_pk_fma_f32 v[40:41], v[40:41], v[162:163], v[80:81] op_sel_hi:[1,0,1]
	v_add_f32_e32 v133, 1.0, v133
	v_rcp_f32_e32 v133, v133
	v_pk_fma_f32 v[42:43], v[42:43], v[162:163], v[66:67] op_sel_hi:[1,0,1]
	v_pk_fma_f32 v[44:45], v[44:45], v[162:163], v[68:69] op_sel_hi:[1,0,1]
	v_pk_fma_f32 v[30:31], v[30:31], v[160:161], v[74:75] op_sel_hi:[1,0,1]
	v_mul_f32_e32 v133, v140, v133
	v_mul_f32_e32 v133, v134, v133
	v_mul_f32_e32 v134, 0xbfb8aa3b, v141
	v_exp_f32_e32 v134, v134
	v_pk_fma_f32 v[22:23], v[22:23], v[160:161], v[78:79] op_sel_hi:[1,0,1]
	v_pk_fma_f32 v[32:33], v[32:33], v[160:161], v[76:77] op_sel_hi:[1,0,1]
	v_pk_fma_f32 v[24:25], v[24:25], v[160:161], v[80:81] op_sel_hi:[1,0,1]
	v_add_f32_e32 v134, 1.0, v134
	v_rcp_f32_e32 v134, v134
	v_pk_fma_f32 v[26:27], v[26:27], v[160:161], v[66:67] op_sel_hi:[1,0,1]
	v_pk_fma_f32 v[28:29], v[28:29], v[160:161], v[68:69] op_sel_hi:[1,0,1]
	v_pk_fma_f32 v[14:15], v[14:15], v[158:159], v[74:75] op_sel_hi:[1,0,1]
	v_mul_f32_e32 v134, v141, v134
	v_mul_f32_e32 v134, v135, v134
	s_nop 0
	v_cvt_pk_bf16_f32 v133, v133, v134
	v_mov_b64_e32 v[134:135], s[6:7]
	v_mad_i64_i32 v[138:139], s[18:19], v156, s74, v[134:135]
	v_lshl_add_u64 v[138:139], v[138:139], 0, v[136:137]
	global_store_dwordx4 v[138:139], v[130:133], off
	v_pk_fma_f32 v[6:7], v[6:7], v[158:159], v[78:79] op_sel_hi:[1,0,1]
	v_pk_fma_f32 v[16:17], v[16:17], v[158:159], v[76:77] op_sel_hi:[1,0,1]
	v_pk_fma_f32 v[130:131], v[116:117], v[172:173], v[72:73] op_sel_hi:[1,0,1]
	v_pk_fma_f32 v[116:117], v[114:115], v[172:173], v[70:71] op_sel_hi:[1,0,1]
	v_mul_f32_e32 v114, 0xbfb8aa3b, v126
	v_mul_f32_e32 v115, 0xbfb8aa3b, v127
	v_exp_f32_e32 v114, v114
	v_exp_f32_e32 v115, v115
	v_or_b32_e32 v132, 16, v156
	v_pk_fma_f32 v[8:9], v[8:9], v[158:159], v[80:81] op_sel_hi:[1,0,1]
	v_add_f32_e32 v114, 1.0, v114
	v_add_f32_e32 v115, 1.0, v115
	v_rcp_f32_e32 v114, v114
	v_rcp_f32_e32 v115, v115
	v_pk_fma_f32 v[10:11], v[10:11], v[158:159], v[66:67] op_sel_hi:[1,0,1]
	v_pk_fma_f32 v[12:13], v[12:13], v[158:159], v[68:69] op_sel_hi:[1,0,1]
	v_mul_f32_e32 v114, v126, v114
	v_mul_f32_e32 v115, v127, v115
	v_mul_f32_e32 v114, v118, v114
	v_mul_f32_e32 v115, v119, v115
	s_nop 0
	v_cvt_pk_bf16_f32 v114, v114, v115
	v_mul_f32_e32 v115, 0xbfb8aa3b, v128
	v_mul_f32_e32 v118, 0xbfb8aa3b, v129
	v_exp_f32_e32 v115, v115
	v_exp_f32_e32 v118, v118
	v_add_f32_e32 v115, 1.0, v115
	v_add_f32_e32 v118, 1.0, v118
	v_rcp_f32_e32 v115, v115
	v_rcp_f32_e32 v118, v118
	v_mul_f32_e32 v115, v128, v115
	v_mul_f32_e32 v118, v129, v118
	v_mul_f32_e32 v115, v120, v115
	v_mul_f32_e32 v118, v121, v118
	s_nop 0
	v_cvt_pk_bf16_f32 v115, v115, v118
	v_mul_f32_e32 v118, 0xbfb8aa3b, v122
	v_exp_f32_e32 v118, v118
	s_nop 0
	v_add_f32_e32 v118, 1.0, v118
	v_rcp_f32_e32 v118, v118
	s_nop 0
	v_mul_f32_e32 v118, v122, v118
	v_mul_f32_e32 v116, v116, v118
	v_mul_f32_e32 v118, 0xbfb8aa3b, v123
	v_exp_f32_e32 v118, v118
	s_nop 0
	v_add_f32_e32 v118, 1.0, v118
	v_rcp_f32_e32 v118, v118
	s_nop 0
	v_mul_f32_e32 v118, v123, v118
	v_mul_f32_e32 v117, v117, v118
	s_nop 0
	v_cvt_pk_bf16_f32 v116, v116, v117
	v_mul_f32_e32 v117, 0xbfb8aa3b, v124
	v_mul_f32_e32 v118, 0xbfb8aa3b, v125
	v_exp_f32_e32 v117, v117
	v_exp_f32_e32 v118, v118
	v_add_f32_e32 v117, 1.0, v117
	v_add_f32_e32 v118, 1.0, v118
	v_rcp_f32_e32 v117, v117
	v_rcp_f32_e32 v118, v118
	v_mul_f32_e32 v117, v124, v117
	v_mul_f32_e32 v118, v125, v118
	v_mul_f32_e32 v117, v130, v117
	v_mul_f32_e32 v118, v131, v118
	s_nop 0
	v_cvt_pk_bf16_f32 v117, v117, v118
	v_mad_i64_i32 v[118:119], s[18:19], v132, s74, v[134:135]
	v_lshl_add_u64 v[118:119], v[118:119], 0, v[136:137]
	global_store_dwordx4 v[118:119], v[114:117], off
	s_nop 1
	v_pk_fma_f32 v[114:115], v[100:101], v[168:169], v[72:73] op_sel_hi:[1,0,1]
	v_pk_fma_f32 v[100:101], v[98:99], v[168:169], v[70:71] op_sel_hi:[1,0,1]
	v_mul_f32_e32 v98, 0xbfb8aa3b, v110
	v_mul_f32_e32 v99, 0xbfb8aa3b, v111
	v_exp_f32_e32 v98, v98
	v_exp_f32_e32 v99, v99
	v_or_b32_e32 v116, 32, v156
	v_add_f32_e32 v98, 1.0, v98
	v_add_f32_e32 v99, 1.0, v99
	v_rcp_f32_e32 v98, v98
	v_rcp_f32_e32 v99, v99
	v_mul_f32_e32 v98, v110, v98
	v_mul_f32_e32 v99, v111, v99
	v_mul_f32_e32 v98, v102, v98
	v_mul_f32_e32 v99, v103, v99
	s_nop 0
	v_cvt_pk_bf16_f32 v98, v98, v99
	v_mul_f32_e32 v99, 0xbfb8aa3b, v112
	v_mul_f32_e32 v102, 0xbfb8aa3b, v113
	v_exp_f32_e32 v99, v99
	v_exp_f32_e32 v102, v102
	v_add_f32_e32 v99, 1.0, v99
	v_add_f32_e32 v102, 1.0, v102
	v_rcp_f32_e32 v99, v99
	v_rcp_f32_e32 v102, v102
	v_mul_f32_e32 v99, v112, v99
	v_mul_f32_e32 v102, v113, v102
	v_mul_f32_e32 v99, v104, v99
	v_mul_f32_e32 v102, v105, v102
	s_nop 0
	v_cvt_pk_bf16_f32 v99, v99, v102
	v_mul_f32_e32 v102, 0xbfb8aa3b, v106
	v_exp_f32_e32 v102, v102
	s_nop 0
	v_add_f32_e32 v102, 1.0, v102
	v_rcp_f32_e32 v102, v102
	s_nop 0
	v_mul_f32_e32 v102, v106, v102
	v_mul_f32_e32 v100, v100, v102
	v_mul_f32_e32 v102, 0xbfb8aa3b, v107
	v_exp_f32_e32 v102, v102
	s_nop 0
	v_add_f32_e32 v102, 1.0, v102
	v_rcp_f32_e32 v102, v102
	s_nop 0
	v_mul_f32_e32 v102, v107, v102
	v_mul_f32_e32 v101, v101, v102
	s_nop 0
	v_cvt_pk_bf16_f32 v100, v100, v101
	v_mul_f32_e32 v101, 0xbfb8aa3b, v108
	v_mul_f32_e32 v102, 0xbfb8aa3b, v109
	v_exp_f32_e32 v101, v101
	v_exp_f32_e32 v102, v102
	v_add_f32_e32 v101, 1.0, v101
	v_add_f32_e32 v102, 1.0, v102
	v_rcp_f32_e32 v101, v101
	v_rcp_f32_e32 v102, v102
	v_mul_f32_e32 v101, v108, v101
	v_mul_f32_e32 v102, v109, v102
	v_mul_f32_e32 v101, v114, v101
	v_mul_f32_e32 v102, v115, v102
	s_nop 0
; __device__ __forceinline__ unsigned cvt_pk_bf16(float lo, float hi) { unsigned r; asm volatile("s_nop 0\n\tv_cvt_pk_bf16_f32 %0, %1, %2" : "=v"(r) : "v"(lo), "v"(hi)); return r; }
; __device__ __forceinline__ float siluf_(float x) { return x * __builtin_amdgcn_rcpf(1.f + __expf(-x)); }
;     __device__ __forceinline__ void operator()(const f32x4 (&acc)[2][2][4][2], const Unit& u, int wr, int wc, int fr, int fq) const {
;     ...
;             for (int m = 0; m < 4; ++m) { const int r = row0 + ai * 128 + m * 16;
;                 const float rstd = ai ? rb[m] : ra[m];
;                 const f32x4 g0 = acc[ai][0][m][0] * rstd + sg0, g1 = acc[ai][0][m][1] * rstd + sg1, u0 = acc[ai][1][m][0] * rstd + su0, u1 = acc[ai][1][m][1] * rstd + su1;
;                 uint4 st; st.x = cvt_pk_bf16(siluf_(g0[0]) * u0[0], siluf_(g0[1]) * u0[1]); st.y = cvt_pk_bf16(siluf_(g0[2]) * u0[2], siluf_(g0[3]) * u0[3]);
;                 st.z = cvt_pk_bf16(siluf_(g1[0]) * u1[0], siluf_(g1[1]) * u1[1]); st.w = cvt_pk_bf16(siluf_(g1[2]) * u1[2], siluf_(g1[3]) * u1[3]);
;                 *(uint4*)(hid + (size_t)r * DFF + hc0) = st; }
	v_cvt_pk_bf16_f32 v101, v101, v102
	v_mad_i64_i32 v[102:103], s[18:19], v116, s74, v[134:135]
	v_lshl_add_u64 v[102:103], v[102:103], 0, v[136:137]
	global_store_dwordx4 v[102:103], v[98:101], off
	s_nop 1
	v_pk_fma_f32 v[98:99], v[84:85], v[166:167], v[72:73] op_sel_hi:[1,0,1]
	v_pk_fma_f32 v[84:85], v[82:83], v[166:167], v[70:71] op_sel_hi:[1,0,1]
	v_mul_f32_e32 v82, 0xbfb8aa3b, v94
	v_mul_f32_e32 v83, 0xbfb8aa3b, v95
	v_exp_f32_e32 v82, v82
	v_exp_f32_e32 v83, v83
	v_or_b32_e32 v100, 48, v156
	v_add_f32_e32 v82, 1.0, v82
	v_add_f32_e32 v83, 1.0, v83
	v_rcp_f32_e32 v82, v82
	v_rcp_f32_e32 v83, v83
	v_mul_f32_e32 v82, v94, v82
	v_mul_f32_e32 v83, v95, v83
	v_mul_f32_e32 v82, v86, v82
	v_mul_f32_e32 v83, v87, v83
	s_nop 0
	v_cvt_pk_bf16_f32 v82, v82, v83
	v_mul_f32_e32 v83, 0xbfb8aa3b, v96
	v_mul_f32_e32 v86, 0xbfb8aa3b, v97
	v_exp_f32_e32 v83, v83
	v_exp_f32_e32 v86, v86
	v_add_f32_e32 v83, 1.0, v83
	v_add_f32_e32 v86, 1.0, v86
	v_rcp_f32_e32 v83, v83
	v_rcp_f32_e32 v86, v86
	v_mul_f32_e32 v83, v96, v83
	v_mul_f32_e32 v86, v97, v86
	v_mul_f32_e32 v83, v88, v83
	v_mul_f32_e32 v86, v89, v86
	s_nop 0
	v_cvt_pk_bf16_f32 v83, v83, v86
	v_mul_f32_e32 v86, 0xbfb8aa3b, v90
	v_exp_f32_e32 v86, v86
	s_nop 0
	v_add_f32_e32 v86, 1.0, v86
	v_rcp_f32_e32 v86, v86
	s_nop 0
	v_mul_f32_e32 v86, v90, v86
	v_mul_f32_e32 v84, v84, v86
	v_mul_f32_e32 v86, 0xbfb8aa3b, v91
	v_exp_f32_e32 v86, v86
	s_nop 0
	v_add_f32_e32 v86, 1.0, v86
	v_rcp_f32_e32 v86, v86
	s_nop 0
	v_mul_f32_e32 v86, v91, v86
	v_mul_f32_e32 v85, v85, v86
	s_nop 0
	v_cvt_pk_bf16_f32 v84, v84, v85
	v_mul_f32_e32 v85, 0xbfb8aa3b, v92
	v_mul_f32_e32 v86, 0xbfb8aa3b, v93
	v_exp_f32_e32 v85, v85
	v_exp_f32_e32 v86, v86
	v_add_f32_e32 v85, 1.0, v85
	v_add_f32_e32 v86, 1.0, v86
	v_rcp_f32_e32 v85, v85
	v_rcp_f32_e32 v86, v86
	v_mul_f32_e32 v85, v92, v85
	v_mul_f32_e32 v86, v93, v86
	v_mul_f32_e32 v85, v98, v85
	v_mul_f32_e32 v86, v99, v86
	s_nop 0
	v_cvt_pk_bf16_f32 v85, v85, v86
	v_mad_i64_i32 v[86:87], s[18:19], v100, s74, v[134:135]
	v_lshl_add_u64 v[86:87], v[86:87], 0, v[136:137]
	global_store_dwordx4 v[86:87], v[82:85], off
	s_nop 1
	v_pk_fma_f32 v[82:83], v[52:53], v[164:165], v[72:73] op_sel_hi:[1,0,1]
	v_pk_fma_f32 v[52:53], v[50:51], v[164:165], v[70:71] op_sel_hi:[1,0,1]
	v_mul_f32_e32 v50, 0xbfb8aa3b, v62
	v_mul_f32_e32 v51, 0xbfb8aa3b, v63
	v_exp_f32_e32 v50, v50
	v_exp_f32_e32 v51, v51
	v_add_u32_e32 v84, 0x80, v156
	v_add_f32_e32 v50, 1.0, v50
	v_add_f32_e32 v51, 1.0, v51
	v_rcp_f32_e32 v50, v50
	v_rcp_f32_e32 v51, v51
	v_mul_f32_e32 v50, v62, v50
	v_mul_f32_e32 v51, v63, v51
	v_mul_f32_e32 v50, v54, v50
	v_mul_f32_e32 v51, v55, v51
	s_nop 0
	v_cvt_pk_bf16_f32 v50, v50, v51
	v_mul_f32_e32 v51, 0xbfb8aa3b, v64
	v_mul_f32_e32 v54, 0xbfb8aa3b, v65
	v_exp_f32_e32 v51, v51
	v_exp_f32_e32 v54, v54
	v_add_f32_e32 v51, 1.0, v51
	v_add_f32_e32 v54, 1.0, v54
	v_rcp_f32_e32 v51, v51
	v_rcp_f32_e32 v54, v54
	v_mul_f32_e32 v51, v64, v51
	v_mul_f32_e32 v54, v65, v54
	v_mul_f32_e32 v51, v56, v51
	v_mul_f32_e32 v54, v57, v54
	s_nop 0
	v_cvt_pk_bf16_f32 v51, v51, v54
	v_mul_f32_e32 v54, 0xbfb8aa3b, v58
	v_exp_f32_e32 v54, v54
	s_nop 0
	v_add_f32_e32 v54, 1.0, v54
	v_rcp_f32_e32 v54, v54
	s_nop 0
	v_mul_f32_e32 v54, v58, v54
	v_mul_f32_e32 v52, v52, v54
	v_mul_f32_e32 v54, 0xbfb8aa3b, v59
	v_exp_f32_e32 v54, v54
	s_nop 0
	v_add_f32_e32 v54, 1.0, v54
	v_rcp_f32_e32 v54, v54
	s_nop 0
	v_mul_f32_e32 v54, v59, v54
	v_mul_f32_e32 v53, v53, v54
	s_nop 0
	v_cvt_pk_bf16_f32 v52, v52, v53
	v_mul_f32_e32 v53, 0xbfb8aa3b, v60
	v_mul_f32_e32 v54, 0xbfb8aa3b, v61
	v_exp_f32_e32 v53, v53
	v_exp_f32_e32 v54, v54
	v_add_f32_e32 v53, 1.0, v53
	v_add_f32_e32 v54, 1.0, v54
	v_rcp_f32_e32 v53, v53
	v_rcp_f32_e32 v54, v54
	v_mul_f32_e32 v53, v60, v53
	v_mul_f32_e32 v54, v61, v54
	v_mul_f32_e32 v53, v82, v53
	v_mul_f32_e32 v54, v83, v54
	s_nop 0
	v_cvt_pk_bf16_f32 v53, v53, v54
	v_mad_i64_i32 v[54:55], s[18:19], v84, s74, v[134:135]
	v_lshl_add_u64 v[54:55], v[54:55], 0, v[136:137]
	global_store_dwordx4 v[54:55], v[50:53], off
	s_nop 1
	v_pk_fma_f32 v[50:51], v[36:37], v[162:163], v[72:73] op_sel_hi:[1,0,1]
	v_pk_fma_f32 v[36:37], v[34:35], v[162:163], v[70:71] op_sel_hi:[1,0,1]
	v_mul_f32_e32 v34, 0xbfb8aa3b, v46
	v_mul_f32_e32 v35, 0xbfb8aa3b, v47
	v_exp_f32_e32 v34, v34
	v_exp_f32_e32 v35, v35
	v_add_u32_e32 v52, 0x90, v156
	v_add_f32_e32 v34, 1.0, v34
	v_add_f32_e32 v35, 1.0, v35
	v_rcp_f32_e32 v34, v34
	v_rcp_f32_e32 v35, v35
	v_mul_f32_e32 v34, v46, v34
	v_mul_f32_e32 v35, v47, v35
	v_mul_f32_e32 v34, v38, v34
	v_mul_f32_e32 v35, v39, v35
	s_nop 0
	v_cvt_pk_bf16_f32 v34, v34, v35
	v_mul_f32_e32 v35, 0xbfb8aa3b, v48
	v_mul_f32_e32 v38, 0xbfb8aa3b, v49
	v_exp_f32_e32 v35, v35
	v_exp_f32_e32 v38, v38
	v_add_f32_e32 v35, 1.0, v35
	v_add_f32_e32 v38, 1.0, v38
	v_rcp_f32_e32 v35, v35
	v_rcp_f32_e32 v38, v38
	v_mul_f32_e32 v35, v48, v35
	v_mul_f32_e32 v38, v49, v38
; __device__ __forceinline__ unsigned cvt_pk_bf16(float lo, float hi) { unsigned r; asm volatile("s_nop 0\n\tv_cvt_pk_bf16_f32 %0, %1, %2" : "=v"(r) : "v"(lo), "v"(hi)); return r; }
; __device__ __forceinline__ float siluf_(float x) { return x * __builtin_amdgcn_rcpf(1.f + __expf(-x)); }
; #define PG8_WAIT_V(n) asm volatile("s_waitcnt vmcnt(" #n ")" ::: "memory")
; #define PG8_BAR __builtin_amdgcn_s_barrier()
; template <class Epi>
; __device__ __forceinline__ void gemm_phase(LAS unsigned char* lds, const Gemm g, const StaticOrder& S, const Epi& E) {
;     ...
;         E(acc, cur, wr, wc, fr, fq);
;         if (!has_next) break;
; #pragma unroll
;         for (int a = 0; a < 2; ++a)
; #pragma unroll
;             for (int b = 0; b < 2; ++b)
; #pragma unroll
;                 for (int m = 0; m < 4; ++m)
; #pragma unroll
;                     for (int n = 0; n < 2; ++n) acc[a][b][m][n] = (f32x4){0.f, 0.f, 0.f, 0.f};
;         cur = nxt; cA = nA; cB = nB; ++ui;
;     }
;     PG8_WAIT_V(0);
;     if (wr == 0) PG8_BAR;
;     __device__ __forceinline__ void operator()(const f32x4 (&acc)[2][2][4][2], const Unit& u, int wr, int wc, int fr, int fq) const {
;     ...
;             for (int m = 0; m < 4; ++m) { const int r = row0 + ai * 128 + m * 16;
;                 const float rstd = ai ? rb[m] : ra[m];
;                 const f32x4 g0 = acc[ai][0][m][0] * rstd + sg0, g1 = acc[ai][0][m][1] * rstd + sg1, u0 = acc[ai][1][m][0] * rstd + su0, u1 = acc[ai][1][m][1] * rstd + su1;
;                 uint4 st; st.x = cvt_pk_bf16(siluf_(g0[0]) * u0[0], siluf_(g0[1]) * u0[1]); st.y = cvt_pk_bf16(siluf_(g0[2]) * u0[2], siluf_(g0[3]) * u0[3]);
;                 st.z = cvt_pk_bf16(siluf_(g1[0]) * u1[0], siluf_(g1[1]) * u1[1]); st.w = cvt_pk_bf16(siluf_(g1[2]) * u1[2], siluf_(g1[3]) * u1[3]);
;                 *(uint4*)(hid + (size_t)r * DFF + hc0) = st; }
	v_mul_f32_e32 v35, v40, v35
	v_mul_f32_e32 v38, v41, v38
	s_nop 0
	v_cvt_pk_bf16_f32 v35, v35, v38
	v_mul_f32_e32 v38, 0xbfb8aa3b, v42
	v_exp_f32_e32 v38, v38
	s_nop 0
	v_add_f32_e32 v38, 1.0, v38
	v_rcp_f32_e32 v38, v38
	s_nop 0
	v_mul_f32_e32 v38, v42, v38
	v_mul_f32_e32 v36, v36, v38
	v_mul_f32_e32 v38, 0xbfb8aa3b, v43
	v_exp_f32_e32 v38, v38
	s_nop 0
	v_add_f32_e32 v38, 1.0, v38
	v_rcp_f32_e32 v38, v38
	s_nop 0
	v_mul_f32_e32 v38, v43, v38
	v_mul_f32_e32 v37, v37, v38
	s_nop 0
	v_cvt_pk_bf16_f32 v36, v36, v37
	v_mul_f32_e32 v37, 0xbfb8aa3b, v44
	v_mul_f32_e32 v38, 0xbfb8aa3b, v45
	v_exp_f32_e32 v37, v37
	v_exp_f32_e32 v38, v38
	v_add_f32_e32 v37, 1.0, v37
	v_add_f32_e32 v38, 1.0, v38
	v_rcp_f32_e32 v37, v37
	v_rcp_f32_e32 v38, v38
	v_mul_f32_e32 v37, v44, v37
	v_mul_f32_e32 v38, v45, v38
	v_mul_f32_e32 v37, v50, v37
	v_mul_f32_e32 v38, v51, v38
	s_nop 0
	v_cvt_pk_bf16_f32 v37, v37, v38
	v_mad_i64_i32 v[38:39], s[18:19], v52, s74, v[134:135]
	v_lshl_add_u64 v[38:39], v[38:39], 0, v[136:137]
	global_store_dwordx4 v[38:39], v[34:37], off
	s_nop 1
	v_pk_fma_f32 v[34:35], v[20:21], v[160:161], v[72:73] op_sel_hi:[1,0,1]
	v_pk_fma_f32 v[20:21], v[18:19], v[160:161], v[70:71] op_sel_hi:[1,0,1]
	v_mul_f32_e32 v18, 0xbfb8aa3b, v30
	v_mul_f32_e32 v19, 0xbfb8aa3b, v31
	v_exp_f32_e32 v18, v18
	v_exp_f32_e32 v19, v19
	v_add_u32_e32 v36, 0xa0, v156
	v_add_f32_e32 v18, 1.0, v18
	v_add_f32_e32 v19, 1.0, v19
	v_rcp_f32_e32 v18, v18
	v_rcp_f32_e32 v19, v19
	v_mul_f32_e32 v18, v30, v18
	v_mul_f32_e32 v19, v31, v19
	v_mul_f32_e32 v18, v22, v18
	v_mul_f32_e32 v19, v23, v19
	s_nop 0
	v_cvt_pk_bf16_f32 v18, v18, v19
	v_mul_f32_e32 v19, 0xbfb8aa3b, v32
	v_mul_f32_e32 v22, 0xbfb8aa3b, v33
	v_exp_f32_e32 v19, v19
	v_exp_f32_e32 v22, v22
	v_add_f32_e32 v19, 1.0, v19
	v_add_f32_e32 v22, 1.0, v22
	v_rcp_f32_e32 v19, v19
	v_rcp_f32_e32 v22, v22
	v_mul_f32_e32 v19, v32, v19
	v_mul_f32_e32 v22, v33, v22
	v_mul_f32_e32 v19, v24, v19
	v_mul_f32_e32 v22, v25, v22
	s_nop 0
	v_cvt_pk_bf16_f32 v19, v19, v22
	v_mul_f32_e32 v22, 0xbfb8aa3b, v26
	v_exp_f32_e32 v22, v22
	s_nop 0
	v_add_f32_e32 v22, 1.0, v22
	v_rcp_f32_e32 v22, v22
	s_nop 0
	v_mul_f32_e32 v22, v26, v22
	v_mul_f32_e32 v20, v20, v22
	v_mul_f32_e32 v22, 0xbfb8aa3b, v27
	v_exp_f32_e32 v22, v22
	s_nop 0
	v_add_f32_e32 v22, 1.0, v22
	v_rcp_f32_e32 v22, v22
	s_nop 0
	v_mul_f32_e32 v22, v27, v22
	v_mul_f32_e32 v21, v21, v22
	s_nop 0
	v_cvt_pk_bf16_f32 v20, v20, v21
	v_mul_f32_e32 v21, 0xbfb8aa3b, v28
	v_mul_f32_e32 v22, 0xbfb8aa3b, v29
	v_exp_f32_e32 v21, v21
	v_exp_f32_e32 v22, v22
	v_add_f32_e32 v21, 1.0, v21
	v_add_f32_e32 v22, 1.0, v22
	v_rcp_f32_e32 v21, v21
	v_rcp_f32_e32 v22, v22
	v_mul_f32_e32 v21, v28, v21
	v_mul_f32_e32 v22, v29, v22
	v_mul_f32_e32 v21, v34, v21
	v_mul_f32_e32 v22, v35, v22
	s_nop 0
	v_cvt_pk_bf16_f32 v21, v21, v22
	v_mad_i64_i32 v[22:23], s[18:19], v36, s74, v[134:135]
	v_lshl_add_u64 v[22:23], v[22:23], 0, v[136:137]
	global_store_dwordx4 v[22:23], v[18:21], off
	s_nop 1
	v_pk_fma_f32 v[18:19], v[2:3], v[158:159], v[72:73] op_sel_hi:[1,0,1]
	v_pk_fma_f32 v[2:3], v[0:1], v[158:159], v[70:71] op_sel_hi:[1,0,1]
	v_mul_f32_e32 v0, 0xbfb8aa3b, v14
	v_mul_f32_e32 v1, 0xbfb8aa3b, v15
	v_exp_f32_e32 v0, v0
	v_exp_f32_e32 v1, v1
	v_add_u32_e32 v20, 0xb0, v156
	v_add_f32_e32 v0, 1.0, v0
	v_add_f32_e32 v1, 1.0, v1
	v_rcp_f32_e32 v0, v0
	v_rcp_f32_e32 v1, v1
	v_mul_f32_e32 v0, v14, v0
	v_mul_f32_e32 v1, v15, v1
	v_mul_f32_e32 v0, v6, v0
	v_mul_f32_e32 v1, v7, v1
	s_nop 0
	v_cvt_pk_bf16_f32 v0, v0, v1
	v_mul_f32_e32 v1, 0xbfb8aa3b, v16
	v_mul_f32_e32 v6, 0xbfb8aa3b, v17
	v_exp_f32_e32 v1, v1
	v_exp_f32_e32 v6, v6
	v_add_f32_e32 v1, 1.0, v1
	v_add_f32_e32 v6, 1.0, v6
	v_rcp_f32_e32 v1, v1
	v_rcp_f32_e32 v6, v6
	v_mul_f32_e32 v1, v16, v1
	v_mul_f32_e32 v6, v17, v6
	v_mul_f32_e32 v1, v8, v1
	v_mul_f32_e32 v6, v9, v6
	s_nop 0
	v_cvt_pk_bf16_f32 v1, v1, v6
	v_mul_f32_e32 v6, 0xbfb8aa3b, v10
	v_exp_f32_e32 v6, v6
	s_nop 0
	v_add_f32_e32 v6, 1.0, v6
	v_rcp_f32_e32 v6, v6
	s_nop 0
	v_mul_f32_e32 v6, v10, v6
	v_mul_f32_e32 v2, v2, v6
	v_mul_f32_e32 v6, 0xbfb8aa3b, v11
	v_exp_f32_e32 v6, v6
	s_nop 0
	v_add_f32_e32 v6, 1.0, v6
	v_rcp_f32_e32 v6, v6
	s_nop 0
	v_mul_f32_e32 v6, v11, v6
	v_mul_f32_e32 v3, v3, v6
	s_nop 0
	v_cvt_pk_bf16_f32 v2, v2, v3
	v_mul_f32_e32 v3, 0xbfb8aa3b, v12
	v_mul_f32_e32 v6, 0xbfb8aa3b, v13
	v_exp_f32_e32 v3, v3
	v_exp_f32_e32 v6, v6
	v_add_f32_e32 v3, 1.0, v3
	v_add_f32_e32 v6, 1.0, v6
	v_rcp_f32_e32 v3, v3
	v_rcp_f32_e32 v6, v6
	v_mul_f32_e32 v3, v12, v3
	v_mul_f32_e32 v6, v13, v6
	v_mul_f32_e32 v3, v18, v3
	v_mul_f32_e32 v6, v19, v6
	s_nop 0
	v_cvt_pk_bf16_f32 v3, v3, v6
	v_mad_i64_i32 v[6:7], s[18:19], v20, s74, v[134:135]
	v_lshl_add_u64 v[6:7], v[6:7], 0, v[136:137]
	s_mov_b64 s[18:19], s[14:15]
	global_store_dwordx4 v[6:7], v[0:3], off
	s_cbranch_vccz .LBB0_2894
	s_waitcnt vmcnt(0)
	s_cmpk_gt_u32 s24, 0xff
	s_cbranch_scc1 .LBB0_2901
	s_barrier

; #define PG8_STAGE(bufoff, gbase, voff) do { _Pragma("unroll") for (int _i = 0; _i < 2; ++_i) \
;         __builtin_amdgcn_global_load_lds((const unsigned*)((const char*)(gbase) + (voff)[_i]), (LAS unsigned*)(lds + (bufoff) + ldsw + _i * 8192), 16, 0, 0); } while (0)
; #define PG8_LDA(dst, b, h) do { _Pragma("unroll") for (int m = 0; m < 4; ++m) _Pragma("unroll") for (int k = 0; k < 2; ++k) dst[m][k] = *(const LAS bf16x8*)(lds + PG8_SA(b, h) + aoff + m * 2048 + k * 1024); } while (0)
; #define PG8_LDB(dst, b, h) do { _Pragma("unroll") for (int n = 0; n < 2; ++n) _Pragma("unroll") for (int k = 0; k < 2; ++k) dst[n][k] = *(const LAS bf16x8*)(lds + PG8_SB(b, h) + boff + n * 2048 + k * 1024); } while (0)
; #define PG8_WAIT_L(n) asm volatile("s_waitcnt lgkmcnt(" #n ")" ::: "memory")
; #define PG8_BAR __builtin_amdgcn_s_barrier()
; #define PG8_SCHED __builtin_amdgcn_sched_barrier(0)
; template <class Epi>
; __device__ __forceinline__ void gemm_phase(LAS unsigned char* lds, const Gemm g, const StaticOrder& S, const Epi& E) {
;     ...
;         const bool has_next = S.next(ui + 1, nxt);
;         const char* nA = has_next ? (const char*)g.A + (size_t)nxt.pm * tstep : cA; const char* nB = has_next ? (const char*)g.Bt + (size_t)nxt.pn * tstep : cB;
;         for (int t = 0; t < nt; t += 2) {
;             const bool last = (t == nt - 2);
;             const char* a1 = cA + (size_t)(t + 1) * kstep;
;             const char* a2 = last ? nA : cA + (size_t)(t + 2) * kstep; const char* b2 = last ? nB : cB + (size_t)(t + 2) * kstep;
;             const char* a3 = a2 + kstep; const char* b3 = b2 + kstep;
;             PG8_LDB(B0, 0, 0); PG8_SCHED; PG8_LDA(At, 0, 0); PG8_STAGE(PG8_SA(1, 1), a1 + hstep, voffA);
;             PG8_WAIT_L(8); PG8_BAR; PG8_WAIT_L(0); PG8_MMA(0, 0, At, B0); PG8_BAR; PG8_SCHED;
;             PG8_LDB(B1, 0, 1); PG8_STAGE(PG8_SB(0, 0), b2, voffB);
;             PG8_BAR; PG8_WAIT_L(0); PG8_MMA(0, 1, At, B1); PG8_BAR;
;             PG8_LDA(At, 0, 1); PG8_STAGE(PG8_SA(0, 0), a2, voffA);
;             PG8_BAR; PG8_WAIT_L(0); PG8_MMA(1, 0, At, B0); PG8_BAR; PG8_SCHED;
;     ...
; #pragma unroll
;         for (int a = 0; a < 2; ++a)
; #pragma unroll
;             for (int b = 0; b < 2; ++b)
; #pragma unroll
;                 for (int m = 0; m < 4; ++m)
; #pragma unroll
;                     for (int n = 0; n < 2; ++n) acc[a][b][m][n] = (f32x4){0.f, 0.f, 0.f, 0.f};
.LBB0_2973:
	s_add_u32 s8, s28, 0x80
	s_addc_u32 s9, s29, 0
	s_add_u32 s62, s26, 0x100
	s_addc_u32 s63, s27, 0
	s_mov_b32 s26, 0
	s_waitcnt lgkmcnt(0)
	s_add_i32 s64, s26, 2
	s_add_u32 s0, s8, 0x80
	s_addc_u32 s1, s9, 0
	s_add_i32 s65, 0, 0x10000
	v_add_u32_e32 v4, s65, v245
	ds_read_b128 v[132:135], v4
	ds_read_b128 v[136:139], v4 offset:1024
	ds_read_b128 v[140:143], v4 offset:2048
	ds_read_b128 v[144:147], v4 offset:3072
	s_cmp_eq_u32 s57, s26
	s_cselect_b32 s26, s24, s0
	s_cselect_b32 s27, s25, s1
	s_cselect_b32 s29, s11, s63
	s_cselect_b32 s28, s10, s62
	v_lshl_add_u64 v[6:7], s[8:9], 0, v[164:165]
	s_add_i32 m0, s39, 0xc000
	ds_read_b128 v[148:151], v249
	ds_read_b128 v[152:155], v249 offset:1024
	ds_read_b128 v[156:159], v249 offset:2048
	ds_read_b128 v[168:171], v249 offset:3072
	ds_read_b128 v[172:175], v249 offset:4096
	ds_read_b128 v[190:193], v249 offset:5120
	ds_read_b128 v[194:197], v249 offset:6144
	ds_read_b128 v[198:201], v249 offset:7168
	global_load_lds_dwordx4 v[6:7], off
	s_add_i32 m0, s39, 0xe000
	v_lshl_add_u64 v[6:7], s[8:9], 0, v[166:167]
	global_load_lds_dwordx4 v[6:7], off
	s_waitcnt lgkmcnt(8)
	s_barrier
	s_waitcnt lgkmcnt(0)
	v_mfma_f32_16x16x32_bf16 v[80:83], v[132:135], v[148:151], 0
	v_mfma_f32_16x16x32_bf16 v[104:107], v[140:143], v[148:151], 0
	v_mfma_f32_16x16x32_bf16 v[128:131], v[132:135], v[156:159], 0
	v_mfma_f32_16x16x32_bf16 v[100:103], v[140:143], v[156:159], 0
	v_mfma_f32_16x16x32_bf16 v[124:127], v[132:135], v[172:175], 0
	v_mfma_f32_16x16x32_bf16 v[96:99], v[140:143], v[172:175], 0
	v_mfma_f32_16x16x32_bf16 v[120:123], v[132:135], v[194:197], 0
	v_mfma_f32_16x16x32_bf16 v[88:91], v[140:143], v[194:197], 0
	v_mfma_f32_16x16x32_bf16 v[80:83], v[136:139], v[152:155], v[80:83]
	v_mfma_f32_16x16x32_bf16 v[104:107], v[144:147], v[152:155], v[104:107]
	v_mfma_f32_16x16x32_bf16 v[128:131], v[136:139], v[168:171], v[128:131]
	v_mfma_f32_16x16x32_bf16 v[100:103], v[144:147], v[168:171], v[100:103]
	v_mfma_f32_16x16x32_bf16 v[124:127], v[136:139], v[190:193], v[124:127]
	v_mfma_f32_16x16x32_bf16 v[96:99], v[144:147], v[190:193], v[96:99]
	v_mfma_f32_16x16x32_bf16 v[120:123], v[136:139], v[198:201], v[120:123]
	v_mfma_f32_16x16x32_bf16 v[88:91], v[144:147], v[198:201], v[88:91]
	s_barrier
	s_add_i32 s70, 0, 0x14000
	s_add_i32 s0, s65, s34
	v_add_u32_e32 v4, s70, v245
	v_lshl_add_u64 v[176:177], s[28:29], 0, v[162:163]
	s_mov_b32 m0, s0
	ds_read_b128 v[202:205], v4
	ds_read_b128 v[206:209], v4 offset:1024
	ds_read_b128 v[210:213], v4 offset:2048
	ds_read_b128 v[214:217], v4 offset:3072
	global_load_lds_dwordx4 v[176:177], off
	s_add_i32 m0, s0, 0x2000
	v_lshl_add_u64 v[186:187], s[28:29], 0, v[160:161]
	global_load_lds_dwordx4 v[186:187], off
	s_barrier
	s_waitcnt lgkmcnt(0)
	v_mfma_f32_16x16x32_bf16 v[64:67], v[202:205], v[148:151], 0
	v_mfma_f32_16x16x32_bf16 v[32:35], v[210:213], v[148:151], 0
	v_mfma_f32_16x16x32_bf16 v[60:63], v[202:205], v[156:159], 0
	v_mfma_f32_16x16x32_bf16 v[28:31], v[210:213], v[156:159], 0
	v_mfma_f32_16x16x32_bf16 v[56:59], v[202:205], v[172:175], 0
	v_mfma_f32_16x16x32_bf16 v[24:27], v[210:213], v[172:175], 0
	v_mfma_f32_16x16x32_bf16 v[52:55], v[202:205], v[194:197], 0
	v_mfma_f32_16x16x32_bf16 v[20:23], v[210:213], v[194:197], 0
	v_mfma_f32_16x16x32_bf16 v[64:67], v[206:209], v[152:155], v[64:67]
	v_mfma_f32_16x16x32_bf16 v[32:35], v[214:217], v[152:155], v[32:35]
	v_mfma_f32_16x16x32_bf16 v[60:63], v[206:209], v[168:171], v[60:63]
	v_mfma_f32_16x16x32_bf16 v[28:31], v[214:217], v[168:171], v[28:31]
	v_mfma_f32_16x16x32_bf16 v[56:59], v[206:209], v[190:193], v[56:59]
	v_mfma_f32_16x16x32_bf16 v[24:27], v[214:217], v[190:193], v[24:27]
	v_mfma_f32_16x16x32_bf16 v[52:55], v[206:209], v[198:201], v[52:55]
	v_mfma_f32_16x16x32_bf16 v[20:23], v[214:217], v[198:201], v[20:23]
	s_mov_b32 m0, s39
	v_lshl_add_u64 v[218:219], s[26:27], 0, v[162:163]
	s_barrier
	ds_read_b128 v[148:151], v249 offset:16384
	ds_read_b128 v[152:155], v249 offset:17408
	ds_read_b128 v[156:159], v249 offset:18432
	ds_read_b128 v[168:171], v249 offset:19456
	ds_read_b128 v[172:175], v249 offset:20480
	ds_read_b128 v[190:193], v249 offset:21504
	ds_read_b128 v[194:197], v249 offset:22528
	ds_read_b128 v[198:201], v249 offset:23552
	global_load_lds_dwordx4 v[218:219], off
	s_mov_b32 m0, s40
	v_lshl_add_u64 v[220:221], s[26:27], 0, v[160:161]
	global_load_lds_dwordx4 v[220:221], off
	s_barrier
	s_waitcnt lgkmcnt(0)
	v_mfma_f32_16x16x32_bf16 v[92:95], v[132:135], v[148:151], 0
	v_mfma_f32_16x16x32_bf16 v[84:87], v[140:143], v[148:151], 0
	v_mfma_f32_16x16x32_bf16 v[116:119], v[132:135], v[156:159], 0
	v_mfma_f32_16x16x32_bf16 v[76:79], v[140:143], v[156:159], 0
	v_mfma_f32_16x16x32_bf16 v[112:115], v[132:135], v[172:175], 0
	v_mfma_f32_16x16x32_bf16 v[72:75], v[140:143], v[172:175], 0
	v_mfma_f32_16x16x32_bf16 v[108:111], v[132:135], v[194:197], 0
	v_mfma_f32_16x16x32_bf16 v[68:71], v[140:143], v[194:197], 0
	v_mfma_f32_16x16x32_bf16 v[92:95], v[136:139], v[152:155], v[92:95]
	v_mfma_f32_16x16x32_bf16 v[84:87], v[144:147], v[152:155], v[84:87]
	v_mfma_f32_16x16x32_bf16 v[116:119], v[136:139], v[168:171], v[116:119]
	v_mfma_f32_16x16x32_bf16 v[76:79], v[144:147], v[168:171], v[76:79]
	v_mfma_f32_16x16x32_bf16 v[112:115], v[136:139], v[190:193], v[112:115]
	v_mfma_f32_16x16x32_bf16 v[72:75], v[144:147], v[190:193], v[72:75]
	v_mfma_f32_16x16x32_bf16 v[108:111], v[136:139], v[198:201], v[108:111]
	v_mfma_f32_16x16x32_bf16 v[68:71], v[144:147], v[198:201], v[68:71]
	s_barrier
; #define PG8_STAGE(bufoff, gbase, voff) do { _Pragma("unroll") for (int _i = 0; _i < 2; ++_i) \
;         __builtin_amdgcn_global_load_lds((const unsigned*)((const char*)(gbase) + (voff)[_i]), (LAS unsigned*)(lds + (bufoff) + ldsw + _i * 8192), 16, 0, 0); } while (0)
; #define PG8_LDA(dst, b, h) do { _Pragma("unroll") for (int m = 0; m < 4; ++m) _Pragma("unroll") for (int k = 0; k < 2; ++k) dst[m][k] = *(const LAS bf16x8*)(lds + PG8_SA(b, h) + aoff + m * 2048 + k * 1024); } while (0)
; #define PG8_LDB(dst, b, h) do { _Pragma("unroll") for (int n = 0; n < 2; ++n) _Pragma("unroll") for (int k = 0; k < 2; ++k) dst[n][k] = *(const LAS bf16x8*)(lds + PG8_SB(b, h) + boff + n * 2048 + k * 1024); } while (0)
; #define PG8_MMA(ai, bj, At, Bt) do { __builtin_amdgcn_s_setprio(1); _Pragma("unroll") for (int m = 0; m < 4; ++m) _Pragma("unroll") for (int n = 0; n < 2; ++n) _Pragma("unroll") for (int k = 0; k < 2; ++k) \
;         acc[ai][bj][m][n] = __builtin_amdgcn_mfma_f32_16x16x32_bf16(Bt[n][k], At[m][k], acc[ai][bj][m][n], 0, 0, 0); __builtin_amdgcn_s_setprio(0); } while (0)
; #define PG8_WAIT_V(n) asm volatile("s_waitcnt vmcnt(" #n ")" ::: "memory")
; #define PG8_WAIT_L(n) asm volatile("s_waitcnt lgkmcnt(" #n ")" ::: "memory")
; #define PG8_BAR __builtin_amdgcn_s_barrier()
; #define PG8_SCHED __builtin_amdgcn_sched_barrier(0)
; template <class Epi>
; __device__ __forceinline__ void gemm_phase(LAS unsigned char* lds, const Gemm g, const StaticOrder& S, const Epi& E) {
;     ...
;             PG8_STAGE(PG8_SB(0, 1), b2 + hstep, voffB);
;             PG8_WAIT_V(6); PG8_BAR; PG8_MMA(1, 1, At, B1); PG8_BAR;
;             PG8_LDB(B0, 1, 0); PG8_SCHED; PG8_LDA(At, 1, 0); PG8_STAGE(PG8_SA(0, 1), a2 + hstep, voffA);
;             PG8_WAIT_L(8); PG8_BAR; PG8_WAIT_L(0); PG8_MMA(0, 0, At, B0); PG8_BAR; PG8_SCHED;
;             PG8_LDB(B1, 1, 1); PG8_STAGE(PG8_SB(1, 0), b3, voffB);
	s_add_u32 s0, s28, s52
	s_addc_u32 s1, s29, 0
	s_add_i32 s28, s70, s34
	v_lshl_add_u64 v[222:223], s[0:1], 0, v[162:163]
	s_mov_b32 m0, s28
	v_lshl_add_u64 v[224:225], s[0:1], 0, v[160:161]
	global_load_lds_dwordx4 v[222:223], off
	s_add_i32 m0, s28, 0x2000
	s_nop 0
	global_load_lds_dwordx4 v[224:225], off
	s_waitcnt vmcnt(6)
	s_barrier
	v_mfma_f32_16x16x32_bf16 v[48:51], v[202:205], v[148:151], 0
	v_mfma_f32_16x16x32_bf16 v[16:19], v[210:213], v[148:151], 0
	v_mfma_f32_16x16x32_bf16 v[44:47], v[202:205], v[156:159], 0
	v_mfma_f32_16x16x32_bf16 v[12:15], v[210:213], v[156:159], 0
	v_mfma_f32_16x16x32_bf16 v[40:43], v[202:205], v[172:175], 0
	v_mfma_f32_16x16x32_bf16 v[6:9], v[210:213], v[172:175], 0
	v_mfma_f32_16x16x32_bf16 v[36:39], v[202:205], v[194:197], 0
	v_mfma_f32_16x16x32_bf16 v[0:3], v[210:213], v[194:197], 0
	v_mfma_f32_16x16x32_bf16 v[48:51], v[206:209], v[152:155], v[48:51]
	v_mfma_f32_16x16x32_bf16 v[16:19], v[214:217], v[152:155], v[16:19]
	v_mfma_f32_16x16x32_bf16 v[44:47], v[206:209], v[168:171], v[44:47]
	v_mfma_f32_16x16x32_bf16 v[12:15], v[214:217], v[168:171], v[12:15]
	v_mfma_f32_16x16x32_bf16 v[40:43], v[206:209], v[190:193], v[40:43]
	v_mfma_f32_16x16x32_bf16 v[6:9], v[214:217], v[190:193], v[6:9]
	v_mfma_f32_16x16x32_bf16 v[36:39], v[206:209], v[198:201], v[36:39]
	v_mfma_f32_16x16x32_bf16 v[0:3], v[214:217], v[198:201], v[0:3]
	s_add_i32 s28, 0, 0x18000
	v_add_u32_e32 v4, s28, v245
	s_barrier
	ds_read_b128 v[132:135], v4
	ds_read_b128 v[136:139], v4 offset:1024
	ds_read_b128 v[140:143], v4 offset:2048
	ds_read_b128 v[144:147], v4 offset:3072
	s_add_u32 s0, s26, s52
	s_addc_u32 s1, s27, 0
	s_mov_b32 m0, s41
	v_lshl_add_u64 v[10:11], s[0:1], 0, v[162:163]
	ds_read_b128 v[148:151], v249 offset:32768
	ds_read_b128 v[152:155], v249 offset:33792
	ds_read_b128 v[156:159], v249 offset:34816
	ds_read_b128 v[168:171], v249 offset:35840
	ds_read_b128 v[172:175], v249 offset:36864
	ds_read_b128 v[190:193], v249 offset:37888
	ds_read_b128 v[194:197], v249 offset:38912
	ds_read_b128 v[198:201], v249 offset:39936
	global_load_lds_dwordx4 v[10:11], off
	s_mov_b32 m0, s42
	v_lshl_add_u64 v[10:11], s[0:1], 0, v[160:161]
	global_load_lds_dwordx4 v[10:11], off
	s_waitcnt lgkmcnt(8)
	s_barrier
	s_waitcnt lgkmcnt(0)
	v_mfma_f32_16x16x32_bf16 v[80:83], v[132:135], v[148:151], v[80:83]
	v_mfma_f32_16x16x32_bf16 v[104:107], v[140:143], v[148:151], v[104:107]
	v_mfma_f32_16x16x32_bf16 v[128:131], v[132:135], v[156:159], v[128:131]
	v_mfma_f32_16x16x32_bf16 v[100:103], v[140:143], v[156:159], v[100:103]
	v_mfma_f32_16x16x32_bf16 v[124:127], v[132:135], v[172:175], v[124:127]
	v_mfma_f32_16x16x32_bf16 v[96:99], v[140:143], v[172:175], v[96:99]
	v_mfma_f32_16x16x32_bf16 v[120:123], v[132:135], v[194:197], v[120:123]
	v_mfma_f32_16x16x32_bf16 v[88:91], v[140:143], v[194:197], v[88:91]
	v_mfma_f32_16x16x32_bf16 v[80:83], v[136:139], v[152:155], v[80:83]
	v_mfma_f32_16x16x32_bf16 v[104:107], v[144:147], v[152:155], v[104:107]
	v_mfma_f32_16x16x32_bf16 v[128:131], v[136:139], v[168:171], v[128:131]
	v_mfma_f32_16x16x32_bf16 v[100:103], v[144:147], v[168:171], v[100:103]
	v_mfma_f32_16x16x32_bf16 v[124:127], v[136:139], v[190:193], v[124:127]
	v_mfma_f32_16x16x32_bf16 v[96:99], v[144:147], v[190:193], v[96:99]
	v_mfma_f32_16x16x32_bf16 v[120:123], v[136:139], v[198:201], v[120:123]
	v_mfma_f32_16x16x32_bf16 v[88:91], v[144:147], v[198:201], v[88:91]
	s_barrier
	s_add_i32 s0, 0, 0x1c000
	s_add_i32 s1, s28, s34
	v_add_u32_e32 v4, s0, v245
	v_lshl_add_u64 v[10:11], v[176:177], 0, s[86:87]
	s_mov_b32 m0, s1
	ds_read_b128 v[202:205], v4
	ds_read_b128 v[206:209], v4 offset:1024
	ds_read_b128 v[210:213], v4 offset:2048
	ds_read_b128 v[214:217], v4 offset:3072
	global_load_lds_dwordx4 v[10:11], off
	s_add_i32 m0, s1, 0x2000
	v_lshl_add_u64 v[10:11], v[186:187], 0, s[86:87]
	global_load_lds_dwordx4 v[10:11], off
	s_barrier
; #define PG8_STAGE(bufoff, gbase, voff) do { _Pragma("unroll") for (int _i = 0; _i < 2; ++_i) \
;         __builtin_amdgcn_global_load_lds((const unsigned*)((const char*)(gbase) + (voff)[_i]), (LAS unsigned*)(lds + (bufoff) + ldsw + _i * 8192), 16, 0, 0); } while (0)
; #define PG8_LDA(dst, b, h) do { _Pragma("unroll") for (int m = 0; m < 4; ++m) _Pragma("unroll") for (int k = 0; k < 2; ++k) dst[m][k] = *(const LAS bf16x8*)(lds + PG8_SA(b, h) + aoff + m * 2048 + k * 1024); } while (0)
; #define PG8_LDB(dst, b, h) do { _Pragma("unroll") for (int n = 0; n < 2; ++n) _Pragma("unroll") for (int k = 0; k < 2; ++k) dst[n][k] = *(const LAS bf16x8*)(lds + PG8_SB(b, h) + boff + n * 2048 + k * 1024); } while (0)
; #define PG8_MMA(ai, bj, At, Bt) do { __builtin_amdgcn_s_setprio(1); _Pragma("unroll") for (int m = 0; m < 4; ++m) _Pragma("unroll") for (int n = 0; n < 2; ++n) _Pragma("unroll") for (int k = 0; k < 2; ++k) \
;         acc[ai][bj][m][n] = __builtin_amdgcn_mfma_f32_16x16x32_bf16(Bt[n][k], At[m][k], acc[ai][bj][m][n], 0, 0, 0); __builtin_amdgcn_s_setprio(0); } while (0)
; #define PG8_WAIT_V(n) asm volatile("s_waitcnt vmcnt(" #n ")" ::: "memory")
; #define PG8_WAIT_L(n) asm volatile("s_waitcnt lgkmcnt(" #n ")" ::: "memory")
; #define PG8_BAR __builtin_amdgcn_s_barrier()
; #define PG8_SCHED __builtin_amdgcn_sched_barrier(0)
; template <class Epi>
; __device__ __forceinline__ void gemm_phase(LAS unsigned char* lds, const Gemm g, const StaticOrder& S, const Epi& E) {
;     ...
;         for (int t = 0; t < nt; t += 2) {
;     ...
;             PG8_LDB(B1, 1, 1); PG8_STAGE(PG8_SB(1, 0), b3, voffB);
;             PG8_BAR; PG8_WAIT_L(0); PG8_MMA(0, 1, At, B1); PG8_BAR;
;             PG8_LDA(At, 1, 1); PG8_STAGE(PG8_SA(1, 0), a3, voffA);
;             PG8_BAR; PG8_WAIT_L(0); PG8_MMA(1, 0, At, B0); PG8_BAR; PG8_SCHED;
;             PG8_STAGE(PG8_SB(1, 1), b3 + hstep, voffB);
;             PG8_WAIT_V(6); PG8_BAR; PG8_MMA(1, 1, At, B1); PG8_BAR;
	s_waitcnt lgkmcnt(0)
	v_mfma_f32_16x16x32_bf16 v[64:67], v[202:205], v[148:151], v[64:67]
	v_mfma_f32_16x16x32_bf16 v[32:35], v[210:213], v[148:151], v[32:35]
	v_mfma_f32_16x16x32_bf16 v[60:63], v[202:205], v[156:159], v[60:63]
	v_mfma_f32_16x16x32_bf16 v[28:31], v[210:213], v[156:159], v[28:31]
	v_mfma_f32_16x16x32_bf16 v[56:59], v[202:205], v[172:175], v[56:59]
	v_mfma_f32_16x16x32_bf16 v[24:27], v[210:213], v[172:175], v[24:27]
	v_mfma_f32_16x16x32_bf16 v[52:55], v[202:205], v[194:197], v[52:55]
	v_mfma_f32_16x16x32_bf16 v[20:23], v[210:213], v[194:197], v[20:23]
	v_mfma_f32_16x16x32_bf16 v[64:67], v[206:209], v[152:155], v[64:67]
	v_mfma_f32_16x16x32_bf16 v[32:35], v[214:217], v[152:155], v[32:35]
	v_mfma_f32_16x16x32_bf16 v[60:63], v[206:209], v[168:171], v[60:63]
	v_mfma_f32_16x16x32_bf16 v[28:31], v[214:217], v[168:171], v[28:31]
	v_mfma_f32_16x16x32_bf16 v[56:59], v[206:209], v[190:193], v[56:59]
	v_mfma_f32_16x16x32_bf16 v[24:27], v[214:217], v[190:193], v[24:27]
	v_mfma_f32_16x16x32_bf16 v[52:55], v[206:209], v[198:201], v[52:55]
	v_mfma_f32_16x16x32_bf16 v[20:23], v[214:217], v[198:201], v[20:23]
	s_mov_b32 m0, s55
	v_lshl_add_u64 v[10:11], v[218:219], 0, s[86:87]
	s_barrier
	ds_read_b128 v[148:151], v249 offset:49152
	ds_read_b128 v[152:155], v249 offset:50176
	ds_read_b128 v[156:159], v249 offset:51200
	ds_read_b128 v[168:171], v249 offset:52224
	ds_read_b128 v[172:175], v249 offset:53248
	ds_read_b128 v[190:193], v249 offset:54272
	ds_read_b128 v[194:197], v249 offset:55296
	ds_read_b128 v[198:201], v249 offset:56320
	global_load_lds_dwordx4 v[10:11], off
	s_mov_b32 m0, s56
	v_lshl_add_u64 v[10:11], v[220:221], 0, s[86:87]
	global_load_lds_dwordx4 v[10:11], off
	s_barrier
	s_waitcnt lgkmcnt(0)
	v_mfma_f32_16x16x32_bf16 v[92:95], v[132:135], v[148:151], v[92:95]
	v_mfma_f32_16x16x32_bf16 v[84:87], v[140:143], v[148:151], v[84:87]
	v_mfma_f32_16x16x32_bf16 v[116:119], v[132:135], v[156:159], v[116:119]
	v_mfma_f32_16x16x32_bf16 v[76:79], v[140:143], v[156:159], v[76:79]
	v_mfma_f32_16x16x32_bf16 v[112:115], v[132:135], v[172:175], v[112:115]
	v_mfma_f32_16x16x32_bf16 v[72:75], v[140:143], v[172:175], v[72:75]
	v_mfma_f32_16x16x32_bf16 v[108:111], v[132:135], v[194:197], v[108:111]
	v_mfma_f32_16x16x32_bf16 v[68:71], v[140:143], v[194:197], v[68:71]
	v_mfma_f32_16x16x32_bf16 v[92:95], v[136:139], v[152:155], v[92:95]
	v_mfma_f32_16x16x32_bf16 v[84:87], v[144:147], v[152:155], v[84:87]
	v_mfma_f32_16x16x32_bf16 v[116:119], v[136:139], v[168:171], v[116:119]
	v_mfma_f32_16x16x32_bf16 v[76:79], v[144:147], v[168:171], v[76:79]
	v_mfma_f32_16x16x32_bf16 v[112:115], v[136:139], v[190:193], v[112:115]
	v_mfma_f32_16x16x32_bf16 v[72:75], v[144:147], v[190:193], v[72:75]
	v_mfma_f32_16x16x32_bf16 v[108:111], v[136:139], v[198:201], v[108:111]
	v_mfma_f32_16x16x32_bf16 v[68:71], v[144:147], v[198:201], v[68:71]
	s_barrier
	s_add_i32 s0, s0, s34
	s_mov_b32 m0, s0
	v_lshl_add_u64 v[10:11], v[222:223], 0, s[86:87]
	global_load_lds_dwordx4 v[10:11], off
	s_add_i32 m0, s0, 0x2000
	v_lshl_add_u64 v[10:11], v[224:225], 0, s[86:87]
	global_load_lds_dwordx4 v[10:11], off
	s_waitcnt vmcnt(6)
	s_barrier
	v_mfma_f32_16x16x32_bf16 v[48:51], v[202:205], v[148:151], v[48:51]
	v_mfma_f32_16x16x32_bf16 v[16:19], v[210:213], v[148:151], v[16:19]
	v_mfma_f32_16x16x32_bf16 v[44:47], v[202:205], v[156:159], v[44:47]
	v_mfma_f32_16x16x32_bf16 v[10:13], v[210:213], v[156:159], v[12:15]
	v_mfma_f32_16x16x32_bf16 v[40:43], v[202:205], v[172:175], v[40:43]
	v_mfma_f32_16x16x32_bf16 v[6:9], v[210:213], v[172:175], v[6:9]
	v_mfma_f32_16x16x32_bf16 v[36:39], v[202:205], v[194:197], v[36:39]
	v_mfma_f32_16x16x32_bf16 v[0:3], v[210:213], v[194:197], v[0:3]
	v_mfma_f32_16x16x32_bf16 v[48:51], v[206:209], v[152:155], v[48:51]
	v_mfma_f32_16x16x32_bf16 v[16:19], v[214:217], v[152:155], v[16:19]
	v_mfma_f32_16x16x32_bf16 v[44:47], v[206:209], v[168:171], v[44:47]
	v_mfma_f32_16x16x32_bf16 v[12:15], v[214:217], v[168:171], v[10:13]
	v_mfma_f32_16x16x32_bf16 v[40:43], v[206:209], v[190:193], v[40:43]
	v_mfma_f32_16x16x32_bf16 v[8:11], v[214:217], v[190:193], v[6:9]
	v_mfma_f32_16x16x32_bf16 v[36:39], v[206:209], v[198:201], v[36:39]
	v_mfma_f32_16x16x32_bf16 v[0:3], v[214:217], v[198:201], v[0:3]
	s_add_u32 s8, s8, 0x100
	s_addc_u32 s9, s9, 0
	s_add_u32 s62, s62, 0x100
	s_addc_u32 s63, s63, 0
	s_cmp_ge_u32 s64, s49
	s_mov_b32 s26, s64
	s_barrier
	s_cbranch_scc1 .Lpeel_exit_0

;     __device__ __forceinline__ void operator()(const f32x4 (&acc)[2][2][4][2], const Unit& u, int wr, int wc, int fr, int fq) const {
;         const int row0 = u.pm * 256 + wr * 64 + fr, col0 = u.pn * 256 + wc * 32 + 4 * fq;
;         const float* mvp = mv + (size_t)(u.pm >> 3) * 9216 + col0;
;         const float fac = __builtin_amdgcn_readfirstlane(ffn) ? 0.5f : 1.f;
;         const bool hb = __builtin_amdgcn_readfirstlane(has_next) != 0;
;         f32x4 rs0 = (f32x4){0.f, 0.f, 0.f, 0.f}, rs1 = rs0;
; #pragma unroll
;         for (int bj = 0; bj < 2; ++bj)
; #pragma unroll
;             for (int n = 0; n < 2; ++n) {
;                 const int co = bj * 128 + n * 16;
;                 const f32x4 mvv = *(const f32x4*)(mvp + co) * fac;
;                 f32x4 gn = (f32x4){0.f, 0.f, 0.f, 0.f};
;                 if (hb) gn = *(const f32x4*)(nwn + col0 + co) * (*(const f32x4*)(scn + (size_t)(u.pm >> 3) * 9216 + col0 + co) + 1.f);
.Lpeel_exit_0:
	s_ashr_i32 s0, s60, 3
	s_mul_i32 s29, s0, 0x9000
	v_lshl_or_b32 v170, s61, 8, v248
	s_mul_hi_i32 s28, s0, 0x9000
	s_add_u32 s0, s50, s29
	s_addc_u32 s1, s51, s28
	v_ashrrev_i32_e32 v171, 31, v170
	v_lshl_add_u64 v[176:177], v[170:171], 2, s[0:1]
	global_load_dwordx4 v[132:135], v[176:177], off
	v_readfirstlane_b32 s0, v243
	s_cmp_lg_u32 s0, 0
	v_lshlrev_b64 v[168:169], 2, v[170:171]
	v_readfirstlane_b32 s8, v242
	s_cselect_b64 s[26:27], -1, 0
	s_cmp_eq_u32 s0, 0
	v_lshl_add_u64 v[190:191], s[18:19], 0, v[168:169]
	s_cbranch_scc1 .LBB0_2977
	s_add_u32 s0, s43, s29
	s_addc_u32 s1, s48, s28
	v_lshl_add_u64 v[6:7], s[0:1], 0, v[168:169]
	global_load_dwordx4 v[136:139], v[6:7], off
	global_load_dwordx4 v[140:143], v[190:191], off
	s_waitcnt vmcnt(0)
	v_pk_add_f32 v[6:7], v[138:139], 1.0 op_sel_hi:[1,0]
	v_pk_add_f32 v[136:137], v[136:137], 1.0 op_sel_hi:[1,0]
	v_pk_mul_f32 v[218:219], v[142:143], v[6:7]
	v_pk_mul_f32 v[216:217], v[140:141], v[136:137]
	s_branch .LBB0_2978
